# EpiRes epilogue (6 GEMM phases): all 16 residual loads issued up front into dead fragment VGPRs with counted vmcnt instead of load-wait-store serial chain; plus convert-phase tile rotation for load ba
# speedup vs baseline: 1.0338x; 1.0175x over previous
; #define LAS __attribute__((address_space(3)))
; DI unsigned char* wsp(const Params& p) { const unsigned long long a = (unsigned long long)p.ws; unsigned lo = __builtin_amdgcn_readfirstlane((unsigned)a), hi = __builtin_amdgcn_readfirstlane((unsigned)(a >> 32)); asm volatile("" : "+s"(lo), "+s"(hi)); return (unsigned char*)(((unsigned long long)hi << 32) | lo); }
; DI int opaque_bid() { int b = blockIdx.x; asm volatile("" : "+s"(b)); return b; }
; DI int opaque_tid() { int t = threadIdx.x; asm volatile("" : "+v"(t)); return t; }
; DI void convert_phase(const Params& p, LAS unsigned char* lds) {
;     unsigned char* const ws = wsp(p);
;     const int bid = opaque_bid();
;     LAS float* tile = (LAS float*)lds;
;     const int tid = opaque_tid();
;     for (int j = 0; j < p.njobs; ++j) {
;         const float* src = p.jobs[j].src; bf16_t* dst = p.jobs[j].dst; const int K = p.jobs[j].K, N = p.jobs[j].N, mode = p.jobs[j].mode;
;         const int nn = (N + 255) >> 8, ntile = (K >> 6) * nn;
;         for (int ti = bid; ti < ntile; ti += gridDim.x) {
;             const int tk = ti / nn, tn = ti - tk * nn;
;             const int rr = tid >> 6, c4 = tid & 63, col = tn * 256 + c4 * 4;
.LBB1_6:
	s_or_b64 exec, exec, s[4:5]
	s_load_dword s33, s[0:1], 0x350
	s_load_dwordx4 s[8:11], s[0:1], 0x0
	v_readfirstlane_b32 s24, v6
	v_readfirstlane_b32 s25, v7
	s_mov_b32 s17, 0
	s_mov_b32 s98, 0
	s_waitcnt lgkmcnt(0)
	s_cmp_gt_i32 s33, 0
	s_mov_b32 s4, s24
	s_mov_b32 s5, s25
	s_mov_b32 s26, s61
	v_mov_b32_e32 v1, v197
	s_cbranch_scc0 .LBB1_22
	v_lshlrev_b32_e32 v2, 2, v1
	v_ashrrev_i32_e32 v10, 6, v1
	v_and_b32_e32 v11, 0xfc, v2
	v_lshlrev_b32_e32 v2, 3, v1
	s_movk_i32 s4, 0x404
	v_lshl_add_u32 v4, v11, 2, 0
	v_and_b32_e32 v2, 56, v2
	v_ashrrev_i32_e32 v5, 3, v1
	v_mul_lo_u32 v8, v10, s4
	v_and_b32_e32 v12, 63, v5
	v_mul_u32_u24_e32 v9, 0x404, v2
	v_lshlrev_b32_e32 v5, 2, v5
	v_add_u32_e32 v14, v4, v8
	v_mov_b32_e32 v3, 0
	v_add3_u32 v13, 0, v9, v5
	s_lshl_b32 s27, s26, 8
	s_lshl_b32 s28, s50, 8
	v_lshlrev_b32_e32 v2, 1, v2
	v_add_u32_e32 v15, 0x2020, v14
	v_add_u32_e32 v16, 0x2028, v14
	v_add_u32_e32 v17, 0x4040, v14
	v_add_u32_e32 v18, 0x4048, v14
	v_add_u32_e32 v19, 0x6060, v14
	v_add_u32_e32 v20, 0x6068, v14
	v_add_u32_e32 v21, 0x8080, v14
	v_add_u32_e32 v22, 0x8088, v14
	v_add_u32_e32 v23, 0xa0a0, v14
	v_add_u32_e32 v24, 0xa0a8, v14
	v_add_u32_e32 v25, 0xc0c0, v14
	v_add_u32_e32 v26, 0xc0c8, v14
	v_add_u32_e32 v27, 0xe0e0, v14
	v_add_u32_e32 v28, 0xe0e8, v14
	s_mov_b32 s16, s17
	s_branch .LBB1_9

; DI void convert_phase(const Params& p, LAS unsigned char* lds) {
;     ...
;     for (int j = 0; j < p.njobs; ++j) {
;         const float* src = p.jobs[j].src; bf16_t* dst = p.jobs[j].dst; const int K = p.jobs[j].K, N = p.jobs[j].N, mode = p.jobs[j].mode;
;         const int nn = (N + 255) >> 8, ntile = (K >> 6) * nn;
;         for (int ti = bid; ti < ntile; ti += gridDim.x) {
;             const int tk = ti / nn, tn = ti - tk * nn;
;             const int rr = tid >> 6, c4 = tid & 63, col = tn * 256 + c4 * 4;
.LBB1_9:
	s_lshl_b64 s[4:5], s[16:17], 5
	s_add_u32 s20, s0, s4
	s_addc_u32 s21, s1, s5
	s_load_dwordx2 s[18:19], s[20:21], 0xa0
	s_waitcnt lgkmcnt(0)
	s_add_i32 s4, s19, 0xff
	s_ashr_i32 s22, s4, 8
	s_ashr_i32 s4, s18, 6
	s_mul_i32 s29, s22, s4
	s_sub_i32 s99, s26, s98
	s_cmp_lt_i32 s99, 0
	s_cbranch_scc0 .Lcvb_noadj
	s_add_i32 s99, s99, s50
.Lcvb_noadj:
	s_add_i32 s98, s98, s29
.Lcvb_red:
	s_cmp_lt_u32 s98, s50
	s_cbranch_scc1 .Lcvb_red_done
	s_sub_i32 s98, s98, s50
	s_branch .Lcvb_red
.Lcvb_red_done:
	s_cmp_ge_i32 s99, s29
	s_cbranch_scc1 .LBB1_8
	s_load_dword s23, s[20:21], 0xa8
	s_load_dwordx4 s[4:7], s[20:21], 0x90
	s_mov_b32 s31, s19
	s_lshl_b32 s34, s99, 8
	s_mov_b32 s40, s99
	s_waitcnt lgkmcnt(0)
	s_cmp_eq_u32 s23, 0
	s_cselect_b64 s[20:21], -1, 0
	s_abs_i32 s30, s22
	v_cvt_f32_u32_e32 v4, s30
	s_lshl_b32 s37, s22, 8
	s_ashr_i32 s35, s22, 31
	s_sub_i32 s36, 0, s22
	v_rcp_iflag_f32_e32 v8, v4
	v_lshl_add_u64 v[4:5], s[6:7], 0, v[2:3]
	s_sub_i32 s6, 0, s30
	s_sub_i32 s38, 0, s37
	v_mul_f32_e32 v8, 0x4f7ffffe, v8
	v_cvt_u32_f32_e32 v8, v8
	s_nop 0
	v_readfirstlane_b32 s7, v8
	s_mul_i32 s6, s6, s7
	s_mul_hi_u32 s6, s7, s6
	s_add_i32 s39, s7, s6
	s_branch .LBB1_12

; #define PG8_STAGE(bufoff, gbase, voff) do { _Pragma("unroll") for (int _i = 0; _i < 2; ++_i) \
;         __builtin_amdgcn_global_load_lds((const unsigned*)((const char*)(gbase) + (voff)[_i]), (LAS unsigned*)(lds + (bufoff) + ldsw + _i * 8192), 16, 0, 0); } while (0)
; #define PG8_LDA(dst, b, h) do { _Pragma("unroll") for (int m = 0; m < 4; ++m) _Pragma("unroll") for (int k = 0; k < 2; ++k) dst[m][k] = *(const LAS bf16x8*)(lds + PG8_SA(b, h) + aoff + m * 2048 + k * 1024); } while (0)
; #define PG8_LDB(dst, b, h) do { _Pragma("unroll") for (int n = 0; n < 2; ++n) _Pragma("unroll") for (int k = 0; k < 2; ++k) dst[n][k] = *(const LAS bf16x8*)(lds + PG8_SB(b, h) + boff + n * 2048 + k * 1024); } while (0)
; #define PG8_MMA(ai, bj, At, Bt) do { __builtin_amdgcn_s_setprio(1); _Pragma("unroll") for (int m = 0; m < 4; ++m) _Pragma("unroll") for (int n = 0; n < 2; ++n) _Pragma("unroll") for (int k = 0; k < 2; ++k) \
;         acc[ai][bj][m][n] = __builtin_amdgcn_mfma_f32_16x16x32_bf16(Bt[n][k], At[m][k], acc[ai][bj][m][n], 0, 0, 0); __builtin_amdgcn_s_setprio(0); } while (0)
; #define PG8_WAIT_L(n) asm volatile("s_waitcnt lgkmcnt(" #n ")" ::: "memory")
; #define PG8_BAR __builtin_amdgcn_s_barrier()
; #define PG8_SCHED __builtin_amdgcn_sched_barrier(0)
; template <class Map, class Epi>
; DI void gemm_phase(LAS unsigned char* lds, const Map& MP, const Epi& E, const int nM, const int nN, const int K, const int lda, const int ldb) {
;     ...
;             PG8_LDB(B0, 0, 0); PG8_SCHED; PG8_LDA(At, 0, 0); PG8_STAGE(PG8_SA(1, 1), a1 + hstepA, voffA);
;             PG8_WAIT_L(8); PG8_BAR; PG8_WAIT_L(0); PG8_MMA(0, 0, At, B0); PG8_BAR; PG8_SCHED;
;             PG8_LDB(B1, 0, 1); PG8_STAGE(PG8_SB(0, 0), b2, voffB);
;             PG8_BAR; PG8_WAIT_L(0); PG8_MMA(0, 1, At, B1); PG8_BAR;
;             PG8_LDA(At, 0, 1); PG8_STAGE(PG8_SA(0, 0), a2, voffA);
;             PG8_BAR; PG8_WAIT_L(0); PG8_MMA(1, 0, At, B0); PG8_BAR; PG8_SCHED;
.LBB1_550:
	ds_read_b128 v[152:155], v149
	ds_read_b128 v[156:159], v149 offset:1024
	ds_read_b128 v[160:163], v149 offset:2048
	ds_read_b128 v[164:167], v149 offset:3072
	s_add_u32 s10, s8, 0x100
	s_addc_u32 s11, s9, 0
	s_cmpk_eq_i32 s3, 0x54
	s_cselect_b32 s15, s43, s11
	s_cselect_b32 s14, s42, s10
	s_cselect_b32 s13, s7, s38
	s_cselect_b32 s12, s6, s5
	v_lshl_add_u64 v[144:145], s[8:9], 0, v[138:139]
	s_add_i32 m0, s24, 0xc000
	ds_read_b128 v[168:171], v150
	ds_read_b128 v[172:175], v150 offset:1024
	ds_read_b128 v[176:179], v150 offset:2048
	ds_read_b128 v[180:183], v150 offset:3072
	ds_read_b128 v[184:187], v150 offset:4096
	ds_read_b128 v[188:191], v150 offset:5120
	ds_read_b128 v[192:195], v150 offset:6144
	ds_read_b128 v[198:201], v150 offset:7168
	global_load_lds_dwordx4 v[144:145], off
	v_lshl_add_u64 v[144:145], s[8:9], 0, v[136:137]
	s_add_i32 m0, s24, 0xe000
	s_nop 0
	global_load_lds_dwordx4 v[144:145], off
	s_waitcnt lgkmcnt(8)
	s_barrier
	s_setprio 1
	s_waitcnt lgkmcnt(7)
	v_mfma_f32_16x16x32_bf16 v[124:127], v[152:155], v[168:171], v[124:127]
	v_mfma_f32_16x16x32_bf16 v[120:123], v[160:163], v[168:171], v[120:123]
	s_waitcnt lgkmcnt(5)
	v_mfma_f32_16x16x32_bf16 v[108:111], v[152:155], v[176:179], v[108:111]
	v_mfma_f32_16x16x32_bf16 v[104:107], v[160:163], v[176:179], v[104:107]
	s_waitcnt lgkmcnt(3)
	v_mfma_f32_16x16x32_bf16 v[92:95], v[152:155], v[184:187], v[92:95]
	v_mfma_f32_16x16x32_bf16 v[88:91], v[160:163], v[184:187], v[88:91]
	s_waitcnt lgkmcnt(1)
	v_mfma_f32_16x16x32_bf16 v[76:79], v[152:155], v[192:195], v[76:79]
	v_mfma_f32_16x16x32_bf16 v[72:75], v[160:163], v[192:195], v[72:75]
	v_mfma_f32_16x16x32_bf16 v[124:127], v[156:159], v[172:175], v[124:127]
	v_mfma_f32_16x16x32_bf16 v[120:123], v[164:167], v[172:175], v[120:123]
	v_mfma_f32_16x16x32_bf16 v[108:111], v[156:159], v[180:183], v[108:111]
	v_mfma_f32_16x16x32_bf16 v[104:107], v[164:167], v[180:183], v[104:107]
	v_mfma_f32_16x16x32_bf16 v[92:95], v[156:159], v[188:191], v[92:95]
	v_mfma_f32_16x16x32_bf16 v[88:91], v[164:167], v[188:191], v[88:91]
	s_waitcnt lgkmcnt(0)
	v_mfma_f32_16x16x32_bf16 v[76:79], v[156:159], v[198:201], v[76:79]
	v_mfma_f32_16x16x32_bf16 v[72:75], v[164:167], v[198:201], v[72:75]
	s_setprio 0
	s_barrier
	s_add_i32 s8, s35, s22
	v_lshl_add_u64 v[144:145], s[12:13], 0, v[132:133]
	s_mov_b32 m0, s8
	ds_read_b128 v[202:205], v151
	ds_read_b128 v[206:209], v151 offset:1024
	ds_read_b128 v[210:213], v151 offset:2048
	ds_read_b128 v[214:217], v151 offset:3072
	global_load_lds_dwordx4 v[144:145], off
	v_lshl_add_u64 v[218:219], s[12:13], 0, v[128:129]
	s_add_i32 m0, s8, 0x2000
	s_nop 0
	global_load_lds_dwordx4 v[218:219], off
	s_barrier
	s_setprio 1
	s_waitcnt lgkmcnt(3)
	v_mfma_f32_16x16x32_bf16 v[116:119], v[202:205], v[168:171], v[116:119]
	s_waitcnt lgkmcnt(1)
	v_mfma_f32_16x16x32_bf16 v[112:115], v[210:213], v[168:171], v[112:115]
	v_mfma_f32_16x16x32_bf16 v[100:103], v[202:205], v[176:179], v[100:103]
	v_mfma_f32_16x16x32_bf16 v[96:99], v[210:213], v[176:179], v[96:99]
	v_mfma_f32_16x16x32_bf16 v[84:87], v[202:205], v[184:187], v[84:87]
	v_mfma_f32_16x16x32_bf16 v[80:83], v[210:213], v[184:187], v[80:83]
	v_mfma_f32_16x16x32_bf16 v[68:71], v[202:205], v[192:195], v[68:71]
	v_mfma_f32_16x16x32_bf16 v[64:67], v[210:213], v[192:195], v[64:67]
	v_mfma_f32_16x16x32_bf16 v[116:119], v[206:209], v[172:175], v[116:119]
	s_waitcnt lgkmcnt(0)
	v_mfma_f32_16x16x32_bf16 v[112:115], v[214:217], v[172:175], v[112:115]
	v_mfma_f32_16x16x32_bf16 v[100:103], v[206:209], v[180:183], v[100:103]
	v_mfma_f32_16x16x32_bf16 v[96:99], v[214:217], v[180:183], v[96:99]
	v_mfma_f32_16x16x32_bf16 v[84:87], v[206:209], v[188:191], v[84:87]
	v_mfma_f32_16x16x32_bf16 v[80:83], v[214:217], v[188:191], v[80:83]
	v_mfma_f32_16x16x32_bf16 v[68:71], v[206:209], v[198:201], v[68:71]
	v_mfma_f32_16x16x32_bf16 v[64:67], v[214:217], v[198:201], v[64:67]
	s_setprio 0
	s_mov_b32 m0, s24
	v_lshl_add_u64 v[220:221], s[14:15], 0, v[134:135]
	s_barrier
	ds_read_b128 v[168:171], v150 offset:16384
	ds_read_b128 v[172:175], v150 offset:17408
	ds_read_b128 v[176:179], v150 offset:18432
	ds_read_b128 v[180:183], v150 offset:19456
	ds_read_b128 v[184:187], v150 offset:20480
	ds_read_b128 v[188:191], v150 offset:21504
	ds_read_b128 v[192:195], v150 offset:22528
	ds_read_b128 v[198:201], v150 offset:23552
	global_load_lds_dwordx4 v[220:221], off
	v_lshl_add_u64 v[222:223], s[14:15], 0, v[130:131]
	s_mov_b32 m0, s25
	s_nop 0
	global_load_lds_dwordx4 v[222:223], off
	s_barrier
	s_setprio 1
	s_waitcnt lgkmcnt(7)
	v_mfma_f32_16x16x32_bf16 v[60:63], v[152:155], v[168:171], v[60:63]
	v_mfma_f32_16x16x32_bf16 v[56:59], v[160:163], v[168:171], v[56:59]
	s_waitcnt lgkmcnt(5)
	v_mfma_f32_16x16x32_bf16 v[44:47], v[152:155], v[176:179], v[44:47]
	v_mfma_f32_16x16x32_bf16 v[40:43], v[160:163], v[176:179], v[40:43]
	s_waitcnt lgkmcnt(3)
	v_mfma_f32_16x16x32_bf16 v[28:31], v[152:155], v[184:187], v[28:31]
	v_mfma_f32_16x16x32_bf16 v[24:27], v[160:163], v[184:187], v[24:27]
	s_waitcnt lgkmcnt(1)
	v_mfma_f32_16x16x32_bf16 v[12:15], v[152:155], v[192:195], v[12:15]
	v_mfma_f32_16x16x32_bf16 v[8:11], v[160:163], v[192:195], v[8:11]
	v_mfma_f32_16x16x32_bf16 v[60:63], v[156:159], v[172:175], v[60:63]
	v_mfma_f32_16x16x32_bf16 v[56:59], v[164:167], v[172:175], v[56:59]
	v_mfma_f32_16x16x32_bf16 v[44:47], v[156:159], v[180:183], v[44:47]
	v_mfma_f32_16x16x32_bf16 v[40:43], v[164:167], v[180:183], v[40:43]
	v_mfma_f32_16x16x32_bf16 v[28:31], v[156:159], v[188:191], v[28:31]
	v_mfma_f32_16x16x32_bf16 v[24:27], v[164:167], v[188:191], v[24:27]
	s_waitcnt lgkmcnt(0)
	v_mfma_f32_16x16x32_bf16 v[12:15], v[156:159], v[198:201], v[12:15]
	v_mfma_f32_16x16x32_bf16 v[8:11], v[164:167], v[198:201], v[8:11]
	s_setprio 0
	s_barrier
; #define PG8_STAGE(bufoff, gbase, voff) do { _Pragma("unroll") for (int _i = 0; _i < 2; ++_i) \
;         __builtin_amdgcn_global_load_lds((const unsigned*)((const char*)(gbase) + (voff)[_i]), (LAS unsigned*)(lds + (bufoff) + ldsw + _i * 8192), 16, 0, 0); } while (0)
; #define PG8_LDA(dst, b, h) do { _Pragma("unroll") for (int m = 0; m < 4; ++m) _Pragma("unroll") for (int k = 0; k < 2; ++k) dst[m][k] = *(const LAS bf16x8*)(lds + PG8_SA(b, h) + aoff + m * 2048 + k * 1024); } while (0)
; #define PG8_LDB(dst, b, h) do { _Pragma("unroll") for (int n = 0; n < 2; ++n) _Pragma("unroll") for (int k = 0; k < 2; ++k) dst[n][k] = *(const LAS bf16x8*)(lds + PG8_SB(b, h) + boff + n * 2048 + k * 1024); } while (0)
; #define PG8_MMA(ai, bj, At, Bt) do { __builtin_amdgcn_s_setprio(1); _Pragma("unroll") for (int m = 0; m < 4; ++m) _Pragma("unroll") for (int n = 0; n < 2; ++n) _Pragma("unroll") for (int k = 0; k < 2; ++k) \
;         acc[ai][bj][m][n] = __builtin_amdgcn_mfma_f32_16x16x32_bf16(Bt[n][k], At[m][k], acc[ai][bj][m][n], 0, 0, 0); __builtin_amdgcn_s_setprio(0); } while (0)
; #define PG8_WAIT_V(n) asm volatile("s_waitcnt vmcnt(" #n ")" ::: "memory")
; #define PG8_WAIT_L(n) asm volatile("s_waitcnt lgkmcnt(" #n ")" ::: "memory")
; #define PG8_BAR __builtin_amdgcn_s_barrier()
; #define PG8_SCHED __builtin_amdgcn_sched_barrier(0)
; template <class Map, class Epi>
; DI void gemm_phase(LAS unsigned char* lds, const Map& MP, const Epi& E, const int nM, const int nN, const int K, const int lda, const int ldb) {
;     ...
;             PG8_STAGE(PG8_SB(0, 1), b2 + hstepB, voffB);
;             PG8_WAIT_V(6); PG8_BAR; PG8_MMA(1, 1, At, B1); PG8_BAR;
;             PG8_LDB(B0, 1, 0); PG8_SCHED; PG8_LDA(At, 1, 0); PG8_STAGE(PG8_SA(0, 1), a2 + hstepA, voffA);
;             PG8_WAIT_L(8); PG8_BAR; PG8_WAIT_L(0); PG8_MMA(0, 0, At, B0); PG8_BAR; PG8_SCHED;
;             PG8_LDB(B1, 1, 1); PG8_STAGE(PG8_SB(1, 0), b3, voffB);
;             PG8_BAR; PG8_WAIT_L(0); PG8_MMA(0, 1, At, B1); PG8_BAR;
	s_add_u32 s8, s12, 0x160000
	s_addc_u32 s9, s13, 0
	s_add_i32 s39, s36, s22
	v_lshl_add_u64 v[152:153], s[8:9], 0, v[132:133]
	s_mov_b32 m0, s39
	s_nop 0
	global_load_lds_dwordx4 v[152:153], off
	v_lshl_add_u64 v[152:153], s[8:9], 0, v[128:129]
	s_add_i32 m0, s39, 0x2000
	s_nop 0
	global_load_lds_dwordx4 v[152:153], off
	s_waitcnt vmcnt(6)
	s_barrier
	s_setprio 1
	v_mfma_f32_16x16x32_bf16 v[52:55], v[202:205], v[168:171], v[52:55]
	v_mfma_f32_16x16x32_bf16 v[48:51], v[210:213], v[168:171], v[48:51]
	v_mfma_f32_16x16x32_bf16 v[36:39], v[202:205], v[176:179], v[36:39]
	v_mfma_f32_16x16x32_bf16 v[32:35], v[210:213], v[176:179], v[32:35]
	v_mfma_f32_16x16x32_bf16 v[20:23], v[202:205], v[184:187], v[20:23]
	v_mfma_f32_16x16x32_bf16 v[16:19], v[210:213], v[184:187], v[16:19]
	v_mfma_f32_16x16x32_bf16 v[4:7], v[202:205], v[192:195], v[4:7]
	v_mfma_f32_16x16x32_bf16 v[0:3], v[210:213], v[192:195], v[0:3]
	v_mfma_f32_16x16x32_bf16 v[52:55], v[206:209], v[172:175], v[52:55]
	v_mfma_f32_16x16x32_bf16 v[48:51], v[214:217], v[172:175], v[48:51]
	v_mfma_f32_16x16x32_bf16 v[36:39], v[206:209], v[180:183], v[36:39]
	v_mfma_f32_16x16x32_bf16 v[32:35], v[214:217], v[180:183], v[32:35]
	v_mfma_f32_16x16x32_bf16 v[20:23], v[206:209], v[188:191], v[20:23]
	v_mfma_f32_16x16x32_bf16 v[16:19], v[214:217], v[188:191], v[16:19]
	v_mfma_f32_16x16x32_bf16 v[4:7], v[206:209], v[198:201], v[4:7]
	v_mfma_f32_16x16x32_bf16 v[0:3], v[214:217], v[198:201], v[0:3]
	s_setprio 0
	s_add_i32 s39, 0, 0x18000
	v_add_u32_e32 v164, s39, v148
	s_barrier
	ds_read_b128 v[152:155], v164
	ds_read_b128 v[156:159], v164 offset:1024
	ds_read_b128 v[160:163], v164 offset:2048
	ds_read_b128 v[164:167], v164 offset:3072
	s_add_u32 s8, s14, 0x160000
	s_addc_u32 s9, s15, 0
	s_mov_b32 m0, s26
	v_lshl_add_u64 v[202:203], s[8:9], 0, v[134:135]
	ds_read_b128 v[168:171], v150 offset:32768
	ds_read_b128 v[172:175], v150 offset:33792
	ds_read_b128 v[176:179], v150 offset:34816
	ds_read_b128 v[180:183], v150 offset:35840
	ds_read_b128 v[184:187], v150 offset:36864
	ds_read_b128 v[188:191], v150 offset:37888
	ds_read_b128 v[192:195], v150 offset:38912
	ds_read_b128 v[198:201], v150 offset:39936
	global_load_lds_dwordx4 v[202:203], off
	v_lshl_add_u64 v[202:203], s[8:9], 0, v[130:131]
	s_mov_b32 m0, s27
	s_nop 0
	global_load_lds_dwordx4 v[202:203], off
	s_waitcnt lgkmcnt(8)
	s_barrier
	s_setprio 1
	s_waitcnt lgkmcnt(7)
	v_mfma_f32_16x16x32_bf16 v[124:127], v[152:155], v[168:171], v[124:127]
	v_mfma_f32_16x16x32_bf16 v[120:123], v[160:163], v[168:171], v[120:123]
	s_waitcnt lgkmcnt(5)
	v_mfma_f32_16x16x32_bf16 v[108:111], v[152:155], v[176:179], v[108:111]
	v_mfma_f32_16x16x32_bf16 v[104:107], v[160:163], v[176:179], v[104:107]
	s_waitcnt lgkmcnt(3)
	v_mfma_f32_16x16x32_bf16 v[92:95], v[152:155], v[184:187], v[92:95]
	v_mfma_f32_16x16x32_bf16 v[88:91], v[160:163], v[184:187], v[88:91]
	s_waitcnt lgkmcnt(1)
	v_mfma_f32_16x16x32_bf16 v[76:79], v[152:155], v[192:195], v[76:79]
	v_mfma_f32_16x16x32_bf16 v[72:75], v[160:163], v[192:195], v[72:75]
	v_mfma_f32_16x16x32_bf16 v[124:127], v[156:159], v[172:175], v[124:127]
	v_mfma_f32_16x16x32_bf16 v[120:123], v[164:167], v[172:175], v[120:123]
	v_mfma_f32_16x16x32_bf16 v[108:111], v[156:159], v[180:183], v[108:111]
	v_mfma_f32_16x16x32_bf16 v[104:107], v[164:167], v[180:183], v[104:107]
	v_mfma_f32_16x16x32_bf16 v[92:95], v[156:159], v[188:191], v[92:95]
	v_mfma_f32_16x16x32_bf16 v[88:91], v[164:167], v[188:191], v[88:91]
	s_waitcnt lgkmcnt(0)
	v_mfma_f32_16x16x32_bf16 v[76:79], v[156:159], v[198:201], v[76:79]
	v_mfma_f32_16x16x32_bf16 v[72:75], v[164:167], v[198:201], v[72:75]
	s_setprio 0
	s_barrier
	s_add_i32 s14, 0, 0x1c000
	s_add_i32 s8, s39, s22
	v_add_u32_e32 v196, s14, v148
	v_lshl_add_u64 v[144:145], v[144:145], 0, s[52:53]
	s_mov_b32 m0, s8
	ds_read_b128 v[202:205], v196
	ds_read_b128 v[206:209], v196 offset:1024
	ds_read_b128 v[210:213], v196 offset:2048
	ds_read_b128 v[214:217], v196 offset:3072
	global_load_lds_dwordx4 v[144:145], off
	v_lshl_add_u64 v[144:145], v[218:219], 0, s[52:53]
	s_add_i32 m0, s8, 0x2000
	s_nop 0
	global_load_lds_dwordx4 v[144:145], off
	s_barrier
	s_setprio 1
	s_waitcnt lgkmcnt(3)
	v_mfma_f32_16x16x32_bf16 v[116:119], v[202:205], v[168:171], v[116:119]
	s_waitcnt lgkmcnt(1)
	v_mfma_f32_16x16x32_bf16 v[112:115], v[210:213], v[168:171], v[112:115]
	v_mfma_f32_16x16x32_bf16 v[100:103], v[202:205], v[176:179], v[100:103]
	v_mfma_f32_16x16x32_bf16 v[96:99], v[210:213], v[176:179], v[96:99]
	v_mfma_f32_16x16x32_bf16 v[84:87], v[202:205], v[184:187], v[84:87]
	v_mfma_f32_16x16x32_bf16 v[80:83], v[210:213], v[184:187], v[80:83]
	v_mfma_f32_16x16x32_bf16 v[68:71], v[202:205], v[192:195], v[68:71]
	v_mfma_f32_16x16x32_bf16 v[64:67], v[210:213], v[192:195], v[64:67]
	v_mfma_f32_16x16x32_bf16 v[116:119], v[206:209], v[172:175], v[116:119]
	s_waitcnt lgkmcnt(0)
	v_mfma_f32_16x16x32_bf16 v[112:115], v[214:217], v[172:175], v[112:115]
	v_mfma_f32_16x16x32_bf16 v[100:103], v[206:209], v[180:183], v[100:103]
	v_mfma_f32_16x16x32_bf16 v[96:99], v[214:217], v[180:183], v[96:99]
	v_mfma_f32_16x16x32_bf16 v[84:87], v[206:209], v[188:191], v[84:87]
	v_mfma_f32_16x16x32_bf16 v[80:83], v[214:217], v[188:191], v[80:83]
	v_mfma_f32_16x16x32_bf16 v[68:71], v[206:209], v[198:201], v[68:71]
	v_mfma_f32_16x16x32_bf16 v[64:67], v[214:217], v[198:201], v[64:67]
	s_setprio 0
	s_mov_b32 m0, s30
	v_lshl_add_u64 v[144:145], v[220:221], 0, s[52:53]
	s_barrier
; #define PG8_STAGE(bufoff, gbase, voff) do { _Pragma("unroll") for (int _i = 0; _i < 2; ++_i) \
;         __builtin_amdgcn_global_load_lds((const unsigned*)((const char*)(gbase) + (voff)[_i]), (LAS unsigned*)(lds + (bufoff) + ldsw + _i * 8192), 16, 0, 0); } while (0)
; #define PG8_LDA(dst, b, h) do { _Pragma("unroll") for (int m = 0; m < 4; ++m) _Pragma("unroll") for (int k = 0; k < 2; ++k) dst[m][k] = *(const LAS bf16x8*)(lds + PG8_SA(b, h) + aoff + m * 2048 + k * 1024); } while (0)
; #define PG8_MMA(ai, bj, At, Bt) do { __builtin_amdgcn_s_setprio(1); _Pragma("unroll") for (int m = 0; m < 4; ++m) _Pragma("unroll") for (int n = 0; n < 2; ++n) _Pragma("unroll") for (int k = 0; k < 2; ++k) \
;         acc[ai][bj][m][n] = __builtin_amdgcn_mfma_f32_16x16x32_bf16(Bt[n][k], At[m][k], acc[ai][bj][m][n], 0, 0, 0); __builtin_amdgcn_s_setprio(0); } while (0)
; #define PG8_WAIT_V(n) asm volatile("s_waitcnt vmcnt(" #n ")" ::: "memory")
; #define PG8_WAIT_L(n) asm volatile("s_waitcnt lgkmcnt(" #n ")" ::: "memory")
; #define PG8_BAR __builtin_amdgcn_s_barrier()
;     DI void operator()(const f32x4 (&acc)[2][2][4][2], const Unit& u, int wr, int wc, int fr, int fq) const {
;         const int row0 = u.pm * BM + wr * 64 + fr, col0 = u.pn * BM + wc * 32 + 8 * fq;
;         f32x4 sc[2][2];
; #pragma unroll
;         for (int bj = 0; bj < 2; ++bj)
; #pragma unroll
;             for (int n = 0; n < 2; ++n) sc[bj][n] = scale ? *(const f32x4*)(scale + col0 + bj * HALF + 4 * n) : (f32x4){1.f, 1.f, 1.f, 1.f};
; #pragma unroll
;         for (int ai = 0; ai < 2; ++ai)
; #pragma unroll
;             for (int m = 0; m < 4; ++m) { const size_t ro = (size_t)(row0 + ai * HALF + m * 16) * D + col0;
; #pragma unroll
;                 for (int bj = 0; bj < 2; ++bj) {
;                     f32x4 x0, x1;
;                     if constexpr (IB) { const u32x4 w = *(const u32x4*)((const bf16_t*)Xin + ro + bj * HALF);
; template <class Map, class Epi>
; DI void gemm_phase(LAS unsigned char* lds, const Map& MP, const Epi& E, const int nM, const int nN, const int K, const int lda, const int ldb) {
;     ...
;             PG8_LDA(At, 1, 1); PG8_STAGE(PG8_SA(1, 0), a3, voffA);
;             PG8_BAR; PG8_WAIT_L(0); PG8_MMA(1, 0, At, B0); PG8_BAR; PG8_SCHED;
;             PG8_STAGE(PG8_SB(1, 1), b3 + hstepB, voffB);
;             PG8_WAIT_V(6); PG8_BAR; PG8_MMA(1, 1, At, B1); PG8_BAR;
	ds_read_b128 v[168:171], v150 offset:49152
	ds_read_b128 v[172:175], v150 offset:50176
	ds_read_b128 v[176:179], v150 offset:51200
	ds_read_b128 v[180:183], v150 offset:52224
	ds_read_b128 v[184:187], v150 offset:53248
	ds_read_b128 v[188:191], v150 offset:54272
	ds_read_b128 v[192:195], v150 offset:55296
	ds_read_b128 v[198:201], v150 offset:56320
	global_load_lds_dwordx4 v[144:145], off
	v_lshl_add_u64 v[144:145], v[222:223], 0, s[52:53]
	s_mov_b32 m0, s31
	s_nop 0
	global_load_lds_dwordx4 v[144:145], off
	s_barrier
	s_setprio 1
	s_waitcnt lgkmcnt(7)
	v_mfma_f32_16x16x32_bf16 v[60:63], v[152:155], v[168:171], v[60:63]
	v_mfma_f32_16x16x32_bf16 v[56:59], v[160:163], v[168:171], v[56:59]
	s_waitcnt lgkmcnt(5)
	v_mfma_f32_16x16x32_bf16 v[44:47], v[152:155], v[176:179], v[44:47]
	v_mfma_f32_16x16x32_bf16 v[40:43], v[160:163], v[176:179], v[40:43]
	s_waitcnt lgkmcnt(3)
	v_mfma_f32_16x16x32_bf16 v[28:31], v[152:155], v[184:187], v[28:31]
	v_mfma_f32_16x16x32_bf16 v[24:27], v[160:163], v[184:187], v[24:27]
	s_waitcnt lgkmcnt(1)
	v_mfma_f32_16x16x32_bf16 v[12:15], v[152:155], v[192:195], v[12:15]
	v_mfma_f32_16x16x32_bf16 v[8:11], v[160:163], v[192:195], v[8:11]
	v_mfma_f32_16x16x32_bf16 v[60:63], v[156:159], v[172:175], v[60:63]
	v_mfma_f32_16x16x32_bf16 v[56:59], v[164:167], v[172:175], v[56:59]
	v_mfma_f32_16x16x32_bf16 v[44:47], v[156:159], v[180:183], v[44:47]
	v_mfma_f32_16x16x32_bf16 v[40:43], v[164:167], v[180:183], v[40:43]
	v_mfma_f32_16x16x32_bf16 v[28:31], v[156:159], v[188:191], v[28:31]
	v_mfma_f32_16x16x32_bf16 v[24:27], v[164:167], v[188:191], v[24:27]
	s_waitcnt lgkmcnt(0)
	v_mfma_f32_16x16x32_bf16 v[12:15], v[156:159], v[198:201], v[12:15]
	v_mfma_f32_16x16x32_bf16 v[8:11], v[164:167], v[198:201], v[8:11]
	s_setprio 0
	s_barrier
	s_add_u32 s8, s12, 0x160080
	s_addc_u32 s9, s13, 0
	s_add_i32 s12, s14, s22
	v_lshl_add_u64 v[144:145], s[8:9], 0, v[132:133]
	s_mov_b32 m0, s12
	s_nop 0
	global_load_lds_dwordx4 v[144:145], off
	v_lshl_add_u64 v[144:145], s[8:9], 0, v[128:129]
	s_add_i32 m0, s12, 0x2000
	s_nop 0
	global_load_lds_dwordx4 v[144:145], off
	s_waitcnt vmcnt(6)
	s_barrier
	s_setprio 1
	v_mfma_f32_16x16x32_bf16 v[52:55], v[202:205], v[168:171], v[52:55]
	v_mfma_f32_16x16x32_bf16 v[48:51], v[210:213], v[168:171], v[48:51]
	v_mfma_f32_16x16x32_bf16 v[36:39], v[202:205], v[176:179], v[36:39]
	v_mfma_f32_16x16x32_bf16 v[32:35], v[210:213], v[176:179], v[32:35]
	v_mfma_f32_16x16x32_bf16 v[20:23], v[202:205], v[184:187], v[20:23]
	v_mfma_f32_16x16x32_bf16 v[16:19], v[210:213], v[184:187], v[16:19]
	v_mfma_f32_16x16x32_bf16 v[4:7], v[202:205], v[192:195], v[4:7]
	v_mfma_f32_16x16x32_bf16 v[0:3], v[210:213], v[192:195], v[0:3]
	v_mfma_f32_16x16x32_bf16 v[52:55], v[206:209], v[172:175], v[52:55]
	v_mfma_f32_16x16x32_bf16 v[48:51], v[214:217], v[172:175], v[48:51]
	v_mfma_f32_16x16x32_bf16 v[36:39], v[206:209], v[180:183], v[36:39]
	v_mfma_f32_16x16x32_bf16 v[32:35], v[214:217], v[180:183], v[32:35]
	v_mfma_f32_16x16x32_bf16 v[20:23], v[206:209], v[188:191], v[20:23]
	v_mfma_f32_16x16x32_bf16 v[16:19], v[214:217], v[188:191], v[16:19]
	v_mfma_f32_16x16x32_bf16 v[4:7], v[206:209], v[198:201], v[4:7]
	v_mfma_f32_16x16x32_bf16 v[0:3], v[214:217], v[198:201], v[0:3]
	s_setprio 0
	s_add_i32 s3, s3, 2
	s_add_u32 s5, s5, 0x100
	s_addc_u32 s38, s38, 0
	s_cmpk_gt_u32 s3, 0x55
	s_mov_b64 s[8:9], s[10:11]
	s_barrier
	s_cbranch_scc0 .LBB1_550
	v_mov_b32_e32 v144, v146
	v_mov_b32_e32 v152, v147
	s_lshl_b32 s2, s2, 8
	s_add_i32 s2, s2, s29
	s_lshl_b32 s3, s4, 8
	v_add_u32_e32 v152, s2, v152
	s_or_b32 s3, s3, s54
	v_ashrrev_i32_e32 v153, 31, v152
	v_lshl_add_u32 v144, v144, 3, s3
	v_lshlrev_b64 v[152:153], 12, v[152:153]
	v_ashrrev_i32_e32 v145, 31, v144
	v_lshl_add_u64 v[152:153], s[46:47], 0, v[152:153]
	v_lshl_add_u64 v[144:145], v[144:145], 1, v[152:153]
	global_load_dwordx4 v[160:163], v[144:145], off
	global_load_dwordx4 v[164:167], v[144:145], off offset:256
	s_mov_b64 s[98:99], 0x10000
	v_lshl_add_u64 v[154:155], v[144:145], 0, s[98:99]
	global_load_dwordx4 v[168:171], v[154:155], off
	global_load_dwordx4 v[172:175], v[154:155], off offset:256
	s_mov_b64 s[98:99], 0x20000
	v_lshl_add_u64 v[154:155], v[144:145], 0, s[98:99]
	global_load_dwordx4 v[176:179], v[154:155], off
	global_load_dwordx4 v[180:183], v[154:155], off offset:256
	s_mov_b64 s[98:99], 0x30000
	v_lshl_add_u64 v[154:155], v[144:145], 0, s[98:99]
	global_load_dwordx4 v[184:187], v[154:155], off
	global_load_dwordx4 v[188:191], v[154:155], off offset:256
	s_mov_b64 s[98:99], 0x80000
	v_lshl_add_u64 v[154:155], v[144:145], 0, s[98:99]
	global_load_dwordx4 v[192:195], v[154:155], off
	global_load_dwordx4 v[198:201], v[154:155], off offset:256
	s_mov_b64 s[98:99], 0x90000
	v_lshl_add_u64 v[154:155], v[144:145], 0, s[98:99]
	global_load_dwordx4 v[202:205], v[154:155], off
	global_load_dwordx4 v[206:209], v[154:155], off offset:256
	s_mov_b64 s[98:99], 0xa0000
	v_lshl_add_u64 v[154:155], v[144:145], 0, s[98:99]
	global_load_dwordx4 v[210:213], v[154:155], off
	global_load_dwordx4 v[214:217], v[154:155], off offset:256
	s_mov_b64 s[98:99], 0xb0000
	v_lshl_add_u64 v[154:155], v[144:145], 0, s[98:99]
	global_load_dwordx4 v[248:251], v[154:155], off
	global_load_dwordx4 v[252:255], v[154:155], off offset:256
	s_waitcnt vmcnt(15)
	s_nop 1
	v_mov_b32_e32 v152, v160
	v_mov_b32_e32 v153, v161
	v_mov_b32_e32 v154, v162
	v_mov_b32_e32 v155, v163
	s_mov_b64 s[2:3], 0x10000
	s_mov_b32 s4, s37
	s_mov_b64 s[10:11], s[6:7]
	s_mov_b64 s[8:9], s[42:43]
	s_waitcnt lgkmcnt(0)
; DI unsigned pack2(float a, float b) { f32x2 v = {a, b}; hwbf16x2 r = __builtin_convertvector(v, hwbf16x2); return __builtin_bit_cast(unsigned, r); }
; DI float bflo(unsigned w) { return __uint_as_float(w << 16); }
; DI float bfhi(unsigned w) { return __uint_as_float(w & 0xffff0000u); }
;     DI void operator()(const f32x4 (&acc)[2][2][4][2], const Unit& u, int wr, int wc, int fr, int fq) const {
;     ...
;             for (int m = 0; m < 4; ++m) { const size_t ro = (size_t)(row0 + ai * HALF + m * 16) * D + col0;
; #pragma unroll
;                 for (int bj = 0; bj < 2; ++bj) {
;                     f32x4 x0, x1;
;                     if constexpr (IB) { const u32x4 w = *(const u32x4*)((const bf16_t*)Xin + ro + bj * HALF);
;                         x0 = (f32x4){bflo(w[0]), bfhi(w[0]), bflo(w[1]), bfhi(w[1])}; x1 = (f32x4){bflo(w[2]), bfhi(w[2]), bflo(w[3]), bfhi(w[3])}; }
;                     else { x0 = *(const f32x4*)((const float*)Xin + ro + bj * HALF); x1 = *(const f32x4*)((const float*)Xin + ro + bj * HALF + 4); }
;                     x0 += acc[ai][bj][m][0] * sc[bj][0]; x1 += acc[ai][bj][m][1] * sc[bj][1];
;                     if constexpr (OB) { u32x4 o; o[0] = pack2(x0[0], x0[1]); o[1] = pack2(x0[2], x0[3]); o[2] = pack2(x1[0], x1[1]); o[3] = pack2(x1[2], x1[3]);
;                         *(u32x4*)((bf16_t*)Xout + ro + bj * HALF) = o; }
	v_lshlrev_b32_e32 v156, 16, v152
	v_and_b32_e32 v157, 0xffff0000, v152
	v_lshlrev_b32_e32 v152, 16, v153
	v_and_b32_e32 v153, 0xffff0000, v153
	v_lshlrev_b32_e32 v158, 16, v154
	v_and_b32_e32 v159, 0xffff0000, v154
	v_lshlrev_b32_e32 v154, 16, v155
	v_and_b32_e32 v155, 0xffff0000, v155
	v_pk_add_f32 v[126:127], v[126:127], v[152:153]
	v_pk_add_f32 v[124:125], v[124:125], v[156:157]
	v_pk_add_f32 v[152:153], v[122:123], v[154:155]
	v_pk_add_f32 v[122:123], v[120:121], v[158:159]
	v_cvt_pk_bf16_f32 v120, v124, v125
	v_cvt_pk_bf16_f32 v121, v126, v127
	v_cvt_pk_bf16_f32 v122, v122, v123
	v_cvt_pk_bf16_f32 v123, v152, v153
	global_store_dwordx4 v[144:145], v[120:123], off
	s_waitcnt vmcnt(15)
	s_nop 1
	v_mov_b32_e32 v120, v164
	v_mov_b32_e32 v121, v165
	v_mov_b32_e32 v122, v166
	v_mov_b32_e32 v123, v167
	s_waitcnt lgkmcnt(0)
	v_lshlrev_b32_e32 v124, 16, v120
	v_and_b32_e32 v125, 0xffff0000, v120
	v_lshlrev_b32_e32 v120, 16, v121
	v_and_b32_e32 v121, 0xffff0000, v121
	v_lshlrev_b32_e32 v126, 16, v122
	v_and_b32_e32 v127, 0xffff0000, v122
	v_lshlrev_b32_e32 v122, 16, v123
	v_and_b32_e32 v123, 0xffff0000, v123
	v_pk_add_f32 v[116:117], v[116:117], v[124:125]
	v_pk_add_f32 v[118:119], v[118:119], v[120:121]
	v_pk_add_f32 v[120:121], v[114:115], v[122:123]
	v_pk_add_f32 v[114:115], v[112:113], v[126:127]
	v_cvt_pk_bf16_f32 v112, v116, v117
	v_lshl_add_u64 v[116:117], v[144:145], 0, s[2:3]
	s_mov_b32 s2, 0x10000
	v_cvt_pk_bf16_f32 v113, v118, v119
	v_add_co_u32_e32 v118, vcc, s2, v144
	v_cvt_pk_bf16_f32 v114, v114, v115
	v_cvt_pk_bf16_f32 v115, v120, v121
	v_addc_co_u32_e32 v119, vcc, 0, v145, vcc
	global_store_dwordx4 v[144:145], v[112:115], off offset:256
	s_waitcnt vmcnt(15)
	s_nop 1
	v_mov_b32_e32 v112, v168
	v_mov_b32_e32 v113, v169
	v_mov_b32_e32 v114, v170
	v_mov_b32_e32 v115, v171
	s_mov_b64 s[2:3], 0x20000
	s_waitcnt lgkmcnt(0)
	v_lshlrev_b32_e32 v120, 16, v112
	v_and_b32_e32 v121, 0xffff0000, v112
	v_lshlrev_b32_e32 v112, 16, v113
	v_and_b32_e32 v113, 0xffff0000, v113
	v_lshlrev_b32_e32 v122, 16, v114
	v_and_b32_e32 v123, 0xffff0000, v114
	v_lshlrev_b32_e32 v114, 16, v115
	v_and_b32_e32 v115, 0xffff0000, v115
	v_pk_add_f32 v[110:111], v[110:111], v[112:113]
	v_pk_add_f32 v[108:109], v[108:109], v[120:121]
	v_pk_add_f32 v[112:113], v[106:107], v[114:115]
	v_pk_add_f32 v[106:107], v[104:105], v[122:123]
	v_cvt_pk_bf16_f32 v104, v108, v109
	v_cvt_pk_bf16_f32 v105, v110, v111
	v_cvt_pk_bf16_f32 v106, v106, v107
	v_cvt_pk_bf16_f32 v107, v112, v113
	global_store_dwordx4 v[118:119], v[104:107], off
	s_waitcnt vmcnt(15)
	s_nop 1
	v_mov_b32_e32 v104, v172
	v_mov_b32_e32 v105, v173
	v_mov_b32_e32 v106, v174
	v_mov_b32_e32 v107, v175
	s_waitcnt lgkmcnt(0)
	v_lshlrev_b32_e32 v108, 16, v104
	v_and_b32_e32 v109, 0xffff0000, v104
	v_lshlrev_b32_e32 v104, 16, v105
	v_and_b32_e32 v105, 0xffff0000, v105
	v_lshlrev_b32_e32 v110, 16, v106
	v_and_b32_e32 v111, 0xffff0000, v106
	v_lshlrev_b32_e32 v106, 16, v107
	v_and_b32_e32 v107, 0xffff0000, v107
	v_pk_add_f32 v[100:101], v[100:101], v[108:109]
	v_pk_add_f32 v[102:103], v[102:103], v[104:105]
	v_pk_add_f32 v[104:105], v[98:99], v[106:107]
	v_pk_add_f32 v[98:99], v[96:97], v[110:111]
	v_cvt_pk_bf16_f32 v96, v100, v101
	v_lshl_add_u64 v[100:101], v[144:145], 0, s[2:3]
	s_mov_b32 s2, 0x20000
	v_cvt_pk_bf16_f32 v97, v102, v103
	v_add_co_u32_e32 v102, vcc, s2, v144
	v_cvt_pk_bf16_f32 v98, v98, v99
	v_cvt_pk_bf16_f32 v99, v104, v105
	v_addc_co_u32_e32 v103, vcc, 0, v145, vcc
	global_store_dwordx4 v[116:117], v[96:99], off offset:256
	s_waitcnt vmcnt(15)
	s_nop 1
	v_mov_b32_e32 v96, v176
	v_mov_b32_e32 v97, v177
	v_mov_b32_e32 v98, v178
	v_mov_b32_e32 v99, v179
	s_mov_b64 s[2:3], 0x30000
	s_waitcnt lgkmcnt(0)
	v_lshlrev_b32_e32 v104, 16, v96
	v_and_b32_e32 v105, 0xffff0000, v96
	v_lshlrev_b32_e32 v96, 16, v97
	v_and_b32_e32 v97, 0xffff0000, v97
	v_lshlrev_b32_e32 v106, 16, v98
	v_and_b32_e32 v107, 0xffff0000, v98
	v_lshlrev_b32_e32 v98, 16, v99
	v_and_b32_e32 v99, 0xffff0000, v99
	v_pk_add_f32 v[94:95], v[94:95], v[96:97]
	v_pk_add_f32 v[92:93], v[92:93], v[104:105]
	v_pk_add_f32 v[96:97], v[90:91], v[98:99]
	v_pk_add_f32 v[90:91], v[88:89], v[106:107]
	v_cvt_pk_bf16_f32 v88, v92, v93
	v_cvt_pk_bf16_f32 v89, v94, v95
	v_cvt_pk_bf16_f32 v90, v90, v91
	v_cvt_pk_bf16_f32 v91, v96, v97
	global_store_dwordx4 v[102:103], v[88:91], off
	s_waitcnt vmcnt(15)
	s_nop 1
	v_mov_b32_e32 v88, v180
	v_mov_b32_e32 v89, v181
	v_mov_b32_e32 v90, v182
	v_mov_b32_e32 v91, v183
	s_waitcnt lgkmcnt(0)
	v_lshlrev_b32_e32 v92, 16, v88
	v_and_b32_e32 v93, 0xffff0000, v88
	v_lshlrev_b32_e32 v88, 16, v89
	v_and_b32_e32 v89, 0xffff0000, v89
	v_lshlrev_b32_e32 v94, 16, v90
	v_and_b32_e32 v95, 0xffff0000, v90
	v_lshlrev_b32_e32 v90, 16, v91
	v_and_b32_e32 v91, 0xffff0000, v91
	v_pk_add_f32 v[86:87], v[86:87], v[88:89]
	v_pk_add_f32 v[84:85], v[84:85], v[92:93]
	v_pk_add_f32 v[88:89], v[82:83], v[90:91]
	v_pk_add_f32 v[82:83], v[80:81], v[94:95]
	v_cvt_pk_bf16_f32 v80, v84, v85
	v_cvt_pk_bf16_f32 v81, v86, v87
	v_cvt_pk_bf16_f32 v82, v82, v83
	v_cvt_pk_bf16_f32 v83, v88, v89
	global_store_dwordx4 v[100:101], v[80:83], off offset:256
	s_nop 1
	v_lshl_add_u64 v[80:81], v[144:145], 0, s[2:3]
	s_mov_b32 s2, 0x30000
	v_add_co_u32_e32 v86, vcc, s2, v144
	s_mov_b64 s[2:3], 0x80000
	s_nop 0
	v_addc_co_u32_e32 v87, vcc, 0, v145, vcc
	s_waitcnt vmcnt(15)
	s_nop 1
	v_mov_b32_e32 v82, v184
	v_mov_b32_e32 v83, v185
	v_mov_b32_e32 v84, v186
	v_mov_b32_e32 v85, v187
	s_waitcnt lgkmcnt(0)
; DI unsigned pack2(float a, float b) { f32x2 v = {a, b}; hwbf16x2 r = __builtin_convertvector(v, hwbf16x2); return __builtin_bit_cast(unsigned, r); }
; DI float bflo(unsigned w) { return __uint_as_float(w << 16); }
; DI float bfhi(unsigned w) { return __uint_as_float(w & 0xffff0000u); }
;     DI void operator()(const f32x4 (&acc)[2][2][4][2], const Unit& u, int wr, int wc, int fr, int fq) const {
;     ...
;             for (int m = 0; m < 4; ++m) { const size_t ro = (size_t)(row0 + ai * HALF + m * 16) * D + col0;
; #pragma unroll
;                 for (int bj = 0; bj < 2; ++bj) {
;                     f32x4 x0, x1;
;                     if constexpr (IB) { const u32x4 w = *(const u32x4*)((const bf16_t*)Xin + ro + bj * HALF);
;                         x0 = (f32x4){bflo(w[0]), bfhi(w[0]), bflo(w[1]), bfhi(w[1])}; x1 = (f32x4){bflo(w[2]), bfhi(w[2]), bflo(w[3]), bfhi(w[3])}; }
;                     else { x0 = *(const f32x4*)((const float*)Xin + ro + bj * HALF); x1 = *(const f32x4*)((const float*)Xin + ro + bj * HALF + 4); }
;                     x0 += acc[ai][bj][m][0] * sc[bj][0]; x1 += acc[ai][bj][m][1] * sc[bj][1];
;                     if constexpr (OB) { u32x4 o; o[0] = pack2(x0[0], x0[1]); o[1] = pack2(x0[2], x0[3]); o[2] = pack2(x1[0], x1[1]); o[3] = pack2(x1[2], x1[3]);
;                         *(u32x4*)((bf16_t*)Xout + ro + bj * HALF) = o; }
	v_lshlrev_b32_e32 v88, 16, v82
	v_and_b32_e32 v89, 0xffff0000, v82
	v_lshlrev_b32_e32 v82, 16, v83
	v_and_b32_e32 v83, 0xffff0000, v83
	v_lshlrev_b32_e32 v90, 16, v84
	v_and_b32_e32 v91, 0xffff0000, v84
	v_lshlrev_b32_e32 v84, 16, v85
	v_and_b32_e32 v85, 0xffff0000, v85
	v_pk_add_f32 v[78:79], v[78:79], v[82:83]
	v_pk_add_f32 v[76:77], v[76:77], v[88:89]
	v_pk_add_f32 v[82:83], v[74:75], v[84:85]
	v_pk_add_f32 v[74:75], v[72:73], v[90:91]
	v_cvt_pk_bf16_f32 v72, v76, v77
	v_cvt_pk_bf16_f32 v73, v78, v79
	v_cvt_pk_bf16_f32 v74, v74, v75
	v_cvt_pk_bf16_f32 v75, v82, v83
	global_store_dwordx4 v[86:87], v[72:75], off
	s_waitcnt vmcnt(15)
	s_nop 1
	v_mov_b32_e32 v72, v188
	v_mov_b32_e32 v73, v189
	v_mov_b32_e32 v74, v190
	v_mov_b32_e32 v75, v191
	s_waitcnt lgkmcnt(0)
	v_lshlrev_b32_e32 v76, 16, v72
	v_and_b32_e32 v77, 0xffff0000, v72
	v_lshlrev_b32_e32 v72, 16, v73
	v_and_b32_e32 v73, 0xffff0000, v73
	v_lshlrev_b32_e32 v78, 16, v74
	v_and_b32_e32 v79, 0xffff0000, v74
	v_lshlrev_b32_e32 v74, 16, v75
	v_and_b32_e32 v75, 0xffff0000, v75
	v_pk_add_f32 v[70:71], v[70:71], v[72:73]
	v_pk_add_f32 v[68:69], v[68:69], v[76:77]
	v_pk_add_f32 v[72:73], v[66:67], v[74:75]
	v_pk_add_f32 v[66:67], v[64:65], v[78:79]
	v_cvt_pk_bf16_f32 v64, v68, v69
	v_cvt_pk_bf16_f32 v65, v70, v71
	v_cvt_pk_bf16_f32 v66, v66, v67
	v_cvt_pk_bf16_f32 v67, v72, v73
	global_store_dwordx4 v[80:81], v[64:67], off offset:256
	s_nop 1
	v_lshl_add_u64 v[64:65], v[144:145], 0, s[2:3]
	s_mov_b32 s2, 0x80000
	v_add_co_u32_e32 v70, vcc, s2, v144
	s_mov_b64 s[2:3], 0x90000
	s_nop 0
	v_addc_co_u32_e32 v71, vcc, 0, v145, vcc
	s_waitcnt vmcnt(15)
	s_nop 1
	v_mov_b32_e32 v66, v192
	v_mov_b32_e32 v67, v193
	v_mov_b32_e32 v68, v194
	v_mov_b32_e32 v69, v195
	s_waitcnt lgkmcnt(0)
	v_lshlrev_b32_e32 v72, 16, v66
	v_and_b32_e32 v73, 0xffff0000, v66
	v_lshlrev_b32_e32 v66, 16, v67
	v_and_b32_e32 v67, 0xffff0000, v67
	v_lshlrev_b32_e32 v74, 16, v68
	v_and_b32_e32 v75, 0xffff0000, v68
	v_lshlrev_b32_e32 v68, 16, v69
	v_and_b32_e32 v69, 0xffff0000, v69
	v_pk_add_f32 v[62:63], v[62:63], v[66:67]
	v_pk_add_f32 v[60:61], v[60:61], v[72:73]
	v_pk_add_f32 v[66:67], v[58:59], v[68:69]
	v_pk_add_f32 v[58:59], v[56:57], v[74:75]
	v_cvt_pk_bf16_f32 v56, v60, v61
	v_cvt_pk_bf16_f32 v57, v62, v63
	v_cvt_pk_bf16_f32 v58, v58, v59
	v_cvt_pk_bf16_f32 v59, v66, v67
	global_store_dwordx4 v[70:71], v[56:59], off
	s_waitcnt vmcnt(15)
	s_nop 1
	v_mov_b32_e32 v56, v198
	v_mov_b32_e32 v57, v199
	v_mov_b32_e32 v58, v200
	v_mov_b32_e32 v59, v201
	s_waitcnt lgkmcnt(0)
	v_lshlrev_b32_e32 v60, 16, v56
	v_and_b32_e32 v61, 0xffff0000, v56
	v_lshlrev_b32_e32 v56, 16, v57
	v_and_b32_e32 v57, 0xffff0000, v57
	v_lshlrev_b32_e32 v62, 16, v58
	v_and_b32_e32 v63, 0xffff0000, v58
	v_lshlrev_b32_e32 v58, 16, v59
	v_and_b32_e32 v59, 0xffff0000, v59
	v_pk_add_f32 v[54:55], v[54:55], v[56:57]
	v_pk_add_f32 v[52:53], v[52:53], v[60:61]
	v_pk_add_f32 v[56:57], v[50:51], v[58:59]
	v_pk_add_f32 v[50:51], v[48:49], v[62:63]
	v_cvt_pk_bf16_f32 v48, v52, v53
	v_cvt_pk_bf16_f32 v49, v54, v55
	v_cvt_pk_bf16_f32 v50, v50, v51
	v_cvt_pk_bf16_f32 v51, v56, v57
	global_store_dwordx4 v[64:65], v[48:51], off offset:256
	s_nop 1
	v_lshl_add_u64 v[48:49], v[144:145], 0, s[2:3]
	s_mov_b32 s2, 0x90000
	v_add_co_u32_e32 v54, vcc, s2, v144
	s_mov_b64 s[2:3], 0xa0000
	s_nop 0
	v_addc_co_u32_e32 v55, vcc, 0, v145, vcc
	s_waitcnt vmcnt(15)
	s_nop 1
	v_mov_b32_e32 v50, v202
	v_mov_b32_e32 v51, v203
	v_mov_b32_e32 v52, v204
	v_mov_b32_e32 v53, v205
	s_waitcnt lgkmcnt(0)
	v_lshlrev_b32_e32 v56, 16, v50
	v_and_b32_e32 v57, 0xffff0000, v50
	v_lshlrev_b32_e32 v50, 16, v51
	v_and_b32_e32 v51, 0xffff0000, v51
	v_lshlrev_b32_e32 v58, 16, v52
	v_and_b32_e32 v59, 0xffff0000, v52
	v_lshlrev_b32_e32 v52, 16, v53
	v_and_b32_e32 v53, 0xffff0000, v53
	v_pk_add_f32 v[46:47], v[46:47], v[50:51]
	v_pk_add_f32 v[44:45], v[44:45], v[56:57]
	v_pk_add_f32 v[50:51], v[42:43], v[52:53]
	v_pk_add_f32 v[42:43], v[40:41], v[58:59]
	v_cvt_pk_bf16_f32 v40, v44, v45
	v_cvt_pk_bf16_f32 v41, v46, v47
	v_cvt_pk_bf16_f32 v42, v42, v43
	v_cvt_pk_bf16_f32 v43, v50, v51
	global_store_dwordx4 v[54:55], v[40:43], off
	s_waitcnt vmcnt(15)
	s_nop 1
	v_mov_b32_e32 v40, v206
	v_mov_b32_e32 v41, v207
	v_mov_b32_e32 v42, v208
	v_mov_b32_e32 v43, v209
	s_waitcnt lgkmcnt(0)
; DI unsigned pack2(float a, float b) { f32x2 v = {a, b}; hwbf16x2 r = __builtin_convertvector(v, hwbf16x2); return __builtin_bit_cast(unsigned, r); }
; DI float bflo(unsigned w) { return __uint_as_float(w << 16); }
; DI float bfhi(unsigned w) { return __uint_as_float(w & 0xffff0000u); }
;     DI void operator()(const f32x4 (&acc)[2][2][4][2], const Unit& u, int wr, int wc, int fr, int fq) const {
;     ...
;             for (int m = 0; m < 4; ++m) { const size_t ro = (size_t)(row0 + ai * HALF + m * 16) * D + col0;
; #pragma unroll
;                 for (int bj = 0; bj < 2; ++bj) {
;                     f32x4 x0, x1;
;                     if constexpr (IB) { const u32x4 w = *(const u32x4*)((const bf16_t*)Xin + ro + bj * HALF);
;                         x0 = (f32x4){bflo(w[0]), bfhi(w[0]), bflo(w[1]), bfhi(w[1])}; x1 = (f32x4){bflo(w[2]), bfhi(w[2]), bflo(w[3]), bfhi(w[3])}; }
;                     else { x0 = *(const f32x4*)((const float*)Xin + ro + bj * HALF); x1 = *(const f32x4*)((const float*)Xin + ro + bj * HALF + 4); }
;                     x0 += acc[ai][bj][m][0] * sc[bj][0]; x1 += acc[ai][bj][m][1] * sc[bj][1];
;                     if constexpr (OB) { u32x4 o; o[0] = pack2(x0[0], x0[1]); o[1] = pack2(x0[2], x0[3]); o[2] = pack2(x1[0], x1[1]); o[3] = pack2(x1[2], x1[3]);
;                         *(u32x4*)((bf16_t*)Xout + ro + bj * HALF) = o; }
	v_lshlrev_b32_e32 v44, 16, v40
	v_and_b32_e32 v45, 0xffff0000, v40
	v_lshlrev_b32_e32 v40, 16, v41
	v_and_b32_e32 v41, 0xffff0000, v41
	v_lshlrev_b32_e32 v46, 16, v42
	v_and_b32_e32 v47, 0xffff0000, v42
	v_lshlrev_b32_e32 v42, 16, v43
	v_and_b32_e32 v43, 0xffff0000, v43
	v_pk_add_f32 v[38:39], v[38:39], v[40:41]
	v_pk_add_f32 v[36:37], v[36:37], v[44:45]
	v_pk_add_f32 v[40:41], v[34:35], v[42:43]
	v_pk_add_f32 v[34:35], v[32:33], v[46:47]
	v_cvt_pk_bf16_f32 v32, v36, v37
	v_cvt_pk_bf16_f32 v33, v38, v39
	v_cvt_pk_bf16_f32 v34, v34, v35
	v_cvt_pk_bf16_f32 v35, v40, v41
	global_store_dwordx4 v[48:49], v[32:35], off offset:256
	s_nop 1
	v_lshl_add_u64 v[32:33], v[144:145], 0, s[2:3]
	s_mov_b32 s2, 0xa0000
	v_add_co_u32_e32 v38, vcc, s2, v144
	s_mov_b64 s[2:3], 0xb0000
	s_nop 0
	v_addc_co_u32_e32 v39, vcc, 0, v145, vcc
	s_waitcnt vmcnt(15)
	s_nop 1
	v_mov_b32_e32 v34, v210
	v_mov_b32_e32 v35, v211
	v_mov_b32_e32 v36, v212
	v_mov_b32_e32 v37, v213
	s_waitcnt lgkmcnt(0)
	v_lshlrev_b32_e32 v40, 16, v34
	v_and_b32_e32 v41, 0xffff0000, v34
	v_lshlrev_b32_e32 v34, 16, v35
	v_and_b32_e32 v35, 0xffff0000, v35
	v_lshlrev_b32_e32 v42, 16, v36
	v_and_b32_e32 v43, 0xffff0000, v36
	v_lshlrev_b32_e32 v36, 16, v37
	v_and_b32_e32 v37, 0xffff0000, v37
	v_pk_add_f32 v[30:31], v[30:31], v[34:35]
	v_pk_add_f32 v[28:29], v[28:29], v[40:41]
	v_pk_add_f32 v[34:35], v[26:27], v[36:37]
	v_pk_add_f32 v[26:27], v[24:25], v[42:43]
	v_cvt_pk_bf16_f32 v24, v28, v29
	v_cvt_pk_bf16_f32 v25, v30, v31
	v_cvt_pk_bf16_f32 v26, v26, v27
	v_cvt_pk_bf16_f32 v27, v34, v35
	global_store_dwordx4 v[38:39], v[24:27], off
	s_waitcnt vmcnt(15)
	s_nop 1
	v_mov_b32_e32 v24, v214
	v_mov_b32_e32 v25, v215
	v_mov_b32_e32 v26, v216
	v_mov_b32_e32 v27, v217
	s_waitcnt lgkmcnt(0)
	v_lshlrev_b32_e32 v28, 16, v24
	v_and_b32_e32 v29, 0xffff0000, v24
	v_lshlrev_b32_e32 v24, 16, v25
	v_and_b32_e32 v25, 0xffff0000, v25
	v_lshlrev_b32_e32 v30, 16, v26
	v_and_b32_e32 v31, 0xffff0000, v26
	v_lshlrev_b32_e32 v26, 16, v27
	v_and_b32_e32 v27, 0xffff0000, v27
	v_pk_add_f32 v[22:23], v[22:23], v[24:25]
	v_pk_add_f32 v[20:21], v[20:21], v[28:29]
	v_pk_add_f32 v[24:25], v[18:19], v[26:27]
	v_pk_add_f32 v[18:19], v[16:17], v[30:31]
	v_cvt_pk_bf16_f32 v16, v20, v21
	v_cvt_pk_bf16_f32 v17, v22, v23
	v_cvt_pk_bf16_f32 v18, v18, v19
	v_cvt_pk_bf16_f32 v19, v24, v25
	global_store_dwordx4 v[32:33], v[16:19], off offset:256
	s_nop 1
	v_lshl_add_u64 v[16:17], v[144:145], 0, s[2:3]
	s_mov_b32 s2, 0xb0000
	v_add_co_u32_e32 v22, vcc, s2, v144
	s_mov_b32 s2, s55
	s_nop 0
	v_addc_co_u32_e32 v23, vcc, 0, v145, vcc
	s_waitcnt vmcnt(15)
	s_nop 1
	v_mov_b32_e32 v18, v248
	v_mov_b32_e32 v19, v249
	v_mov_b32_e32 v20, v250
	v_mov_b32_e32 v21, v251
	s_and_b64 vcc, exec, s[40:41]
	s_waitcnt lgkmcnt(0)
	v_lshlrev_b32_e32 v24, 16, v18
	v_and_b32_e32 v25, 0xffff0000, v18
	v_lshlrev_b32_e32 v18, 16, v19
	v_and_b32_e32 v19, 0xffff0000, v19
	v_lshlrev_b32_e32 v26, 16, v20
	v_and_b32_e32 v27, 0xffff0000, v20
	v_lshlrev_b32_e32 v20, 16, v21
	v_and_b32_e32 v21, 0xffff0000, v21
	v_pk_add_f32 v[14:15], v[14:15], v[18:19]
	v_pk_add_f32 v[12:13], v[12:13], v[24:25]
	v_pk_add_f32 v[18:19], v[10:11], v[20:21]
	v_pk_add_f32 v[10:11], v[8:9], v[26:27]
	v_cvt_pk_bf16_f32 v8, v12, v13
	v_cvt_pk_bf16_f32 v9, v14, v15
	v_cvt_pk_bf16_f32 v10, v10, v11
	v_cvt_pk_bf16_f32 v11, v18, v19
	global_store_dwordx4 v[22:23], v[8:11], off
	s_waitcnt vmcnt(15)
	s_nop 1
	v_mov_b32_e32 v8, v252
	v_mov_b32_e32 v9, v253
	v_mov_b32_e32 v10, v254
	v_mov_b32_e32 v11, v255
	s_waitcnt lgkmcnt(0)
	v_lshlrev_b32_e32 v12, 16, v8
	v_and_b32_e32 v13, 0xffff0000, v8
	v_lshlrev_b32_e32 v8, 16, v9
	v_and_b32_e32 v9, 0xffff0000, v9
	v_lshlrev_b32_e32 v14, 16, v10
	v_and_b32_e32 v15, 0xffff0000, v10
	v_lshlrev_b32_e32 v10, 16, v11
	v_and_b32_e32 v11, 0xffff0000, v11
	v_pk_add_f32 v[6:7], v[6:7], v[8:9]
	v_pk_add_f32 v[4:5], v[4:5], v[12:13]
	v_pk_add_f32 v[8:9], v[2:3], v[10:11]
	v_pk_add_f32 v[2:3], v[0:1], v[14:15]
	v_cvt_pk_bf16_f32 v0, v4, v5
	v_cvt_pk_bf16_f32 v1, v6, v7
	v_cvt_pk_bf16_f32 v2, v2, v3
	v_cvt_pk_bf16_f32 v3, v8, v9
	global_store_dwordx4 v[16:17], v[0:3], off offset:256
	s_cbranch_vccz .LBB1_543
	s_waitcnt vmcnt(0)
	s_cmpk_gt_u32 s17, 0xff
	s_cbranch_scc1 .LBB1_554
	s_barrier

; #define PG8_STAGE(bufoff, gbase, voff) do { _Pragma("unroll") for (int _i = 0; _i < 2; ++_i) \
;         __builtin_amdgcn_global_load_lds((const unsigned*)((const char*)(gbase) + (voff)[_i]), (LAS unsigned*)(lds + (bufoff) + ldsw + _i * 8192), 16, 0, 0); } while (0)
; #define PG8_LDA(dst, b, h) do { _Pragma("unroll") for (int m = 0; m < 4; ++m) _Pragma("unroll") for (int k = 0; k < 2; ++k) dst[m][k] = *(const LAS bf16x8*)(lds + PG8_SA(b, h) + aoff + m * 2048 + k * 1024); } while (0)
; #define PG8_LDB(dst, b, h) do { _Pragma("unroll") for (int n = 0; n < 2; ++n) _Pragma("unroll") for (int k = 0; k < 2; ++k) dst[n][k] = *(const LAS bf16x8*)(lds + PG8_SB(b, h) + boff + n * 2048 + k * 1024); } while (0)
; #define PG8_MMA(ai, bj, At, Bt) do { __builtin_amdgcn_s_setprio(1); _Pragma("unroll") for (int m = 0; m < 4; ++m) _Pragma("unroll") for (int n = 0; n < 2; ++n) _Pragma("unroll") for (int k = 0; k < 2; ++k) \
;         acc[ai][bj][m][n] = __builtin_amdgcn_mfma_f32_16x16x32_bf16(Bt[n][k], At[m][k], acc[ai][bj][m][n], 0, 0, 0); __builtin_amdgcn_s_setprio(0); } while (0)
; #define PG8_WAIT_L(n) asm volatile("s_waitcnt lgkmcnt(" #n ")" ::: "memory")
; #define PG8_BAR __builtin_amdgcn_s_barrier()
; #define PG8_SCHED __builtin_amdgcn_sched_barrier(0)
; template <class Map, class Epi>
; DI void gemm_phase(LAS unsigned char* lds, const Map& MP, const Epi& E, const int nM, const int nN, const int K, const int lda, const int ldb) {
;     ...
;             PG8_LDB(B0, 0, 0); PG8_SCHED; PG8_LDA(At, 0, 0); PG8_STAGE(PG8_SA(1, 1), a1 + hstepA, voffA);
;             PG8_WAIT_L(8); PG8_BAR; PG8_WAIT_L(0); PG8_MMA(0, 0, At, B0); PG8_BAR; PG8_SCHED;
;             PG8_LDB(B1, 0, 1); PG8_STAGE(PG8_SB(0, 0), b2, voffB);
;             PG8_BAR; PG8_WAIT_L(0); PG8_MMA(0, 1, At, B1); PG8_BAR;
;             PG8_LDA(At, 0, 1); PG8_STAGE(PG8_SA(0, 0), a2, voffA);
;             PG8_BAR; PG8_WAIT_L(0); PG8_MMA(1, 0, At, B0); PG8_BAR; PG8_SCHED;
.LBB1_925:
	ds_read_b128 v[152:155], v149
	ds_read_b128 v[156:159], v149 offset:1024
	ds_read_b128 v[160:163], v149 offset:2048
	ds_read_b128 v[164:167], v149 offset:3072
	s_add_u32 s3, s10, 0xfff80080
	s_addc_u32 s12, s11, -1
	s_cmp_eq_u32 s48, 28
	s_cselect_b32 s15, s4, s12
	s_cselect_b32 s14, s5, s3
	s_cselect_b32 s13, s37, s47
	s_cselect_b32 s12, s38, s39
	v_lshl_add_u64 v[144:145], s[10:11], 0, v[138:139]
	s_add_i32 m0, s24, 0xc000
	ds_read_b128 v[168:171], v150
	ds_read_b128 v[172:175], v150 offset:1024
	ds_read_b128 v[176:179], v150 offset:2048
	ds_read_b128 v[180:183], v150 offset:3072
	ds_read_b128 v[184:187], v150 offset:4096
	ds_read_b128 v[188:191], v150 offset:5120
	ds_read_b128 v[192:195], v150 offset:6144
	ds_read_b128 v[198:201], v150 offset:7168
	global_load_lds_dwordx4 v[144:145], off
	v_lshl_add_u64 v[144:145], s[10:11], 0, v[136:137]
	s_add_i32 m0, s24, 0xe000
	s_nop 0
	global_load_lds_dwordx4 v[144:145], off
	s_waitcnt lgkmcnt(8)
	s_barrier
	s_setprio 1
	s_waitcnt lgkmcnt(7)
	v_mfma_f32_16x16x32_bf16 v[124:127], v[152:155], v[168:171], v[124:127]
	v_mfma_f32_16x16x32_bf16 v[120:123], v[160:163], v[168:171], v[120:123]
	s_waitcnt lgkmcnt(5)
	v_mfma_f32_16x16x32_bf16 v[108:111], v[152:155], v[176:179], v[108:111]
	v_mfma_f32_16x16x32_bf16 v[104:107], v[160:163], v[176:179], v[104:107]
	s_waitcnt lgkmcnt(3)
	v_mfma_f32_16x16x32_bf16 v[92:95], v[152:155], v[184:187], v[92:95]
	v_mfma_f32_16x16x32_bf16 v[88:91], v[160:163], v[184:187], v[88:91]
	s_waitcnt lgkmcnt(1)
	v_mfma_f32_16x16x32_bf16 v[76:79], v[152:155], v[192:195], v[76:79]
	v_mfma_f32_16x16x32_bf16 v[72:75], v[160:163], v[192:195], v[72:75]
	v_mfma_f32_16x16x32_bf16 v[124:127], v[156:159], v[172:175], v[124:127]
	v_mfma_f32_16x16x32_bf16 v[120:123], v[164:167], v[172:175], v[120:123]
	v_mfma_f32_16x16x32_bf16 v[108:111], v[156:159], v[180:183], v[108:111]
	v_mfma_f32_16x16x32_bf16 v[104:107], v[164:167], v[180:183], v[104:107]
	v_mfma_f32_16x16x32_bf16 v[92:95], v[156:159], v[188:191], v[92:95]
	v_mfma_f32_16x16x32_bf16 v[88:91], v[164:167], v[188:191], v[88:91]
	s_waitcnt lgkmcnt(0)
	v_mfma_f32_16x16x32_bf16 v[76:79], v[156:159], v[198:201], v[76:79]
	v_mfma_f32_16x16x32_bf16 v[72:75], v[164:167], v[198:201], v[72:75]
	s_setprio 0
	s_barrier
	s_add_i32 s3, s35, s22
	v_lshl_add_u64 v[144:145], s[12:13], 0, v[132:133]
	s_mov_b32 m0, s3
	ds_read_b128 v[202:205], v151
	ds_read_b128 v[206:209], v151 offset:1024
	ds_read_b128 v[210:213], v151 offset:2048
	ds_read_b128 v[214:217], v151 offset:3072
	global_load_lds_dwordx4 v[144:145], off
	v_lshl_add_u64 v[218:219], s[12:13], 0, v[128:129]
	s_add_i32 m0, s3, 0x2000
	s_nop 0
	global_load_lds_dwordx4 v[218:219], off
	s_barrier
	s_setprio 1
	s_waitcnt lgkmcnt(3)
	v_mfma_f32_16x16x32_bf16 v[116:119], v[202:205], v[168:171], v[116:119]
	s_waitcnt lgkmcnt(1)
	v_mfma_f32_16x16x32_bf16 v[112:115], v[210:213], v[168:171], v[112:115]
	v_mfma_f32_16x16x32_bf16 v[100:103], v[202:205], v[176:179], v[100:103]
	v_mfma_f32_16x16x32_bf16 v[96:99], v[210:213], v[176:179], v[96:99]
	v_mfma_f32_16x16x32_bf16 v[84:87], v[202:205], v[184:187], v[84:87]
	v_mfma_f32_16x16x32_bf16 v[80:83], v[210:213], v[184:187], v[80:83]
	v_mfma_f32_16x16x32_bf16 v[68:71], v[202:205], v[192:195], v[68:71]
	v_mfma_f32_16x16x32_bf16 v[64:67], v[210:213], v[192:195], v[64:67]
	v_mfma_f32_16x16x32_bf16 v[116:119], v[206:209], v[172:175], v[116:119]
	s_waitcnt lgkmcnt(0)
	v_mfma_f32_16x16x32_bf16 v[112:115], v[214:217], v[172:175], v[112:115]
	v_mfma_f32_16x16x32_bf16 v[100:103], v[206:209], v[180:183], v[100:103]
	v_mfma_f32_16x16x32_bf16 v[96:99], v[214:217], v[180:183], v[96:99]
	v_mfma_f32_16x16x32_bf16 v[84:87], v[206:209], v[188:191], v[84:87]
	v_mfma_f32_16x16x32_bf16 v[80:83], v[214:217], v[188:191], v[80:83]
	v_mfma_f32_16x16x32_bf16 v[68:71], v[206:209], v[198:201], v[68:71]
	v_mfma_f32_16x16x32_bf16 v[64:67], v[214:217], v[198:201], v[64:67]
	s_setprio 0
	s_mov_b32 m0, s24
	v_lshl_add_u64 v[220:221], s[14:15], 0, v[134:135]
	s_barrier
	ds_read_b128 v[168:171], v150 offset:16384
	ds_read_b128 v[172:175], v150 offset:17408
	ds_read_b128 v[176:179], v150 offset:18432
	ds_read_b128 v[180:183], v150 offset:19456
	ds_read_b128 v[184:187], v150 offset:20480
	ds_read_b128 v[188:191], v150 offset:21504
	ds_read_b128 v[192:195], v150 offset:22528
	ds_read_b128 v[198:201], v150 offset:23552
	global_load_lds_dwordx4 v[220:221], off
	v_lshl_add_u64 v[222:223], s[14:15], 0, v[130:131]
	s_mov_b32 m0, s9
	s_nop 0
	global_load_lds_dwordx4 v[222:223], off
	s_barrier
	s_setprio 1
	s_waitcnt lgkmcnt(7)
	v_mfma_f32_16x16x32_bf16 v[60:63], v[152:155], v[168:171], v[60:63]
	v_mfma_f32_16x16x32_bf16 v[56:59], v[160:163], v[168:171], v[56:59]
	s_waitcnt lgkmcnt(5)
	v_mfma_f32_16x16x32_bf16 v[44:47], v[152:155], v[176:179], v[44:47]
	v_mfma_f32_16x16x32_bf16 v[40:43], v[160:163], v[176:179], v[40:43]
	s_waitcnt lgkmcnt(3)
	v_mfma_f32_16x16x32_bf16 v[28:31], v[152:155], v[184:187], v[28:31]
	v_mfma_f32_16x16x32_bf16 v[24:27], v[160:163], v[184:187], v[24:27]
	s_waitcnt lgkmcnt(1)
	v_mfma_f32_16x16x32_bf16 v[12:15], v[152:155], v[192:195], v[12:15]
	v_mfma_f32_16x16x32_bf16 v[8:11], v[160:163], v[192:195], v[8:11]
	v_mfma_f32_16x16x32_bf16 v[60:63], v[156:159], v[172:175], v[60:63]
	v_mfma_f32_16x16x32_bf16 v[56:59], v[164:167], v[172:175], v[56:59]
	v_mfma_f32_16x16x32_bf16 v[44:47], v[156:159], v[180:183], v[44:47]
	v_mfma_f32_16x16x32_bf16 v[40:43], v[164:167], v[180:183], v[40:43]
	v_mfma_f32_16x16x32_bf16 v[28:31], v[156:159], v[188:191], v[28:31]
	v_mfma_f32_16x16x32_bf16 v[24:27], v[164:167], v[188:191], v[24:27]
	s_waitcnt lgkmcnt(0)
	v_mfma_f32_16x16x32_bf16 v[12:15], v[156:159], v[198:201], v[12:15]
	v_mfma_f32_16x16x32_bf16 v[8:11], v[164:167], v[198:201], v[8:11]
	s_setprio 0
	s_barrier
; #define PG8_STAGE(bufoff, gbase, voff) do { _Pragma("unroll") for (int _i = 0; _i < 2; ++_i) \
;         __builtin_amdgcn_global_load_lds((const unsigned*)((const char*)(gbase) + (voff)[_i]), (LAS unsigned*)(lds + (bufoff) + ldsw + _i * 8192), 16, 0, 0); } while (0)
; #define PG8_LDA(dst, b, h) do { _Pragma("unroll") for (int m = 0; m < 4; ++m) _Pragma("unroll") for (int k = 0; k < 2; ++k) dst[m][k] = *(const LAS bf16x8*)(lds + PG8_SA(b, h) + aoff + m * 2048 + k * 1024); } while (0)
; #define PG8_LDB(dst, b, h) do { _Pragma("unroll") for (int n = 0; n < 2; ++n) _Pragma("unroll") for (int k = 0; k < 2; ++k) dst[n][k] = *(const LAS bf16x8*)(lds + PG8_SB(b, h) + boff + n * 2048 + k * 1024); } while (0)
; #define PG8_MMA(ai, bj, At, Bt) do { __builtin_amdgcn_s_setprio(1); _Pragma("unroll") for (int m = 0; m < 4; ++m) _Pragma("unroll") for (int n = 0; n < 2; ++n) _Pragma("unroll") for (int k = 0; k < 2; ++k) \
;         acc[ai][bj][m][n] = __builtin_amdgcn_mfma_f32_16x16x32_bf16(Bt[n][k], At[m][k], acc[ai][bj][m][n], 0, 0, 0); __builtin_amdgcn_s_setprio(0); } while (0)
; #define PG8_WAIT_V(n) asm volatile("s_waitcnt vmcnt(" #n ")" ::: "memory")
; #define PG8_WAIT_L(n) asm volatile("s_waitcnt lgkmcnt(" #n ")" ::: "memory")
; #define PG8_BAR __builtin_amdgcn_s_barrier()
; #define PG8_SCHED __builtin_amdgcn_sched_barrier(0)
; template <class Map, class Epi>
; DI void gemm_phase(LAS unsigned char* lds, const Map& MP, const Epi& E, const int nM, const int nN, const int K, const int lda, const int ldb) {
;     ...
;             PG8_STAGE(PG8_SB(0, 1), b2 + hstepB, voffB);
;             PG8_WAIT_V(6); PG8_BAR; PG8_MMA(1, 1, At, B1); PG8_BAR;
;             PG8_LDB(B0, 1, 0); PG8_SCHED; PG8_LDA(At, 1, 0); PG8_STAGE(PG8_SA(0, 1), a2 + hstepA, voffA);
;             PG8_WAIT_L(8); PG8_BAR; PG8_WAIT_L(0); PG8_MMA(0, 0, At, B0); PG8_BAR; PG8_SCHED;
;             PG8_LDB(B1, 1, 1); PG8_STAGE(PG8_SB(1, 0), b3, voffB);
;             PG8_BAR; PG8_WAIT_L(0); PG8_MMA(0, 1, At, B1); PG8_BAR;
	s_add_u32 s56, s12, 0x80000
	s_addc_u32 s57, s13, 0
	s_add_i32 s3, s36, s22
	v_lshl_add_u64 v[152:153], s[56:57], 0, v[132:133]
	s_mov_b32 m0, s3
	s_nop 0
	global_load_lds_dwordx4 v[152:153], off
	v_lshl_add_u64 v[152:153], s[56:57], 0, v[128:129]
	s_add_i32 m0, s3, 0x2000
	s_nop 0
	global_load_lds_dwordx4 v[152:153], off
	s_waitcnt vmcnt(6)
	s_barrier
	s_setprio 1
	v_mfma_f32_16x16x32_bf16 v[52:55], v[202:205], v[168:171], v[52:55]
	v_mfma_f32_16x16x32_bf16 v[48:51], v[210:213], v[168:171], v[48:51]
	v_mfma_f32_16x16x32_bf16 v[36:39], v[202:205], v[176:179], v[36:39]
	v_mfma_f32_16x16x32_bf16 v[32:35], v[210:213], v[176:179], v[32:35]
	v_mfma_f32_16x16x32_bf16 v[20:23], v[202:205], v[184:187], v[20:23]
	v_mfma_f32_16x16x32_bf16 v[16:19], v[210:213], v[184:187], v[16:19]
	v_mfma_f32_16x16x32_bf16 v[4:7], v[202:205], v[192:195], v[4:7]
	v_mfma_f32_16x16x32_bf16 v[0:3], v[210:213], v[192:195], v[0:3]
	v_mfma_f32_16x16x32_bf16 v[52:55], v[206:209], v[172:175], v[52:55]
	v_mfma_f32_16x16x32_bf16 v[48:51], v[214:217], v[172:175], v[48:51]
	v_mfma_f32_16x16x32_bf16 v[36:39], v[206:209], v[180:183], v[36:39]
	v_mfma_f32_16x16x32_bf16 v[32:35], v[214:217], v[180:183], v[32:35]
	v_mfma_f32_16x16x32_bf16 v[20:23], v[206:209], v[188:191], v[20:23]
	v_mfma_f32_16x16x32_bf16 v[16:19], v[214:217], v[188:191], v[16:19]
	v_mfma_f32_16x16x32_bf16 v[4:7], v[206:209], v[198:201], v[4:7]
	v_mfma_f32_16x16x32_bf16 v[0:3], v[214:217], v[198:201], v[0:3]
	s_setprio 0
	s_add_i32 s3, 0, 0x18000
	v_add_u32_e32 v164, s3, v148
	s_barrier
	ds_read_b128 v[152:155], v164
	ds_read_b128 v[156:159], v164 offset:1024
	ds_read_b128 v[160:163], v164 offset:2048
	ds_read_b128 v[164:167], v164 offset:3072
	s_add_u32 s14, s14, 0x80000
	s_addc_u32 s15, s15, 0
	s_mov_b32 m0, s25
	v_lshl_add_u64 v[202:203], s[14:15], 0, v[134:135]
	ds_read_b128 v[168:171], v150 offset:32768
	ds_read_b128 v[172:175], v150 offset:33792
	ds_read_b128 v[176:179], v150 offset:34816
	ds_read_b128 v[180:183], v150 offset:35840
	ds_read_b128 v[184:187], v150 offset:36864
	ds_read_b128 v[188:191], v150 offset:37888
	ds_read_b128 v[192:195], v150 offset:38912
	ds_read_b128 v[198:201], v150 offset:39936
	global_load_lds_dwordx4 v[202:203], off
	v_lshl_add_u64 v[202:203], s[14:15], 0, v[130:131]
	s_mov_b32 m0, s26
	s_nop 0
	global_load_lds_dwordx4 v[202:203], off
	s_waitcnt lgkmcnt(8)
	s_barrier
	s_setprio 1
	s_waitcnt lgkmcnt(7)
	v_mfma_f32_16x16x32_bf16 v[124:127], v[152:155], v[168:171], v[124:127]
	v_mfma_f32_16x16x32_bf16 v[120:123], v[160:163], v[168:171], v[120:123]
	s_waitcnt lgkmcnt(5)
	v_mfma_f32_16x16x32_bf16 v[108:111], v[152:155], v[176:179], v[108:111]
	v_mfma_f32_16x16x32_bf16 v[104:107], v[160:163], v[176:179], v[104:107]
	s_waitcnt lgkmcnt(3)
	v_mfma_f32_16x16x32_bf16 v[92:95], v[152:155], v[184:187], v[92:95]
	v_mfma_f32_16x16x32_bf16 v[88:91], v[160:163], v[184:187], v[88:91]
	s_waitcnt lgkmcnt(1)
	v_mfma_f32_16x16x32_bf16 v[76:79], v[152:155], v[192:195], v[76:79]
	v_mfma_f32_16x16x32_bf16 v[72:75], v[160:163], v[192:195], v[72:75]
	v_mfma_f32_16x16x32_bf16 v[124:127], v[156:159], v[172:175], v[124:127]
	v_mfma_f32_16x16x32_bf16 v[120:123], v[164:167], v[172:175], v[120:123]
	v_mfma_f32_16x16x32_bf16 v[108:111], v[156:159], v[180:183], v[108:111]
	v_mfma_f32_16x16x32_bf16 v[104:107], v[164:167], v[180:183], v[104:107]
	v_mfma_f32_16x16x32_bf16 v[92:95], v[156:159], v[188:191], v[92:95]
	v_mfma_f32_16x16x32_bf16 v[88:91], v[164:167], v[188:191], v[88:91]
	s_waitcnt lgkmcnt(0)
	v_mfma_f32_16x16x32_bf16 v[76:79], v[156:159], v[198:201], v[76:79]
	v_mfma_f32_16x16x32_bf16 v[72:75], v[164:167], v[198:201], v[72:75]
	s_setprio 0
	s_barrier
	s_add_i32 s14, 0, 0x1c000
	s_add_i32 s3, s3, s22
	v_add_u32_e32 v196, s14, v148
	v_lshl_add_u64 v[144:145], v[144:145], 0, s[44:45]
	s_mov_b32 m0, s3
	ds_read_b128 v[202:205], v196
	ds_read_b128 v[206:209], v196 offset:1024
	ds_read_b128 v[210:213], v196 offset:2048
	ds_read_b128 v[214:217], v196 offset:3072
	global_load_lds_dwordx4 v[144:145], off
	v_lshl_add_u64 v[144:145], v[218:219], 0, s[44:45]
	s_add_i32 m0, s3, 0x2000
	s_nop 0
	global_load_lds_dwordx4 v[144:145], off
	s_barrier
	s_setprio 1
	s_waitcnt lgkmcnt(3)
	v_mfma_f32_16x16x32_bf16 v[116:119], v[202:205], v[168:171], v[116:119]
	s_waitcnt lgkmcnt(1)
	v_mfma_f32_16x16x32_bf16 v[112:115], v[210:213], v[168:171], v[112:115]
	v_mfma_f32_16x16x32_bf16 v[100:103], v[202:205], v[176:179], v[100:103]
	v_mfma_f32_16x16x32_bf16 v[96:99], v[210:213], v[176:179], v[96:99]
	v_mfma_f32_16x16x32_bf16 v[84:87], v[202:205], v[184:187], v[84:87]
	v_mfma_f32_16x16x32_bf16 v[80:83], v[210:213], v[184:187], v[80:83]
	v_mfma_f32_16x16x32_bf16 v[68:71], v[202:205], v[192:195], v[68:71]
	v_mfma_f32_16x16x32_bf16 v[64:67], v[210:213], v[192:195], v[64:67]
	v_mfma_f32_16x16x32_bf16 v[116:119], v[206:209], v[172:175], v[116:119]
	s_waitcnt lgkmcnt(0)
	v_mfma_f32_16x16x32_bf16 v[112:115], v[214:217], v[172:175], v[112:115]
	v_mfma_f32_16x16x32_bf16 v[100:103], v[206:209], v[180:183], v[100:103]
	v_mfma_f32_16x16x32_bf16 v[96:99], v[214:217], v[180:183], v[96:99]
	v_mfma_f32_16x16x32_bf16 v[84:87], v[206:209], v[188:191], v[84:87]
	v_mfma_f32_16x16x32_bf16 v[80:83], v[214:217], v[188:191], v[80:83]
	v_mfma_f32_16x16x32_bf16 v[68:71], v[206:209], v[198:201], v[68:71]
	v_mfma_f32_16x16x32_bf16 v[64:67], v[214:217], v[198:201], v[64:67]
	s_setprio 0
	s_mov_b32 m0, s30
	v_lshl_add_u64 v[144:145], v[220:221], 0, s[44:45]
	s_barrier
; #define PG8_STAGE(bufoff, gbase, voff) do { _Pragma("unroll") for (int _i = 0; _i < 2; ++_i) \
;         __builtin_amdgcn_global_load_lds((const unsigned*)((const char*)(gbase) + (voff)[_i]), (LAS unsigned*)(lds + (bufoff) + ldsw + _i * 8192), 16, 0, 0); } while (0)
; #define PG8_LDA(dst, b, h) do { _Pragma("unroll") for (int m = 0; m < 4; ++m) _Pragma("unroll") for (int k = 0; k < 2; ++k) dst[m][k] = *(const LAS bf16x8*)(lds + PG8_SA(b, h) + aoff + m * 2048 + k * 1024); } while (0)
; #define PG8_MMA(ai, bj, At, Bt) do { __builtin_amdgcn_s_setprio(1); _Pragma("unroll") for (int m = 0; m < 4; ++m) _Pragma("unroll") for (int n = 0; n < 2; ++n) _Pragma("unroll") for (int k = 0; k < 2; ++k) \
;         acc[ai][bj][m][n] = __builtin_amdgcn_mfma_f32_16x16x32_bf16(Bt[n][k], At[m][k], acc[ai][bj][m][n], 0, 0, 0); __builtin_amdgcn_s_setprio(0); } while (0)
; #define PG8_WAIT_V(n) asm volatile("s_waitcnt vmcnt(" #n ")" ::: "memory")
; #define PG8_WAIT_L(n) asm volatile("s_waitcnt lgkmcnt(" #n ")" ::: "memory")
; #define PG8_BAR __builtin_amdgcn_s_barrier()
;     DI void operator()(const f32x4 (&acc)[2][2][4][2], const Unit& u, int wr, int wc, int fr, int fq) const {
;         const int row0 = u.pm * BM + wr * 64 + fr, col0 = u.pn * BM + wc * 32 + 8 * fq;
;         f32x4 sc[2][2];
; #pragma unroll
;         for (int bj = 0; bj < 2; ++bj)
; #pragma unroll
;             for (int n = 0; n < 2; ++n) sc[bj][n] = scale ? *(const f32x4*)(scale + col0 + bj * HALF + 4 * n) : (f32x4){1.f, 1.f, 1.f, 1.f};
; #pragma unroll
;         for (int ai = 0; ai < 2; ++ai)
; #pragma unroll
;             for (int m = 0; m < 4; ++m) { const size_t ro = (size_t)(row0 + ai * HALF + m * 16) * D + col0;
; #pragma unroll
;                 for (int bj = 0; bj < 2; ++bj) {
;                     f32x4 x0, x1;
;                     if constexpr (IB) { const u32x4 w = *(const u32x4*)((const bf16_t*)Xin + ro + bj * HALF);
; template <class Map, class Epi>
; DI void gemm_phase(LAS unsigned char* lds, const Map& MP, const Epi& E, const int nM, const int nN, const int K, const int lda, const int ldb) {
;     ...
;             PG8_LDA(At, 1, 1); PG8_STAGE(PG8_SA(1, 0), a3, voffA);
;             PG8_BAR; PG8_WAIT_L(0); PG8_MMA(1, 0, At, B0); PG8_BAR; PG8_SCHED;
;             PG8_STAGE(PG8_SB(1, 1), b3 + hstepB, voffB);
;             PG8_WAIT_V(6); PG8_BAR; PG8_MMA(1, 1, At, B1); PG8_BAR;
	ds_read_b128 v[168:171], v150 offset:49152
	ds_read_b128 v[172:175], v150 offset:50176
	ds_read_b128 v[176:179], v150 offset:51200
	ds_read_b128 v[180:183], v150 offset:52224
	ds_read_b128 v[184:187], v150 offset:53248
	ds_read_b128 v[188:191], v150 offset:54272
	ds_read_b128 v[192:195], v150 offset:55296
	ds_read_b128 v[198:201], v150 offset:56320
	global_load_lds_dwordx4 v[144:145], off
	v_lshl_add_u64 v[144:145], v[222:223], 0, s[44:45]
	s_mov_b32 m0, s31
	s_nop 0
	global_load_lds_dwordx4 v[144:145], off
	s_barrier
	s_setprio 1
	s_waitcnt lgkmcnt(7)
	v_mfma_f32_16x16x32_bf16 v[60:63], v[152:155], v[168:171], v[60:63]
	v_mfma_f32_16x16x32_bf16 v[56:59], v[160:163], v[168:171], v[56:59]
	s_waitcnt lgkmcnt(5)
	v_mfma_f32_16x16x32_bf16 v[44:47], v[152:155], v[176:179], v[44:47]
	v_mfma_f32_16x16x32_bf16 v[40:43], v[160:163], v[176:179], v[40:43]
	s_waitcnt lgkmcnt(3)
	v_mfma_f32_16x16x32_bf16 v[28:31], v[152:155], v[184:187], v[28:31]
	v_mfma_f32_16x16x32_bf16 v[24:27], v[160:163], v[184:187], v[24:27]
	s_waitcnt lgkmcnt(1)
	v_mfma_f32_16x16x32_bf16 v[12:15], v[152:155], v[192:195], v[12:15]
	v_mfma_f32_16x16x32_bf16 v[8:11], v[160:163], v[192:195], v[8:11]
	v_mfma_f32_16x16x32_bf16 v[60:63], v[156:159], v[172:175], v[60:63]
	v_mfma_f32_16x16x32_bf16 v[56:59], v[164:167], v[172:175], v[56:59]
	v_mfma_f32_16x16x32_bf16 v[44:47], v[156:159], v[180:183], v[44:47]
	v_mfma_f32_16x16x32_bf16 v[40:43], v[164:167], v[180:183], v[40:43]
	v_mfma_f32_16x16x32_bf16 v[28:31], v[156:159], v[188:191], v[28:31]
	v_mfma_f32_16x16x32_bf16 v[24:27], v[164:167], v[188:191], v[24:27]
	s_waitcnt lgkmcnt(0)
	v_mfma_f32_16x16x32_bf16 v[12:15], v[156:159], v[198:201], v[12:15]
	v_mfma_f32_16x16x32_bf16 v[8:11], v[164:167], v[198:201], v[8:11]
	s_setprio 0
	s_barrier
	s_add_u32 s12, s12, 0x80080
	s_addc_u32 s13, s13, 0
	s_add_i32 s3, s14, s22
	v_lshl_add_u64 v[144:145], s[12:13], 0, v[132:133]
	s_mov_b32 m0, s3
	s_nop 0
	global_load_lds_dwordx4 v[144:145], off
	v_lshl_add_u64 v[144:145], s[12:13], 0, v[128:129]
	s_add_i32 m0, s3, 0x2000
	s_nop 0
	global_load_lds_dwordx4 v[144:145], off
	s_waitcnt vmcnt(6)
	s_barrier
	s_setprio 1
	v_mfma_f32_16x16x32_bf16 v[52:55], v[202:205], v[168:171], v[52:55]
	v_mfma_f32_16x16x32_bf16 v[48:51], v[210:213], v[168:171], v[48:51]
	v_mfma_f32_16x16x32_bf16 v[36:39], v[202:205], v[176:179], v[36:39]
	v_mfma_f32_16x16x32_bf16 v[32:35], v[210:213], v[176:179], v[32:35]
	v_mfma_f32_16x16x32_bf16 v[20:23], v[202:205], v[184:187], v[20:23]
	v_mfma_f32_16x16x32_bf16 v[16:19], v[210:213], v[184:187], v[16:19]
	v_mfma_f32_16x16x32_bf16 v[4:7], v[202:205], v[192:195], v[4:7]
	v_mfma_f32_16x16x32_bf16 v[0:3], v[210:213], v[192:195], v[0:3]
	v_mfma_f32_16x16x32_bf16 v[52:55], v[206:209], v[172:175], v[52:55]
	v_mfma_f32_16x16x32_bf16 v[48:51], v[214:217], v[172:175], v[48:51]
	v_mfma_f32_16x16x32_bf16 v[36:39], v[206:209], v[180:183], v[36:39]
	v_mfma_f32_16x16x32_bf16 v[32:35], v[214:217], v[180:183], v[32:35]
	v_mfma_f32_16x16x32_bf16 v[20:23], v[206:209], v[188:191], v[20:23]
	v_mfma_f32_16x16x32_bf16 v[16:19], v[214:217], v[188:191], v[16:19]
	v_mfma_f32_16x16x32_bf16 v[4:7], v[206:209], v[198:201], v[4:7]
	v_mfma_f32_16x16x32_bf16 v[0:3], v[214:217], v[198:201], v[0:3]
	s_setprio 0
	s_add_i32 s48, s48, 2
	s_add_u32 s39, s39, 0x100
	s_addc_u32 s47, s47, 0
	s_add_u32 s10, s10, 0x100
	s_addc_u32 s11, s11, 0
	s_cmp_gt_u32 s48, 29
	s_barrier
	s_cbranch_scc0 .LBB1_925
	v_mov_b32_e32 v152, v147
	v_mov_b32_e32 v144, v146
	s_lshl_b32 s2, s2, 8
	s_or_b32 s2, s2, s29
	v_lshl_add_u32 v144, v144, 3, s2
	s_lshl_b32 s2, s8, 8
	s_add_i32 s2, s2, s28
	v_add_u32_e32 v152, s2, v152
	v_ashrrev_i32_e32 v153, 31, v152
	v_lshlrev_b64 v[152:153], 12, v[152:153]
	v_ashrrev_i32_e32 v145, 31, v144
	v_lshl_add_u64 v[152:153], s[42:43], 0, v[152:153]
	v_lshl_add_u64 v[144:145], v[144:145], 1, v[152:153]
	global_load_dwordx4 v[160:163], v[144:145], off
	global_load_dwordx4 v[164:167], v[144:145], off offset:256
	s_mov_b64 s[98:99], 0x10000
	v_lshl_add_u64 v[154:155], v[144:145], 0, s[98:99]
	global_load_dwordx4 v[168:171], v[154:155], off
	global_load_dwordx4 v[172:175], v[154:155], off offset:256
	s_mov_b64 s[98:99], 0x20000
	v_lshl_add_u64 v[154:155], v[144:145], 0, s[98:99]
	global_load_dwordx4 v[176:179], v[154:155], off
	global_load_dwordx4 v[180:183], v[154:155], off offset:256
	s_mov_b64 s[98:99], 0x30000
	v_lshl_add_u64 v[154:155], v[144:145], 0, s[98:99]
	global_load_dwordx4 v[184:187], v[154:155], off
	global_load_dwordx4 v[188:191], v[154:155], off offset:256
	s_mov_b64 s[98:99], 0x80000
	v_lshl_add_u64 v[154:155], v[144:145], 0, s[98:99]
	global_load_dwordx4 v[192:195], v[154:155], off
	global_load_dwordx4 v[198:201], v[154:155], off offset:256
	s_mov_b64 s[98:99], 0x90000
	v_lshl_add_u64 v[154:155], v[144:145], 0, s[98:99]
	global_load_dwordx4 v[202:205], v[154:155], off
	global_load_dwordx4 v[206:209], v[154:155], off offset:256
	s_mov_b64 s[98:99], 0xa0000
	v_lshl_add_u64 v[154:155], v[144:145], 0, s[98:99]
	global_load_dwordx4 v[210:213], v[154:155], off
	global_load_dwordx4 v[214:217], v[154:155], off offset:256
	s_mov_b64 s[98:99], 0xb0000
	v_lshl_add_u64 v[154:155], v[144:145], 0, s[98:99]
	global_load_dwordx4 v[248:251], v[154:155], off
	global_load_dwordx4 v[252:255], v[154:155], off offset:256
	s_waitcnt vmcnt(15)
	s_nop 1
	v_mov_b32_e32 v152, v160
	v_mov_b32_e32 v153, v161
	v_mov_b32_e32 v154, v162
	v_mov_b32_e32 v155, v163
	s_mov_b64 s[2:3], 0x10000
	s_mov_b32 s8, s52
	s_mov_b64 s[10:11], s[6:7]
	s_mov_b64 s[12:13], s[54:55]
	s_waitcnt lgkmcnt(0)
; DI unsigned pack2(float a, float b) { f32x2 v = {a, b}; hwbf16x2 r = __builtin_convertvector(v, hwbf16x2); return __builtin_bit_cast(unsigned, r); }
; DI float bflo(unsigned w) { return __uint_as_float(w << 16); }
; DI float bfhi(unsigned w) { return __uint_as_float(w & 0xffff0000u); }
;     DI void operator()(const f32x4 (&acc)[2][2][4][2], const Unit& u, int wr, int wc, int fr, int fq) const {
;     ...
;             for (int m = 0; m < 4; ++m) { const size_t ro = (size_t)(row0 + ai * HALF + m * 16) * D + col0;
; #pragma unroll
;                 for (int bj = 0; bj < 2; ++bj) {
;                     f32x4 x0, x1;
;                     if constexpr (IB) { const u32x4 w = *(const u32x4*)((const bf16_t*)Xin + ro + bj * HALF);
;                         x0 = (f32x4){bflo(w[0]), bfhi(w[0]), bflo(w[1]), bfhi(w[1])}; x1 = (f32x4){bflo(w[2]), bfhi(w[2]), bflo(w[3]), bfhi(w[3])}; }
;                     else { x0 = *(const f32x4*)((const float*)Xin + ro + bj * HALF); x1 = *(const f32x4*)((const float*)Xin + ro + bj * HALF + 4); }
;                     x0 += acc[ai][bj][m][0] * sc[bj][0]; x1 += acc[ai][bj][m][1] * sc[bj][1];
;                     if constexpr (OB) { u32x4 o; o[0] = pack2(x0[0], x0[1]); o[1] = pack2(x0[2], x0[3]); o[2] = pack2(x1[0], x1[1]); o[3] = pack2(x1[2], x1[3]);
;                         *(u32x4*)((bf16_t*)Xout + ro + bj * HALF) = o; }
	v_lshlrev_b32_e32 v156, 16, v152
	v_and_b32_e32 v157, 0xffff0000, v152
	v_lshlrev_b32_e32 v152, 16, v153
	v_and_b32_e32 v153, 0xffff0000, v153
	v_lshlrev_b32_e32 v158, 16, v154
	v_and_b32_e32 v159, 0xffff0000, v154
	v_lshlrev_b32_e32 v154, 16, v155
	v_and_b32_e32 v155, 0xffff0000, v155
	v_pk_add_f32 v[126:127], v[126:127], v[152:153]
	v_pk_add_f32 v[124:125], v[124:125], v[156:157]
	v_pk_add_f32 v[152:153], v[122:123], v[154:155]
	v_pk_add_f32 v[122:123], v[120:121], v[158:159]
	v_cvt_pk_bf16_f32 v120, v124, v125
	v_cvt_pk_bf16_f32 v121, v126, v127
	v_cvt_pk_bf16_f32 v122, v122, v123
	v_cvt_pk_bf16_f32 v123, v152, v153
	global_store_dwordx4 v[144:145], v[120:123], off
	s_waitcnt vmcnt(15)
	s_nop 1
	v_mov_b32_e32 v120, v164
	v_mov_b32_e32 v121, v165
	v_mov_b32_e32 v122, v166
	v_mov_b32_e32 v123, v167
	s_waitcnt lgkmcnt(0)
	v_lshlrev_b32_e32 v124, 16, v120
	v_and_b32_e32 v125, 0xffff0000, v120
	v_lshlrev_b32_e32 v120, 16, v121
	v_and_b32_e32 v121, 0xffff0000, v121
	v_lshlrev_b32_e32 v126, 16, v122
	v_and_b32_e32 v127, 0xffff0000, v122
	v_lshlrev_b32_e32 v122, 16, v123
	v_and_b32_e32 v123, 0xffff0000, v123
	v_pk_add_f32 v[116:117], v[116:117], v[124:125]
	v_pk_add_f32 v[118:119], v[118:119], v[120:121]
	v_pk_add_f32 v[120:121], v[114:115], v[122:123]
	v_pk_add_f32 v[114:115], v[112:113], v[126:127]
	v_cvt_pk_bf16_f32 v112, v116, v117
	v_lshl_add_u64 v[116:117], v[144:145], 0, s[2:3]
	s_mov_b32 s2, 0x10000
	v_cvt_pk_bf16_f32 v113, v118, v119
	v_add_co_u32_e32 v118, vcc, s2, v144
	v_cvt_pk_bf16_f32 v114, v114, v115
	v_cvt_pk_bf16_f32 v115, v120, v121
	v_addc_co_u32_e32 v119, vcc, 0, v145, vcc
	global_store_dwordx4 v[144:145], v[112:115], off offset:256
	s_waitcnt vmcnt(15)
	s_nop 1
	v_mov_b32_e32 v112, v168
	v_mov_b32_e32 v113, v169
	v_mov_b32_e32 v114, v170
	v_mov_b32_e32 v115, v171
	s_mov_b64 s[2:3], 0x20000
	s_waitcnt lgkmcnt(0)
	v_lshlrev_b32_e32 v120, 16, v112
	v_and_b32_e32 v121, 0xffff0000, v112
	v_lshlrev_b32_e32 v112, 16, v113
	v_and_b32_e32 v113, 0xffff0000, v113
	v_lshlrev_b32_e32 v122, 16, v114
	v_and_b32_e32 v123, 0xffff0000, v114
	v_lshlrev_b32_e32 v114, 16, v115
	v_and_b32_e32 v115, 0xffff0000, v115
	v_pk_add_f32 v[110:111], v[110:111], v[112:113]
	v_pk_add_f32 v[108:109], v[108:109], v[120:121]
	v_pk_add_f32 v[112:113], v[106:107], v[114:115]
	v_pk_add_f32 v[106:107], v[104:105], v[122:123]
	v_cvt_pk_bf16_f32 v104, v108, v109
	v_cvt_pk_bf16_f32 v105, v110, v111
	v_cvt_pk_bf16_f32 v106, v106, v107
	v_cvt_pk_bf16_f32 v107, v112, v113
	global_store_dwordx4 v[118:119], v[104:107], off
	s_waitcnt vmcnt(15)
	s_nop 1
	v_mov_b32_e32 v104, v172
	v_mov_b32_e32 v105, v173
	v_mov_b32_e32 v106, v174
	v_mov_b32_e32 v107, v175
	s_waitcnt lgkmcnt(0)
	v_lshlrev_b32_e32 v108, 16, v104
	v_and_b32_e32 v109, 0xffff0000, v104
	v_lshlrev_b32_e32 v104, 16, v105
	v_and_b32_e32 v105, 0xffff0000, v105
	v_lshlrev_b32_e32 v110, 16, v106
	v_and_b32_e32 v111, 0xffff0000, v106
	v_lshlrev_b32_e32 v106, 16, v107
	v_and_b32_e32 v107, 0xffff0000, v107
	v_pk_add_f32 v[100:101], v[100:101], v[108:109]
	v_pk_add_f32 v[102:103], v[102:103], v[104:105]
	v_pk_add_f32 v[104:105], v[98:99], v[106:107]
	v_pk_add_f32 v[98:99], v[96:97], v[110:111]
	v_cvt_pk_bf16_f32 v96, v100, v101
	v_lshl_add_u64 v[100:101], v[144:145], 0, s[2:3]
	s_mov_b32 s2, 0x20000
	v_cvt_pk_bf16_f32 v97, v102, v103
	v_add_co_u32_e32 v102, vcc, s2, v144
	v_cvt_pk_bf16_f32 v98, v98, v99
	v_cvt_pk_bf16_f32 v99, v104, v105
	v_addc_co_u32_e32 v103, vcc, 0, v145, vcc
	global_store_dwordx4 v[116:117], v[96:99], off offset:256
	s_waitcnt vmcnt(15)
	s_nop 1
	v_mov_b32_e32 v96, v176
	v_mov_b32_e32 v97, v177
	v_mov_b32_e32 v98, v178
	v_mov_b32_e32 v99, v179
	s_mov_b64 s[2:3], 0x30000
	s_waitcnt lgkmcnt(0)
	v_lshlrev_b32_e32 v104, 16, v96
	v_and_b32_e32 v105, 0xffff0000, v96
	v_lshlrev_b32_e32 v96, 16, v97
	v_and_b32_e32 v97, 0xffff0000, v97
	v_lshlrev_b32_e32 v106, 16, v98
	v_and_b32_e32 v107, 0xffff0000, v98
	v_lshlrev_b32_e32 v98, 16, v99
	v_and_b32_e32 v99, 0xffff0000, v99
	v_pk_add_f32 v[94:95], v[94:95], v[96:97]
	v_pk_add_f32 v[92:93], v[92:93], v[104:105]
	v_pk_add_f32 v[96:97], v[90:91], v[98:99]
	v_pk_add_f32 v[90:91], v[88:89], v[106:107]
	v_cvt_pk_bf16_f32 v88, v92, v93
	v_cvt_pk_bf16_f32 v89, v94, v95
	v_cvt_pk_bf16_f32 v90, v90, v91
	v_cvt_pk_bf16_f32 v91, v96, v97
	global_store_dwordx4 v[102:103], v[88:91], off
	s_waitcnt vmcnt(15)
	s_nop 1
	v_mov_b32_e32 v88, v180
	v_mov_b32_e32 v89, v181
	v_mov_b32_e32 v90, v182
	v_mov_b32_e32 v91, v183
	s_waitcnt lgkmcnt(0)
	v_lshlrev_b32_e32 v92, 16, v88
	v_and_b32_e32 v93, 0xffff0000, v88
	v_lshlrev_b32_e32 v88, 16, v89
	v_and_b32_e32 v89, 0xffff0000, v89
	v_lshlrev_b32_e32 v94, 16, v90
	v_and_b32_e32 v95, 0xffff0000, v90
	v_lshlrev_b32_e32 v90, 16, v91
	v_and_b32_e32 v91, 0xffff0000, v91
	v_pk_add_f32 v[86:87], v[86:87], v[88:89]
	v_pk_add_f32 v[84:85], v[84:85], v[92:93]
	v_pk_add_f32 v[88:89], v[82:83], v[90:91]
	v_pk_add_f32 v[82:83], v[80:81], v[94:95]
	v_cvt_pk_bf16_f32 v80, v84, v85
	v_cvt_pk_bf16_f32 v81, v86, v87
	v_cvt_pk_bf16_f32 v82, v82, v83
	v_cvt_pk_bf16_f32 v83, v88, v89
	global_store_dwordx4 v[100:101], v[80:83], off offset:256
	s_nop 1
	v_lshl_add_u64 v[80:81], v[144:145], 0, s[2:3]
	s_mov_b32 s2, 0x30000
	v_add_co_u32_e32 v86, vcc, s2, v144
	s_mov_b64 s[2:3], 0x80000
	s_nop 0
	v_addc_co_u32_e32 v87, vcc, 0, v145, vcc
	s_waitcnt vmcnt(15)
	s_nop 1
	v_mov_b32_e32 v82, v184
	v_mov_b32_e32 v83, v185
	v_mov_b32_e32 v84, v186
	v_mov_b32_e32 v85, v187
	s_waitcnt lgkmcnt(0)
; DI unsigned pack2(float a, float b) { f32x2 v = {a, b}; hwbf16x2 r = __builtin_convertvector(v, hwbf16x2); return __builtin_bit_cast(unsigned, r); }
; DI float bflo(unsigned w) { return __uint_as_float(w << 16); }
; DI float bfhi(unsigned w) { return __uint_as_float(w & 0xffff0000u); }
;     DI void operator()(const f32x4 (&acc)[2][2][4][2], const Unit& u, int wr, int wc, int fr, int fq) const {
;     ...
;             for (int m = 0; m < 4; ++m) { const size_t ro = (size_t)(row0 + ai * HALF + m * 16) * D + col0;
; #pragma unroll
;                 for (int bj = 0; bj < 2; ++bj) {
;                     f32x4 x0, x1;
;                     if constexpr (IB) { const u32x4 w = *(const u32x4*)((const bf16_t*)Xin + ro + bj * HALF);
;                         x0 = (f32x4){bflo(w[0]), bfhi(w[0]), bflo(w[1]), bfhi(w[1])}; x1 = (f32x4){bflo(w[2]), bfhi(w[2]), bflo(w[3]), bfhi(w[3])}; }
;                     else { x0 = *(const f32x4*)((const float*)Xin + ro + bj * HALF); x1 = *(const f32x4*)((const float*)Xin + ro + bj * HALF + 4); }
;                     x0 += acc[ai][bj][m][0] * sc[bj][0]; x1 += acc[ai][bj][m][1] * sc[bj][1];
;                     if constexpr (OB) { u32x4 o; o[0] = pack2(x0[0], x0[1]); o[1] = pack2(x0[2], x0[3]); o[2] = pack2(x1[0], x1[1]); o[3] = pack2(x1[2], x1[3]);
;                         *(u32x4*)((bf16_t*)Xout + ro + bj * HALF) = o; }
	v_lshlrev_b32_e32 v88, 16, v82
	v_and_b32_e32 v89, 0xffff0000, v82
	v_lshlrev_b32_e32 v82, 16, v83
	v_and_b32_e32 v83, 0xffff0000, v83
	v_lshlrev_b32_e32 v90, 16, v84
	v_and_b32_e32 v91, 0xffff0000, v84
	v_lshlrev_b32_e32 v84, 16, v85
	v_and_b32_e32 v85, 0xffff0000, v85
	v_pk_add_f32 v[78:79], v[78:79], v[82:83]
	v_pk_add_f32 v[76:77], v[76:77], v[88:89]
	v_pk_add_f32 v[82:83], v[74:75], v[84:85]
	v_pk_add_f32 v[74:75], v[72:73], v[90:91]
	v_cvt_pk_bf16_f32 v72, v76, v77
	v_cvt_pk_bf16_f32 v73, v78, v79
	v_cvt_pk_bf16_f32 v74, v74, v75
	v_cvt_pk_bf16_f32 v75, v82, v83
	global_store_dwordx4 v[86:87], v[72:75], off
	s_waitcnt vmcnt(15)
	s_nop 1
	v_mov_b32_e32 v72, v188
	v_mov_b32_e32 v73, v189
	v_mov_b32_e32 v74, v190
	v_mov_b32_e32 v75, v191
	s_waitcnt lgkmcnt(0)
	v_lshlrev_b32_e32 v76, 16, v72
	v_and_b32_e32 v77, 0xffff0000, v72
	v_lshlrev_b32_e32 v72, 16, v73
	v_and_b32_e32 v73, 0xffff0000, v73
	v_lshlrev_b32_e32 v78, 16, v74
	v_and_b32_e32 v79, 0xffff0000, v74
	v_lshlrev_b32_e32 v74, 16, v75
	v_and_b32_e32 v75, 0xffff0000, v75
	v_pk_add_f32 v[70:71], v[70:71], v[72:73]
	v_pk_add_f32 v[68:69], v[68:69], v[76:77]
	v_pk_add_f32 v[72:73], v[66:67], v[74:75]
	v_pk_add_f32 v[66:67], v[64:65], v[78:79]
	v_cvt_pk_bf16_f32 v64, v68, v69
	v_cvt_pk_bf16_f32 v65, v70, v71
	v_cvt_pk_bf16_f32 v66, v66, v67
	v_cvt_pk_bf16_f32 v67, v72, v73
	global_store_dwordx4 v[80:81], v[64:67], off offset:256
	s_nop 1
	v_lshl_add_u64 v[64:65], v[144:145], 0, s[2:3]
	s_mov_b32 s2, 0x80000
	v_add_co_u32_e32 v70, vcc, s2, v144
	s_mov_b64 s[2:3], 0x90000
	s_nop 0
	v_addc_co_u32_e32 v71, vcc, 0, v145, vcc
	s_waitcnt vmcnt(15)
	s_nop 1
	v_mov_b32_e32 v66, v192
	v_mov_b32_e32 v67, v193
	v_mov_b32_e32 v68, v194
	v_mov_b32_e32 v69, v195
	s_waitcnt lgkmcnt(0)
	v_lshlrev_b32_e32 v72, 16, v66
	v_and_b32_e32 v73, 0xffff0000, v66
	v_lshlrev_b32_e32 v66, 16, v67
	v_and_b32_e32 v67, 0xffff0000, v67
	v_lshlrev_b32_e32 v74, 16, v68
	v_and_b32_e32 v75, 0xffff0000, v68
	v_lshlrev_b32_e32 v68, 16, v69
	v_and_b32_e32 v69, 0xffff0000, v69
	v_pk_add_f32 v[62:63], v[62:63], v[66:67]
	v_pk_add_f32 v[60:61], v[60:61], v[72:73]
	v_pk_add_f32 v[66:67], v[58:59], v[68:69]
	v_pk_add_f32 v[58:59], v[56:57], v[74:75]
	v_cvt_pk_bf16_f32 v56, v60, v61
	v_cvt_pk_bf16_f32 v57, v62, v63
	v_cvt_pk_bf16_f32 v58, v58, v59
	v_cvt_pk_bf16_f32 v59, v66, v67
	global_store_dwordx4 v[70:71], v[56:59], off
	s_waitcnt vmcnt(15)
	s_nop 1
	v_mov_b32_e32 v56, v198
	v_mov_b32_e32 v57, v199
	v_mov_b32_e32 v58, v200
	v_mov_b32_e32 v59, v201
	s_waitcnt lgkmcnt(0)
	v_lshlrev_b32_e32 v60, 16, v56
	v_and_b32_e32 v61, 0xffff0000, v56
	v_lshlrev_b32_e32 v56, 16, v57
	v_and_b32_e32 v57, 0xffff0000, v57
	v_lshlrev_b32_e32 v62, 16, v58
	v_and_b32_e32 v63, 0xffff0000, v58
	v_lshlrev_b32_e32 v58, 16, v59
	v_and_b32_e32 v59, 0xffff0000, v59
	v_pk_add_f32 v[54:55], v[54:55], v[56:57]
	v_pk_add_f32 v[52:53], v[52:53], v[60:61]
	v_pk_add_f32 v[56:57], v[50:51], v[58:59]
	v_pk_add_f32 v[50:51], v[48:49], v[62:63]
	v_cvt_pk_bf16_f32 v48, v52, v53
	v_cvt_pk_bf16_f32 v49, v54, v55
	v_cvt_pk_bf16_f32 v50, v50, v51
	v_cvt_pk_bf16_f32 v51, v56, v57
	global_store_dwordx4 v[64:65], v[48:51], off offset:256
	s_nop 1
	v_lshl_add_u64 v[48:49], v[144:145], 0, s[2:3]
	s_mov_b32 s2, 0x90000
	v_add_co_u32_e32 v54, vcc, s2, v144
	s_mov_b64 s[2:3], 0xa0000
	s_nop 0
	v_addc_co_u32_e32 v55, vcc, 0, v145, vcc
	s_waitcnt vmcnt(15)
	s_nop 1
	v_mov_b32_e32 v50, v202
	v_mov_b32_e32 v51, v203
	v_mov_b32_e32 v52, v204
	v_mov_b32_e32 v53, v205
	s_waitcnt lgkmcnt(0)
	v_lshlrev_b32_e32 v56, 16, v50
	v_and_b32_e32 v57, 0xffff0000, v50
	v_lshlrev_b32_e32 v50, 16, v51
	v_and_b32_e32 v51, 0xffff0000, v51
	v_lshlrev_b32_e32 v58, 16, v52
	v_and_b32_e32 v59, 0xffff0000, v52
	v_lshlrev_b32_e32 v52, 16, v53
	v_and_b32_e32 v53, 0xffff0000, v53
	v_pk_add_f32 v[46:47], v[46:47], v[50:51]
	v_pk_add_f32 v[44:45], v[44:45], v[56:57]
	v_pk_add_f32 v[50:51], v[42:43], v[52:53]
	v_pk_add_f32 v[42:43], v[40:41], v[58:59]
	v_cvt_pk_bf16_f32 v40, v44, v45
	v_cvt_pk_bf16_f32 v41, v46, v47
	v_cvt_pk_bf16_f32 v42, v42, v43
	v_cvt_pk_bf16_f32 v43, v50, v51
	global_store_dwordx4 v[54:55], v[40:43], off
	s_waitcnt vmcnt(15)
	s_nop 1
	v_mov_b32_e32 v40, v206
	v_mov_b32_e32 v41, v207
	v_mov_b32_e32 v42, v208
	v_mov_b32_e32 v43, v209
	s_waitcnt lgkmcnt(0)
; DI unsigned pack2(float a, float b) { f32x2 v = {a, b}; hwbf16x2 r = __builtin_convertvector(v, hwbf16x2); return __builtin_bit_cast(unsigned, r); }
; DI float bflo(unsigned w) { return __uint_as_float(w << 16); }
; DI float bfhi(unsigned w) { return __uint_as_float(w & 0xffff0000u); }
;     DI void operator()(const f32x4 (&acc)[2][2][4][2], const Unit& u, int wr, int wc, int fr, int fq) const {
;     ...
;             for (int m = 0; m < 4; ++m) { const size_t ro = (size_t)(row0 + ai * HALF + m * 16) * D + col0;
; #pragma unroll
;                 for (int bj = 0; bj < 2; ++bj) {
;                     f32x4 x0, x1;
;                     if constexpr (IB) { const u32x4 w = *(const u32x4*)((const bf16_t*)Xin + ro + bj * HALF);
;                         x0 = (f32x4){bflo(w[0]), bfhi(w[0]), bflo(w[1]), bfhi(w[1])}; x1 = (f32x4){bflo(w[2]), bfhi(w[2]), bflo(w[3]), bfhi(w[3])}; }
;                     else { x0 = *(const f32x4*)((const float*)Xin + ro + bj * HALF); x1 = *(const f32x4*)((const float*)Xin + ro + bj * HALF + 4); }
;                     x0 += acc[ai][bj][m][0] * sc[bj][0]; x1 += acc[ai][bj][m][1] * sc[bj][1];
;                     if constexpr (OB) { u32x4 o; o[0] = pack2(x0[0], x0[1]); o[1] = pack2(x0[2], x0[3]); o[2] = pack2(x1[0], x1[1]); o[3] = pack2(x1[2], x1[3]);
;                         *(u32x4*)((bf16_t*)Xout + ro + bj * HALF) = o; }
	v_lshlrev_b32_e32 v44, 16, v40
	v_and_b32_e32 v45, 0xffff0000, v40
	v_lshlrev_b32_e32 v40, 16, v41
	v_and_b32_e32 v41, 0xffff0000, v41
	v_lshlrev_b32_e32 v46, 16, v42
	v_and_b32_e32 v47, 0xffff0000, v42
	v_lshlrev_b32_e32 v42, 16, v43
	v_and_b32_e32 v43, 0xffff0000, v43
	v_pk_add_f32 v[38:39], v[38:39], v[40:41]
	v_pk_add_f32 v[36:37], v[36:37], v[44:45]
	v_pk_add_f32 v[40:41], v[34:35], v[42:43]
	v_pk_add_f32 v[34:35], v[32:33], v[46:47]
	v_cvt_pk_bf16_f32 v32, v36, v37
	v_cvt_pk_bf16_f32 v33, v38, v39
	v_cvt_pk_bf16_f32 v34, v34, v35
	v_cvt_pk_bf16_f32 v35, v40, v41
	global_store_dwordx4 v[48:49], v[32:35], off offset:256
	s_nop 1
	v_lshl_add_u64 v[32:33], v[144:145], 0, s[2:3]
	s_mov_b32 s2, 0xa0000
	v_add_co_u32_e32 v38, vcc, s2, v144
	s_mov_b64 s[2:3], 0xb0000
	s_nop 0
	v_addc_co_u32_e32 v39, vcc, 0, v145, vcc
	s_waitcnt vmcnt(15)
	s_nop 1
	v_mov_b32_e32 v34, v210
	v_mov_b32_e32 v35, v211
	v_mov_b32_e32 v36, v212
	v_mov_b32_e32 v37, v213
	s_waitcnt lgkmcnt(0)
	v_lshlrev_b32_e32 v40, 16, v34
	v_and_b32_e32 v41, 0xffff0000, v34
	v_lshlrev_b32_e32 v34, 16, v35
	v_and_b32_e32 v35, 0xffff0000, v35
	v_lshlrev_b32_e32 v42, 16, v36
	v_and_b32_e32 v43, 0xffff0000, v36
	v_lshlrev_b32_e32 v36, 16, v37
	v_and_b32_e32 v37, 0xffff0000, v37
	v_pk_add_f32 v[30:31], v[30:31], v[34:35]
	v_pk_add_f32 v[28:29], v[28:29], v[40:41]
	v_pk_add_f32 v[34:35], v[26:27], v[36:37]
	v_pk_add_f32 v[26:27], v[24:25], v[42:43]
	v_cvt_pk_bf16_f32 v24, v28, v29
	v_cvt_pk_bf16_f32 v25, v30, v31
	v_cvt_pk_bf16_f32 v26, v26, v27
	v_cvt_pk_bf16_f32 v27, v34, v35
	global_store_dwordx4 v[38:39], v[24:27], off
	s_waitcnt vmcnt(15)
	s_nop 1
	v_mov_b32_e32 v24, v214
	v_mov_b32_e32 v25, v215
	v_mov_b32_e32 v26, v216
	v_mov_b32_e32 v27, v217
	s_waitcnt lgkmcnt(0)
	v_lshlrev_b32_e32 v28, 16, v24
	v_and_b32_e32 v29, 0xffff0000, v24
	v_lshlrev_b32_e32 v24, 16, v25
	v_and_b32_e32 v25, 0xffff0000, v25
	v_lshlrev_b32_e32 v30, 16, v26
	v_and_b32_e32 v31, 0xffff0000, v26
	v_lshlrev_b32_e32 v26, 16, v27
	v_and_b32_e32 v27, 0xffff0000, v27
	v_pk_add_f32 v[22:23], v[22:23], v[24:25]
	v_pk_add_f32 v[20:21], v[20:21], v[28:29]
	v_pk_add_f32 v[24:25], v[18:19], v[26:27]
	v_pk_add_f32 v[18:19], v[16:17], v[30:31]
	v_cvt_pk_bf16_f32 v16, v20, v21
	v_cvt_pk_bf16_f32 v17, v22, v23
	v_cvt_pk_bf16_f32 v18, v18, v19
	v_cvt_pk_bf16_f32 v19, v24, v25
	global_store_dwordx4 v[32:33], v[16:19], off offset:256
	s_nop 1
	v_lshl_add_u64 v[16:17], v[144:145], 0, s[2:3]
	s_mov_b32 s2, 0xb0000
	v_add_co_u32_e32 v22, vcc, s2, v144
	s_mov_b32 s2, s46
	s_nop 0
	v_addc_co_u32_e32 v23, vcc, 0, v145, vcc
	s_waitcnt vmcnt(15)
	s_nop 1
	v_mov_b32_e32 v18, v248
	v_mov_b32_e32 v19, v249
	v_mov_b32_e32 v20, v250
	v_mov_b32_e32 v21, v251
	s_and_b64 vcc, exec, s[40:41]
	s_waitcnt lgkmcnt(0)
	v_lshlrev_b32_e32 v24, 16, v18
	v_and_b32_e32 v25, 0xffff0000, v18
	v_lshlrev_b32_e32 v18, 16, v19
	v_and_b32_e32 v19, 0xffff0000, v19
	v_lshlrev_b32_e32 v26, 16, v20
	v_and_b32_e32 v27, 0xffff0000, v20
	v_lshlrev_b32_e32 v20, 16, v21
	v_and_b32_e32 v21, 0xffff0000, v21
	v_pk_add_f32 v[14:15], v[14:15], v[18:19]
	v_pk_add_f32 v[12:13], v[12:13], v[24:25]
	v_pk_add_f32 v[18:19], v[10:11], v[20:21]
	v_pk_add_f32 v[10:11], v[8:9], v[26:27]
	v_cvt_pk_bf16_f32 v8, v12, v13
	v_cvt_pk_bf16_f32 v9, v14, v15
	v_cvt_pk_bf16_f32 v10, v10, v11
	v_cvt_pk_bf16_f32 v11, v18, v19
	global_store_dwordx4 v[22:23], v[8:11], off
	s_waitcnt vmcnt(15)
	s_nop 1
	v_mov_b32_e32 v8, v252
	v_mov_b32_e32 v9, v253
	v_mov_b32_e32 v10, v254
	v_mov_b32_e32 v11, v255
	s_waitcnt lgkmcnt(0)
	v_lshlrev_b32_e32 v12, 16, v8
	v_and_b32_e32 v13, 0xffff0000, v8
	v_lshlrev_b32_e32 v8, 16, v9
	v_and_b32_e32 v9, 0xffff0000, v9
	v_lshlrev_b32_e32 v14, 16, v10
	v_and_b32_e32 v15, 0xffff0000, v10
	v_lshlrev_b32_e32 v10, 16, v11
	v_and_b32_e32 v11, 0xffff0000, v11
	v_pk_add_f32 v[6:7], v[6:7], v[8:9]
	v_pk_add_f32 v[4:5], v[4:5], v[12:13]
	v_pk_add_f32 v[8:9], v[2:3], v[10:11]
	v_pk_add_f32 v[2:3], v[0:1], v[14:15]
	v_cvt_pk_bf16_f32 v0, v4, v5
	v_cvt_pk_bf16_f32 v1, v6, v7
	v_cvt_pk_bf16_f32 v2, v2, v3
	v_cvt_pk_bf16_f32 v3, v8, v9
	global_store_dwordx4 v[16:17], v[0:3], off offset:256
	s_cbranch_vccz .LBB1_922
	s_waitcnt vmcnt(0)
	s_cmpk_gt_u32 s17, 0xff
	s_cbranch_scc1 .LBB1_929
	s_barrier

; #define PG8_STAGE(bufoff, gbase, voff) do { _Pragma("unroll") for (int _i = 0; _i < 2; ++_i) \
;         __builtin_amdgcn_global_load_lds((const unsigned*)((const char*)(gbase) + (voff)[_i]), (LAS unsigned*)(lds + (bufoff) + ldsw + _i * 8192), 16, 0, 0); } while (0)
; #define PG8_LDA(dst, b, h) do { _Pragma("unroll") for (int m = 0; m < 4; ++m) _Pragma("unroll") for (int k = 0; k < 2; ++k) dst[m][k] = *(const LAS bf16x8*)(lds + PG8_SA(b, h) + aoff + m * 2048 + k * 1024); } while (0)
; #define PG8_LDB(dst, b, h) do { _Pragma("unroll") for (int n = 0; n < 2; ++n) _Pragma("unroll") for (int k = 0; k < 2; ++k) dst[n][k] = *(const LAS bf16x8*)(lds + PG8_SB(b, h) + boff + n * 2048 + k * 1024); } while (0)
; #define PG8_MMA(ai, bj, At, Bt) do { __builtin_amdgcn_s_setprio(1); _Pragma("unroll") for (int m = 0; m < 4; ++m) _Pragma("unroll") for (int n = 0; n < 2; ++n) _Pragma("unroll") for (int k = 0; k < 2; ++k) \
;         acc[ai][bj][m][n] = __builtin_amdgcn_mfma_f32_16x16x32_bf16(Bt[n][k], At[m][k], acc[ai][bj][m][n], 0, 0, 0); __builtin_amdgcn_s_setprio(0); } while (0)
; #define PG8_WAIT_L(n) asm volatile("s_waitcnt lgkmcnt(" #n ")" ::: "memory")
; #define PG8_BAR __builtin_amdgcn_s_barrier()
; #define PG8_SCHED __builtin_amdgcn_sched_barrier(0)
; template <class Map, class Epi>
; DI void gemm_phase(LAS unsigned char* lds, const Map& MP, const Epi& E, const int nM, const int nN, const int K, const int lda, const int ldb) {
;     ...
;             PG8_LDB(B0, 0, 0); PG8_SCHED; PG8_LDA(At, 0, 0); PG8_STAGE(PG8_SA(1, 1), a1 + hstepA, voffA);
;             PG8_WAIT_L(8); PG8_BAR; PG8_WAIT_L(0); PG8_MMA(0, 0, At, B0); PG8_BAR; PG8_SCHED;
;             PG8_LDB(B1, 0, 1); PG8_STAGE(PG8_SB(0, 0), b2, voffB);
;             PG8_BAR; PG8_WAIT_L(0); PG8_MMA(0, 1, At, B1); PG8_BAR;
;             PG8_LDA(At, 0, 1); PG8_STAGE(PG8_SA(0, 0), a2, voffA);
;             PG8_BAR; PG8_WAIT_L(0); PG8_MMA(1, 0, At, B0); PG8_BAR; PG8_SCHED;
.LBB1_1239:
	ds_read_b128 v[152:155], v149
	ds_read_b128 v[156:159], v149 offset:1024
	ds_read_b128 v[160:163], v149 offset:2048
	ds_read_b128 v[164:167], v149 offset:3072
	s_add_u32 s10, s8, 0x100
	s_addc_u32 s11, s9, 0
	s_cmpk_eq_i32 s3, 0x54
	s_cselect_b32 s15, s43, s11
	s_cselect_b32 s14, s42, s10
	s_cselect_b32 s13, s7, s38
	s_cselect_b32 s12, s6, s5
	v_lshl_add_u64 v[144:145], s[8:9], 0, v[138:139]
	s_add_i32 m0, s24, 0xc000
	ds_read_b128 v[168:171], v150
	ds_read_b128 v[172:175], v150 offset:1024
	ds_read_b128 v[176:179], v150 offset:2048
	ds_read_b128 v[180:183], v150 offset:3072
	ds_read_b128 v[184:187], v150 offset:4096
	ds_read_b128 v[188:191], v150 offset:5120
	ds_read_b128 v[192:195], v150 offset:6144
	ds_read_b128 v[198:201], v150 offset:7168
	global_load_lds_dwordx4 v[144:145], off
	v_lshl_add_u64 v[144:145], s[8:9], 0, v[136:137]
	s_add_i32 m0, s24, 0xe000
	s_nop 0
	global_load_lds_dwordx4 v[144:145], off
	s_waitcnt lgkmcnt(8)
	s_barrier
	s_setprio 1
	s_waitcnt lgkmcnt(7)
	v_mfma_f32_16x16x32_bf16 v[124:127], v[152:155], v[168:171], v[124:127]
	v_mfma_f32_16x16x32_bf16 v[120:123], v[160:163], v[168:171], v[120:123]
	s_waitcnt lgkmcnt(5)
	v_mfma_f32_16x16x32_bf16 v[108:111], v[152:155], v[176:179], v[108:111]
	v_mfma_f32_16x16x32_bf16 v[104:107], v[160:163], v[176:179], v[104:107]
	s_waitcnt lgkmcnt(3)
	v_mfma_f32_16x16x32_bf16 v[92:95], v[152:155], v[184:187], v[92:95]
	v_mfma_f32_16x16x32_bf16 v[88:91], v[160:163], v[184:187], v[88:91]
	s_waitcnt lgkmcnt(1)
	v_mfma_f32_16x16x32_bf16 v[76:79], v[152:155], v[192:195], v[76:79]
	v_mfma_f32_16x16x32_bf16 v[72:75], v[160:163], v[192:195], v[72:75]
	v_mfma_f32_16x16x32_bf16 v[124:127], v[156:159], v[172:175], v[124:127]
	v_mfma_f32_16x16x32_bf16 v[120:123], v[164:167], v[172:175], v[120:123]
	v_mfma_f32_16x16x32_bf16 v[108:111], v[156:159], v[180:183], v[108:111]
	v_mfma_f32_16x16x32_bf16 v[104:107], v[164:167], v[180:183], v[104:107]
	v_mfma_f32_16x16x32_bf16 v[92:95], v[156:159], v[188:191], v[92:95]
	v_mfma_f32_16x16x32_bf16 v[88:91], v[164:167], v[188:191], v[88:91]
	s_waitcnt lgkmcnt(0)
	v_mfma_f32_16x16x32_bf16 v[76:79], v[156:159], v[198:201], v[76:79]
	v_mfma_f32_16x16x32_bf16 v[72:75], v[164:167], v[198:201], v[72:75]
	s_setprio 0
	s_barrier
	s_add_i32 s8, s35, s22
	v_lshl_add_u64 v[144:145], s[12:13], 0, v[132:133]
	s_mov_b32 m0, s8
	ds_read_b128 v[202:205], v151
	ds_read_b128 v[206:209], v151 offset:1024
	ds_read_b128 v[210:213], v151 offset:2048
	ds_read_b128 v[214:217], v151 offset:3072
	global_load_lds_dwordx4 v[144:145], off
	v_lshl_add_u64 v[218:219], s[12:13], 0, v[128:129]
	s_add_i32 m0, s8, 0x2000
	s_nop 0
	global_load_lds_dwordx4 v[218:219], off
	s_barrier
	s_setprio 1
	s_waitcnt lgkmcnt(3)
	v_mfma_f32_16x16x32_bf16 v[116:119], v[202:205], v[168:171], v[116:119]
	s_waitcnt lgkmcnt(1)
	v_mfma_f32_16x16x32_bf16 v[112:115], v[210:213], v[168:171], v[112:115]
	v_mfma_f32_16x16x32_bf16 v[100:103], v[202:205], v[176:179], v[100:103]
	v_mfma_f32_16x16x32_bf16 v[96:99], v[210:213], v[176:179], v[96:99]
	v_mfma_f32_16x16x32_bf16 v[84:87], v[202:205], v[184:187], v[84:87]
	v_mfma_f32_16x16x32_bf16 v[80:83], v[210:213], v[184:187], v[80:83]
	v_mfma_f32_16x16x32_bf16 v[68:71], v[202:205], v[192:195], v[68:71]
	v_mfma_f32_16x16x32_bf16 v[64:67], v[210:213], v[192:195], v[64:67]
	v_mfma_f32_16x16x32_bf16 v[116:119], v[206:209], v[172:175], v[116:119]
	s_waitcnt lgkmcnt(0)
	v_mfma_f32_16x16x32_bf16 v[112:115], v[214:217], v[172:175], v[112:115]
	v_mfma_f32_16x16x32_bf16 v[100:103], v[206:209], v[180:183], v[100:103]
	v_mfma_f32_16x16x32_bf16 v[96:99], v[214:217], v[180:183], v[96:99]
	v_mfma_f32_16x16x32_bf16 v[84:87], v[206:209], v[188:191], v[84:87]
	v_mfma_f32_16x16x32_bf16 v[80:83], v[214:217], v[188:191], v[80:83]
	v_mfma_f32_16x16x32_bf16 v[68:71], v[206:209], v[198:201], v[68:71]
	v_mfma_f32_16x16x32_bf16 v[64:67], v[214:217], v[198:201], v[64:67]
	s_setprio 0
	s_mov_b32 m0, s24
	v_lshl_add_u64 v[220:221], s[14:15], 0, v[134:135]
	s_barrier
	ds_read_b128 v[168:171], v150 offset:16384
	ds_read_b128 v[172:175], v150 offset:17408
	ds_read_b128 v[176:179], v150 offset:18432
	ds_read_b128 v[180:183], v150 offset:19456
	ds_read_b128 v[184:187], v150 offset:20480
	ds_read_b128 v[188:191], v150 offset:21504
	ds_read_b128 v[192:195], v150 offset:22528
	ds_read_b128 v[198:201], v150 offset:23552
	global_load_lds_dwordx4 v[220:221], off
	v_lshl_add_u64 v[222:223], s[14:15], 0, v[130:131]
	s_mov_b32 m0, s25
	s_nop 0
	global_load_lds_dwordx4 v[222:223], off
	s_barrier
	s_setprio 1
	s_waitcnt lgkmcnt(7)
	v_mfma_f32_16x16x32_bf16 v[60:63], v[152:155], v[168:171], v[60:63]
	v_mfma_f32_16x16x32_bf16 v[56:59], v[160:163], v[168:171], v[56:59]
	s_waitcnt lgkmcnt(5)
	v_mfma_f32_16x16x32_bf16 v[44:47], v[152:155], v[176:179], v[44:47]
	v_mfma_f32_16x16x32_bf16 v[40:43], v[160:163], v[176:179], v[40:43]
	s_waitcnt lgkmcnt(3)
	v_mfma_f32_16x16x32_bf16 v[28:31], v[152:155], v[184:187], v[28:31]
	v_mfma_f32_16x16x32_bf16 v[24:27], v[160:163], v[184:187], v[24:27]
	s_waitcnt lgkmcnt(1)
	v_mfma_f32_16x16x32_bf16 v[12:15], v[152:155], v[192:195], v[12:15]
	v_mfma_f32_16x16x32_bf16 v[8:11], v[160:163], v[192:195], v[8:11]
	v_mfma_f32_16x16x32_bf16 v[60:63], v[156:159], v[172:175], v[60:63]
	v_mfma_f32_16x16x32_bf16 v[56:59], v[164:167], v[172:175], v[56:59]
	v_mfma_f32_16x16x32_bf16 v[44:47], v[156:159], v[180:183], v[44:47]
	v_mfma_f32_16x16x32_bf16 v[40:43], v[164:167], v[180:183], v[40:43]
	v_mfma_f32_16x16x32_bf16 v[28:31], v[156:159], v[188:191], v[28:31]
	v_mfma_f32_16x16x32_bf16 v[24:27], v[164:167], v[188:191], v[24:27]
	s_waitcnt lgkmcnt(0)
	v_mfma_f32_16x16x32_bf16 v[12:15], v[156:159], v[198:201], v[12:15]
	v_mfma_f32_16x16x32_bf16 v[8:11], v[164:167], v[198:201], v[8:11]
	s_setprio 0
	s_barrier
; #define PG8_STAGE(bufoff, gbase, voff) do { _Pragma("unroll") for (int _i = 0; _i < 2; ++_i) \
;         __builtin_amdgcn_global_load_lds((const unsigned*)((const char*)(gbase) + (voff)[_i]), (LAS unsigned*)(lds + (bufoff) + ldsw + _i * 8192), 16, 0, 0); } while (0)
; #define PG8_LDA(dst, b, h) do { _Pragma("unroll") for (int m = 0; m < 4; ++m) _Pragma("unroll") for (int k = 0; k < 2; ++k) dst[m][k] = *(const LAS bf16x8*)(lds + PG8_SA(b, h) + aoff + m * 2048 + k * 1024); } while (0)
; #define PG8_LDB(dst, b, h) do { _Pragma("unroll") for (int n = 0; n < 2; ++n) _Pragma("unroll") for (int k = 0; k < 2; ++k) dst[n][k] = *(const LAS bf16x8*)(lds + PG8_SB(b, h) + boff + n * 2048 + k * 1024); } while (0)
; #define PG8_MMA(ai, bj, At, Bt) do { __builtin_amdgcn_s_setprio(1); _Pragma("unroll") for (int m = 0; m < 4; ++m) _Pragma("unroll") for (int n = 0; n < 2; ++n) _Pragma("unroll") for (int k = 0; k < 2; ++k) \
;         acc[ai][bj][m][n] = __builtin_amdgcn_mfma_f32_16x16x32_bf16(Bt[n][k], At[m][k], acc[ai][bj][m][n], 0, 0, 0); __builtin_amdgcn_s_setprio(0); } while (0)
; #define PG8_WAIT_V(n) asm volatile("s_waitcnt vmcnt(" #n ")" ::: "memory")
; #define PG8_WAIT_L(n) asm volatile("s_waitcnt lgkmcnt(" #n ")" ::: "memory")
; #define PG8_BAR __builtin_amdgcn_s_barrier()
; #define PG8_SCHED __builtin_amdgcn_sched_barrier(0)
; template <class Map, class Epi>
; DI void gemm_phase(LAS unsigned char* lds, const Map& MP, const Epi& E, const int nM, const int nN, const int K, const int lda, const int ldb) {
;     ...
;             PG8_STAGE(PG8_SB(0, 1), b2 + hstepB, voffB);
;             PG8_WAIT_V(6); PG8_BAR; PG8_MMA(1, 1, At, B1); PG8_BAR;
;             PG8_LDB(B0, 1, 0); PG8_SCHED; PG8_LDA(At, 1, 0); PG8_STAGE(PG8_SA(0, 1), a2 + hstepA, voffA);
;             PG8_WAIT_L(8); PG8_BAR; PG8_WAIT_L(0); PG8_MMA(0, 0, At, B0); PG8_BAR; PG8_SCHED;
;             PG8_LDB(B1, 1, 1); PG8_STAGE(PG8_SB(1, 0), b3, voffB);
;             PG8_BAR; PG8_WAIT_L(0); PG8_MMA(0, 1, At, B1); PG8_BAR;
	s_add_u32 s8, s12, 0x160000
	s_addc_u32 s9, s13, 0
	s_add_i32 s39, s36, s22
	v_lshl_add_u64 v[152:153], s[8:9], 0, v[132:133]
	s_mov_b32 m0, s39
	s_nop 0
	global_load_lds_dwordx4 v[152:153], off
	v_lshl_add_u64 v[152:153], s[8:9], 0, v[128:129]
	s_add_i32 m0, s39, 0x2000
	s_nop 0
	global_load_lds_dwordx4 v[152:153], off
	s_waitcnt vmcnt(6)
	s_barrier
	s_setprio 1
	v_mfma_f32_16x16x32_bf16 v[52:55], v[202:205], v[168:171], v[52:55]
	v_mfma_f32_16x16x32_bf16 v[48:51], v[210:213], v[168:171], v[48:51]
	v_mfma_f32_16x16x32_bf16 v[36:39], v[202:205], v[176:179], v[36:39]
	v_mfma_f32_16x16x32_bf16 v[32:35], v[210:213], v[176:179], v[32:35]
	v_mfma_f32_16x16x32_bf16 v[20:23], v[202:205], v[184:187], v[20:23]
	v_mfma_f32_16x16x32_bf16 v[16:19], v[210:213], v[184:187], v[16:19]
	v_mfma_f32_16x16x32_bf16 v[4:7], v[202:205], v[192:195], v[4:7]
	v_mfma_f32_16x16x32_bf16 v[0:3], v[210:213], v[192:195], v[0:3]
	v_mfma_f32_16x16x32_bf16 v[52:55], v[206:209], v[172:175], v[52:55]
	v_mfma_f32_16x16x32_bf16 v[48:51], v[214:217], v[172:175], v[48:51]
	v_mfma_f32_16x16x32_bf16 v[36:39], v[206:209], v[180:183], v[36:39]
	v_mfma_f32_16x16x32_bf16 v[32:35], v[214:217], v[180:183], v[32:35]
	v_mfma_f32_16x16x32_bf16 v[20:23], v[206:209], v[188:191], v[20:23]
	v_mfma_f32_16x16x32_bf16 v[16:19], v[214:217], v[188:191], v[16:19]
	v_mfma_f32_16x16x32_bf16 v[4:7], v[206:209], v[198:201], v[4:7]
	v_mfma_f32_16x16x32_bf16 v[0:3], v[214:217], v[198:201], v[0:3]
	s_setprio 0
	s_add_i32 s39, 0, 0x18000
	v_add_u32_e32 v164, s39, v148
	s_barrier
	ds_read_b128 v[152:155], v164
	ds_read_b128 v[156:159], v164 offset:1024
	ds_read_b128 v[160:163], v164 offset:2048
	ds_read_b128 v[164:167], v164 offset:3072
	s_add_u32 s8, s14, 0x160000
	s_addc_u32 s9, s15, 0
	s_mov_b32 m0, s26
	v_lshl_add_u64 v[202:203], s[8:9], 0, v[134:135]
	ds_read_b128 v[168:171], v150 offset:32768
	ds_read_b128 v[172:175], v150 offset:33792
	ds_read_b128 v[176:179], v150 offset:34816
	ds_read_b128 v[180:183], v150 offset:35840
	ds_read_b128 v[184:187], v150 offset:36864
	ds_read_b128 v[188:191], v150 offset:37888
	ds_read_b128 v[192:195], v150 offset:38912
	ds_read_b128 v[198:201], v150 offset:39936
	global_load_lds_dwordx4 v[202:203], off
	v_lshl_add_u64 v[202:203], s[8:9], 0, v[130:131]
	s_mov_b32 m0, s27
	s_nop 0
	global_load_lds_dwordx4 v[202:203], off
	s_waitcnt lgkmcnt(8)
	s_barrier
	s_setprio 1
	s_waitcnt lgkmcnt(7)
	v_mfma_f32_16x16x32_bf16 v[124:127], v[152:155], v[168:171], v[124:127]
	v_mfma_f32_16x16x32_bf16 v[120:123], v[160:163], v[168:171], v[120:123]
	s_waitcnt lgkmcnt(5)
	v_mfma_f32_16x16x32_bf16 v[108:111], v[152:155], v[176:179], v[108:111]
	v_mfma_f32_16x16x32_bf16 v[104:107], v[160:163], v[176:179], v[104:107]
	s_waitcnt lgkmcnt(3)
	v_mfma_f32_16x16x32_bf16 v[92:95], v[152:155], v[184:187], v[92:95]
	v_mfma_f32_16x16x32_bf16 v[88:91], v[160:163], v[184:187], v[88:91]
	s_waitcnt lgkmcnt(1)
	v_mfma_f32_16x16x32_bf16 v[76:79], v[152:155], v[192:195], v[76:79]
	v_mfma_f32_16x16x32_bf16 v[72:75], v[160:163], v[192:195], v[72:75]
	v_mfma_f32_16x16x32_bf16 v[124:127], v[156:159], v[172:175], v[124:127]
	v_mfma_f32_16x16x32_bf16 v[120:123], v[164:167], v[172:175], v[120:123]
	v_mfma_f32_16x16x32_bf16 v[108:111], v[156:159], v[180:183], v[108:111]
	v_mfma_f32_16x16x32_bf16 v[104:107], v[164:167], v[180:183], v[104:107]
	v_mfma_f32_16x16x32_bf16 v[92:95], v[156:159], v[188:191], v[92:95]
	v_mfma_f32_16x16x32_bf16 v[88:91], v[164:167], v[188:191], v[88:91]
	s_waitcnt lgkmcnt(0)
	v_mfma_f32_16x16x32_bf16 v[76:79], v[156:159], v[198:201], v[76:79]
	v_mfma_f32_16x16x32_bf16 v[72:75], v[164:167], v[198:201], v[72:75]
	s_setprio 0
	s_barrier
	s_add_i32 s14, 0, 0x1c000
	s_add_i32 s8, s39, s22
	v_add_u32_e32 v196, s14, v148
	v_lshl_add_u64 v[144:145], v[144:145], 0, s[52:53]
	s_mov_b32 m0, s8
	ds_read_b128 v[202:205], v196
	ds_read_b128 v[206:209], v196 offset:1024
	ds_read_b128 v[210:213], v196 offset:2048
	ds_read_b128 v[214:217], v196 offset:3072
	global_load_lds_dwordx4 v[144:145], off
	v_lshl_add_u64 v[144:145], v[218:219], 0, s[52:53]
	s_add_i32 m0, s8, 0x2000
	s_nop 0
	global_load_lds_dwordx4 v[144:145], off
	s_barrier
	s_setprio 1
	s_waitcnt lgkmcnt(3)
	v_mfma_f32_16x16x32_bf16 v[116:119], v[202:205], v[168:171], v[116:119]
	s_waitcnt lgkmcnt(1)
	v_mfma_f32_16x16x32_bf16 v[112:115], v[210:213], v[168:171], v[112:115]
	v_mfma_f32_16x16x32_bf16 v[100:103], v[202:205], v[176:179], v[100:103]
	v_mfma_f32_16x16x32_bf16 v[96:99], v[210:213], v[176:179], v[96:99]
	v_mfma_f32_16x16x32_bf16 v[84:87], v[202:205], v[184:187], v[84:87]
	v_mfma_f32_16x16x32_bf16 v[80:83], v[210:213], v[184:187], v[80:83]
	v_mfma_f32_16x16x32_bf16 v[68:71], v[202:205], v[192:195], v[68:71]
	v_mfma_f32_16x16x32_bf16 v[64:67], v[210:213], v[192:195], v[64:67]
	v_mfma_f32_16x16x32_bf16 v[116:119], v[206:209], v[172:175], v[116:119]
	s_waitcnt lgkmcnt(0)
	v_mfma_f32_16x16x32_bf16 v[112:115], v[214:217], v[172:175], v[112:115]
	v_mfma_f32_16x16x32_bf16 v[100:103], v[206:209], v[180:183], v[100:103]
	v_mfma_f32_16x16x32_bf16 v[96:99], v[214:217], v[180:183], v[96:99]
	v_mfma_f32_16x16x32_bf16 v[84:87], v[206:209], v[188:191], v[84:87]
	v_mfma_f32_16x16x32_bf16 v[80:83], v[214:217], v[188:191], v[80:83]
	v_mfma_f32_16x16x32_bf16 v[68:71], v[206:209], v[198:201], v[68:71]
	v_mfma_f32_16x16x32_bf16 v[64:67], v[214:217], v[198:201], v[64:67]
	s_setprio 0
	s_mov_b32 m0, s30
	v_lshl_add_u64 v[144:145], v[220:221], 0, s[52:53]
	s_barrier
; #define PG8_STAGE(bufoff, gbase, voff) do { _Pragma("unroll") for (int _i = 0; _i < 2; ++_i) \
;         __builtin_amdgcn_global_load_lds((const unsigned*)((const char*)(gbase) + (voff)[_i]), (LAS unsigned*)(lds + (bufoff) + ldsw + _i * 8192), 16, 0, 0); } while (0)
; #define PG8_LDA(dst, b, h) do { _Pragma("unroll") for (int m = 0; m < 4; ++m) _Pragma("unroll") for (int k = 0; k < 2; ++k) dst[m][k] = *(const LAS bf16x8*)(lds + PG8_SA(b, h) + aoff + m * 2048 + k * 1024); } while (0)
; #define PG8_MMA(ai, bj, At, Bt) do { __builtin_amdgcn_s_setprio(1); _Pragma("unroll") for (int m = 0; m < 4; ++m) _Pragma("unroll") for (int n = 0; n < 2; ++n) _Pragma("unroll") for (int k = 0; k < 2; ++k) \
;         acc[ai][bj][m][n] = __builtin_amdgcn_mfma_f32_16x16x32_bf16(Bt[n][k], At[m][k], acc[ai][bj][m][n], 0, 0, 0); __builtin_amdgcn_s_setprio(0); } while (0)
; #define PG8_WAIT_V(n) asm volatile("s_waitcnt vmcnt(" #n ")" ::: "memory")
; #define PG8_WAIT_L(n) asm volatile("s_waitcnt lgkmcnt(" #n ")" ::: "memory")
; #define PG8_BAR __builtin_amdgcn_s_barrier()
;     DI void operator()(const f32x4 (&acc)[2][2][4][2], const Unit& u, int wr, int wc, int fr, int fq) const {
;         const int row0 = u.pm * BM + wr * 64 + fr, col0 = u.pn * BM + wc * 32 + 8 * fq;
;         f32x4 sc[2][2];
; #pragma unroll
;         for (int bj = 0; bj < 2; ++bj)
; #pragma unroll
;             for (int n = 0; n < 2; ++n) sc[bj][n] = scale ? *(const f32x4*)(scale + col0 + bj * HALF + 4 * n) : (f32x4){1.f, 1.f, 1.f, 1.f};
; #pragma unroll
;         for (int ai = 0; ai < 2; ++ai)
; #pragma unroll
;             for (int m = 0; m < 4; ++m) { const size_t ro = (size_t)(row0 + ai * HALF + m * 16) * D + col0;
; #pragma unroll
;                 for (int bj = 0; bj < 2; ++bj) {
;                     f32x4 x0, x1;
;                     if constexpr (IB) { const u32x4 w = *(const u32x4*)((const bf16_t*)Xin + ro + bj * HALF);
; template <class Map, class Epi>
; DI void gemm_phase(LAS unsigned char* lds, const Map& MP, const Epi& E, const int nM, const int nN, const int K, const int lda, const int ldb) {
;     ...
;             PG8_LDA(At, 1, 1); PG8_STAGE(PG8_SA(1, 0), a3, voffA);
;             PG8_BAR; PG8_WAIT_L(0); PG8_MMA(1, 0, At, B0); PG8_BAR; PG8_SCHED;
;             PG8_STAGE(PG8_SB(1, 1), b3 + hstepB, voffB);
;             PG8_WAIT_V(6); PG8_BAR; PG8_MMA(1, 1, At, B1); PG8_BAR;
	ds_read_b128 v[168:171], v150 offset:49152
	ds_read_b128 v[172:175], v150 offset:50176
	ds_read_b128 v[176:179], v150 offset:51200
	ds_read_b128 v[180:183], v150 offset:52224
	ds_read_b128 v[184:187], v150 offset:53248
	ds_read_b128 v[188:191], v150 offset:54272
	ds_read_b128 v[192:195], v150 offset:55296
	ds_read_b128 v[198:201], v150 offset:56320
	global_load_lds_dwordx4 v[144:145], off
	v_lshl_add_u64 v[144:145], v[222:223], 0, s[52:53]
	s_mov_b32 m0, s31
	s_nop 0
	global_load_lds_dwordx4 v[144:145], off
	s_barrier
	s_setprio 1
	s_waitcnt lgkmcnt(7)
	v_mfma_f32_16x16x32_bf16 v[60:63], v[152:155], v[168:171], v[60:63]
	v_mfma_f32_16x16x32_bf16 v[56:59], v[160:163], v[168:171], v[56:59]
	s_waitcnt lgkmcnt(5)
	v_mfma_f32_16x16x32_bf16 v[44:47], v[152:155], v[176:179], v[44:47]
	v_mfma_f32_16x16x32_bf16 v[40:43], v[160:163], v[176:179], v[40:43]
	s_waitcnt lgkmcnt(3)
	v_mfma_f32_16x16x32_bf16 v[28:31], v[152:155], v[184:187], v[28:31]
	v_mfma_f32_16x16x32_bf16 v[24:27], v[160:163], v[184:187], v[24:27]
	s_waitcnt lgkmcnt(1)
	v_mfma_f32_16x16x32_bf16 v[12:15], v[152:155], v[192:195], v[12:15]
	v_mfma_f32_16x16x32_bf16 v[8:11], v[160:163], v[192:195], v[8:11]
	v_mfma_f32_16x16x32_bf16 v[60:63], v[156:159], v[172:175], v[60:63]
	v_mfma_f32_16x16x32_bf16 v[56:59], v[164:167], v[172:175], v[56:59]
	v_mfma_f32_16x16x32_bf16 v[44:47], v[156:159], v[180:183], v[44:47]
	v_mfma_f32_16x16x32_bf16 v[40:43], v[164:167], v[180:183], v[40:43]
	v_mfma_f32_16x16x32_bf16 v[28:31], v[156:159], v[188:191], v[28:31]
	v_mfma_f32_16x16x32_bf16 v[24:27], v[164:167], v[188:191], v[24:27]
	s_waitcnt lgkmcnt(0)
	v_mfma_f32_16x16x32_bf16 v[12:15], v[156:159], v[198:201], v[12:15]
	v_mfma_f32_16x16x32_bf16 v[8:11], v[164:167], v[198:201], v[8:11]
	s_setprio 0
	s_barrier
	s_add_u32 s8, s12, 0x160080
	s_addc_u32 s9, s13, 0
	s_add_i32 s12, s14, s22
	v_lshl_add_u64 v[144:145], s[8:9], 0, v[132:133]
	s_mov_b32 m0, s12
	s_nop 0
	global_load_lds_dwordx4 v[144:145], off
	v_lshl_add_u64 v[144:145], s[8:9], 0, v[128:129]
	s_add_i32 m0, s12, 0x2000
	s_nop 0
	global_load_lds_dwordx4 v[144:145], off
	s_waitcnt vmcnt(6)
	s_barrier
	s_setprio 1
	v_mfma_f32_16x16x32_bf16 v[52:55], v[202:205], v[168:171], v[52:55]
	v_mfma_f32_16x16x32_bf16 v[48:51], v[210:213], v[168:171], v[48:51]
	v_mfma_f32_16x16x32_bf16 v[36:39], v[202:205], v[176:179], v[36:39]
	v_mfma_f32_16x16x32_bf16 v[32:35], v[210:213], v[176:179], v[32:35]
	v_mfma_f32_16x16x32_bf16 v[20:23], v[202:205], v[184:187], v[20:23]
	v_mfma_f32_16x16x32_bf16 v[16:19], v[210:213], v[184:187], v[16:19]
	v_mfma_f32_16x16x32_bf16 v[4:7], v[202:205], v[192:195], v[4:7]
	v_mfma_f32_16x16x32_bf16 v[0:3], v[210:213], v[192:195], v[0:3]
	v_mfma_f32_16x16x32_bf16 v[52:55], v[206:209], v[172:175], v[52:55]
	v_mfma_f32_16x16x32_bf16 v[48:51], v[214:217], v[172:175], v[48:51]
	v_mfma_f32_16x16x32_bf16 v[36:39], v[206:209], v[180:183], v[36:39]
	v_mfma_f32_16x16x32_bf16 v[32:35], v[214:217], v[180:183], v[32:35]
	v_mfma_f32_16x16x32_bf16 v[20:23], v[206:209], v[188:191], v[20:23]
	v_mfma_f32_16x16x32_bf16 v[16:19], v[214:217], v[188:191], v[16:19]
	v_mfma_f32_16x16x32_bf16 v[4:7], v[206:209], v[198:201], v[4:7]
	v_mfma_f32_16x16x32_bf16 v[0:3], v[214:217], v[198:201], v[0:3]
	s_setprio 0
	s_add_i32 s3, s3, 2
	s_add_u32 s5, s5, 0x100
	s_addc_u32 s38, s38, 0
	s_cmpk_gt_u32 s3, 0x55
	s_mov_b64 s[8:9], s[10:11]
	s_barrier
	s_cbranch_scc0 .LBB1_1239
	v_mov_b32_e32 v152, v147
	v_mov_b32_e32 v144, v146
	s_lshl_b32 s2, s2, 8
	s_add_i32 s2, s2, s29
	s_lshl_b32 s3, s4, 8
	v_add_u32_e32 v152, s2, v152
	s_or_b32 s3, s3, s54
	v_ashrrev_i32_e32 v153, 31, v152
	v_lshl_add_u32 v144, v144, 3, s3
	v_lshlrev_b64 v[152:153], 12, v[152:153]
	v_ashrrev_i32_e32 v145, 31, v144
	v_lshl_add_u64 v[152:153], s[46:47], 0, v[152:153]
	v_lshl_add_u64 v[144:145], v[144:145], 1, v[152:153]
	global_load_dwordx4 v[160:163], v[144:145], off
	global_load_dwordx4 v[164:167], v[144:145], off offset:256
	s_mov_b64 s[98:99], 0x10000
	v_lshl_add_u64 v[154:155], v[144:145], 0, s[98:99]
	global_load_dwordx4 v[168:171], v[154:155], off
	global_load_dwordx4 v[172:175], v[154:155], off offset:256
	s_mov_b64 s[98:99], 0x20000
	v_lshl_add_u64 v[154:155], v[144:145], 0, s[98:99]
	global_load_dwordx4 v[176:179], v[154:155], off
	global_load_dwordx4 v[180:183], v[154:155], off offset:256
	s_mov_b64 s[98:99], 0x30000
	v_lshl_add_u64 v[154:155], v[144:145], 0, s[98:99]
	global_load_dwordx4 v[184:187], v[154:155], off
	global_load_dwordx4 v[188:191], v[154:155], off offset:256
	s_mov_b64 s[98:99], 0x80000
	v_lshl_add_u64 v[154:155], v[144:145], 0, s[98:99]
	global_load_dwordx4 v[192:195], v[154:155], off
	global_load_dwordx4 v[198:201], v[154:155], off offset:256
	s_mov_b64 s[98:99], 0x90000
	v_lshl_add_u64 v[154:155], v[144:145], 0, s[98:99]
	global_load_dwordx4 v[202:205], v[154:155], off
	global_load_dwordx4 v[206:209], v[154:155], off offset:256
	s_mov_b64 s[98:99], 0xa0000
	v_lshl_add_u64 v[154:155], v[144:145], 0, s[98:99]
	global_load_dwordx4 v[210:213], v[154:155], off
	global_load_dwordx4 v[214:217], v[154:155], off offset:256
	s_mov_b64 s[98:99], 0xb0000
	v_lshl_add_u64 v[154:155], v[144:145], 0, s[98:99]
	global_load_dwordx4 v[248:251], v[154:155], off
	global_load_dwordx4 v[252:255], v[154:155], off offset:256
	s_waitcnt vmcnt(15)
	s_nop 1
	v_mov_b32_e32 v152, v160
	v_mov_b32_e32 v153, v161
	v_mov_b32_e32 v154, v162
	v_mov_b32_e32 v155, v163
	s_mov_b64 s[2:3], 0x10000
	s_mov_b32 s4, s37
	s_mov_b64 s[10:11], s[6:7]
	s_mov_b64 s[8:9], s[42:43]
	s_waitcnt lgkmcnt(0)
; DI unsigned pack2(float a, float b) { f32x2 v = {a, b}; hwbf16x2 r = __builtin_convertvector(v, hwbf16x2); return __builtin_bit_cast(unsigned, r); }
; DI float bflo(unsigned w) { return __uint_as_float(w << 16); }
; DI float bfhi(unsigned w) { return __uint_as_float(w & 0xffff0000u); }
;     DI void operator()(const f32x4 (&acc)[2][2][4][2], const Unit& u, int wr, int wc, int fr, int fq) const {
;     ...
;             for (int m = 0; m < 4; ++m) { const size_t ro = (size_t)(row0 + ai * HALF + m * 16) * D + col0;
; #pragma unroll
;                 for (int bj = 0; bj < 2; ++bj) {
;                     f32x4 x0, x1;
;                     if constexpr (IB) { const u32x4 w = *(const u32x4*)((const bf16_t*)Xin + ro + bj * HALF);
;                         x0 = (f32x4){bflo(w[0]), bfhi(w[0]), bflo(w[1]), bfhi(w[1])}; x1 = (f32x4){bflo(w[2]), bfhi(w[2]), bflo(w[3]), bfhi(w[3])}; }
;                     else { x0 = *(const f32x4*)((const float*)Xin + ro + bj * HALF); x1 = *(const f32x4*)((const float*)Xin + ro + bj * HALF + 4); }
;                     x0 += acc[ai][bj][m][0] * sc[bj][0]; x1 += acc[ai][bj][m][1] * sc[bj][1];
;                     if constexpr (OB) { u32x4 o; o[0] = pack2(x0[0], x0[1]); o[1] = pack2(x0[2], x0[3]); o[2] = pack2(x1[0], x1[1]); o[3] = pack2(x1[2], x1[3]);
;                         *(u32x4*)((bf16_t*)Xout + ro + bj * HALF) = o; }
	v_lshlrev_b32_e32 v156, 16, v152
	v_and_b32_e32 v157, 0xffff0000, v152
	v_lshlrev_b32_e32 v152, 16, v153
	v_and_b32_e32 v153, 0xffff0000, v153
	v_lshlrev_b32_e32 v158, 16, v154
	v_and_b32_e32 v159, 0xffff0000, v154
	v_lshlrev_b32_e32 v154, 16, v155
	v_and_b32_e32 v155, 0xffff0000, v155
	v_pk_add_f32 v[126:127], v[126:127], v[152:153]
	v_pk_add_f32 v[124:125], v[124:125], v[156:157]
	v_pk_add_f32 v[152:153], v[122:123], v[154:155]
	v_pk_add_f32 v[122:123], v[120:121], v[158:159]
	v_cvt_pk_bf16_f32 v120, v124, v125
	v_cvt_pk_bf16_f32 v121, v126, v127
	v_cvt_pk_bf16_f32 v122, v122, v123
	v_cvt_pk_bf16_f32 v123, v152, v153
	global_store_dwordx4 v[144:145], v[120:123], off
	s_waitcnt vmcnt(15)
	s_nop 1
	v_mov_b32_e32 v120, v164
	v_mov_b32_e32 v121, v165
	v_mov_b32_e32 v122, v166
	v_mov_b32_e32 v123, v167
	s_waitcnt lgkmcnt(0)
	v_lshlrev_b32_e32 v124, 16, v120
	v_and_b32_e32 v125, 0xffff0000, v120
	v_lshlrev_b32_e32 v120, 16, v121
	v_and_b32_e32 v121, 0xffff0000, v121
	v_lshlrev_b32_e32 v126, 16, v122
	v_and_b32_e32 v127, 0xffff0000, v122
	v_lshlrev_b32_e32 v122, 16, v123
	v_and_b32_e32 v123, 0xffff0000, v123
	v_pk_add_f32 v[116:117], v[116:117], v[124:125]
	v_pk_add_f32 v[118:119], v[118:119], v[120:121]
	v_pk_add_f32 v[120:121], v[114:115], v[122:123]
	v_pk_add_f32 v[114:115], v[112:113], v[126:127]
	v_cvt_pk_bf16_f32 v112, v116, v117
	v_lshl_add_u64 v[116:117], v[144:145], 0, s[2:3]
	s_mov_b32 s2, 0x10000
	v_cvt_pk_bf16_f32 v113, v118, v119
	v_add_co_u32_e32 v118, vcc, s2, v144
	v_cvt_pk_bf16_f32 v114, v114, v115
	v_cvt_pk_bf16_f32 v115, v120, v121
	v_addc_co_u32_e32 v119, vcc, 0, v145, vcc
	global_store_dwordx4 v[144:145], v[112:115], off offset:256
	s_waitcnt vmcnt(15)
	s_nop 1
	v_mov_b32_e32 v112, v168
	v_mov_b32_e32 v113, v169
	v_mov_b32_e32 v114, v170
	v_mov_b32_e32 v115, v171
	s_mov_b64 s[2:3], 0x20000
	s_waitcnt lgkmcnt(0)
	v_lshlrev_b32_e32 v120, 16, v112
	v_and_b32_e32 v121, 0xffff0000, v112
	v_lshlrev_b32_e32 v112, 16, v113
	v_and_b32_e32 v113, 0xffff0000, v113
	v_lshlrev_b32_e32 v122, 16, v114
	v_and_b32_e32 v123, 0xffff0000, v114
	v_lshlrev_b32_e32 v114, 16, v115
	v_and_b32_e32 v115, 0xffff0000, v115
	v_pk_add_f32 v[110:111], v[110:111], v[112:113]
	v_pk_add_f32 v[108:109], v[108:109], v[120:121]
	v_pk_add_f32 v[112:113], v[106:107], v[114:115]
	v_pk_add_f32 v[106:107], v[104:105], v[122:123]
	v_cvt_pk_bf16_f32 v104, v108, v109
	v_cvt_pk_bf16_f32 v105, v110, v111
	v_cvt_pk_bf16_f32 v106, v106, v107
	v_cvt_pk_bf16_f32 v107, v112, v113
	global_store_dwordx4 v[118:119], v[104:107], off
	s_waitcnt vmcnt(15)
	s_nop 1
	v_mov_b32_e32 v104, v172
	v_mov_b32_e32 v105, v173
	v_mov_b32_e32 v106, v174
	v_mov_b32_e32 v107, v175
	s_waitcnt lgkmcnt(0)
	v_lshlrev_b32_e32 v108, 16, v104
	v_and_b32_e32 v109, 0xffff0000, v104
	v_lshlrev_b32_e32 v104, 16, v105
	v_and_b32_e32 v105, 0xffff0000, v105
	v_lshlrev_b32_e32 v110, 16, v106
	v_and_b32_e32 v111, 0xffff0000, v106
	v_lshlrev_b32_e32 v106, 16, v107
	v_and_b32_e32 v107, 0xffff0000, v107
	v_pk_add_f32 v[100:101], v[100:101], v[108:109]
	v_pk_add_f32 v[102:103], v[102:103], v[104:105]
	v_pk_add_f32 v[104:105], v[98:99], v[106:107]
	v_pk_add_f32 v[98:99], v[96:97], v[110:111]
	v_cvt_pk_bf16_f32 v96, v100, v101
	v_lshl_add_u64 v[100:101], v[144:145], 0, s[2:3]
	s_mov_b32 s2, 0x20000
	v_cvt_pk_bf16_f32 v97, v102, v103
	v_add_co_u32_e32 v102, vcc, s2, v144
	v_cvt_pk_bf16_f32 v98, v98, v99
	v_cvt_pk_bf16_f32 v99, v104, v105
	v_addc_co_u32_e32 v103, vcc, 0, v145, vcc
	global_store_dwordx4 v[116:117], v[96:99], off offset:256
	s_waitcnt vmcnt(15)
	s_nop 1
	v_mov_b32_e32 v96, v176
	v_mov_b32_e32 v97, v177
	v_mov_b32_e32 v98, v178
	v_mov_b32_e32 v99, v179
	s_mov_b64 s[2:3], 0x30000
	s_waitcnt lgkmcnt(0)
	v_lshlrev_b32_e32 v104, 16, v96
	v_and_b32_e32 v105, 0xffff0000, v96
	v_lshlrev_b32_e32 v96, 16, v97
	v_and_b32_e32 v97, 0xffff0000, v97
	v_lshlrev_b32_e32 v106, 16, v98
	v_and_b32_e32 v107, 0xffff0000, v98
	v_lshlrev_b32_e32 v98, 16, v99
	v_and_b32_e32 v99, 0xffff0000, v99
	v_pk_add_f32 v[94:95], v[94:95], v[96:97]
	v_pk_add_f32 v[92:93], v[92:93], v[104:105]
	v_pk_add_f32 v[96:97], v[90:91], v[98:99]
	v_pk_add_f32 v[90:91], v[88:89], v[106:107]
	v_cvt_pk_bf16_f32 v88, v92, v93
	v_cvt_pk_bf16_f32 v89, v94, v95
	v_cvt_pk_bf16_f32 v90, v90, v91
	v_cvt_pk_bf16_f32 v91, v96, v97
	global_store_dwordx4 v[102:103], v[88:91], off
	s_waitcnt vmcnt(15)
	s_nop 1
	v_mov_b32_e32 v88, v180
	v_mov_b32_e32 v89, v181
	v_mov_b32_e32 v90, v182
	v_mov_b32_e32 v91, v183
	s_waitcnt lgkmcnt(0)
	v_lshlrev_b32_e32 v92, 16, v88
	v_and_b32_e32 v93, 0xffff0000, v88
	v_lshlrev_b32_e32 v88, 16, v89
	v_and_b32_e32 v89, 0xffff0000, v89
	v_lshlrev_b32_e32 v94, 16, v90
	v_and_b32_e32 v95, 0xffff0000, v90
	v_lshlrev_b32_e32 v90, 16, v91
	v_and_b32_e32 v91, 0xffff0000, v91
	v_pk_add_f32 v[86:87], v[86:87], v[88:89]
	v_pk_add_f32 v[84:85], v[84:85], v[92:93]
	v_pk_add_f32 v[88:89], v[82:83], v[90:91]
	v_pk_add_f32 v[82:83], v[80:81], v[94:95]
	v_cvt_pk_bf16_f32 v80, v84, v85
	v_cvt_pk_bf16_f32 v81, v86, v87
	v_cvt_pk_bf16_f32 v82, v82, v83
	v_cvt_pk_bf16_f32 v83, v88, v89
	global_store_dwordx4 v[100:101], v[80:83], off offset:256
	s_nop 1
	v_lshl_add_u64 v[80:81], v[144:145], 0, s[2:3]
	s_mov_b32 s2, 0x30000
	v_add_co_u32_e32 v86, vcc, s2, v144
	s_mov_b64 s[2:3], 0x80000
	s_nop 0
	v_addc_co_u32_e32 v87, vcc, 0, v145, vcc
	s_waitcnt vmcnt(15)
	s_nop 1
	v_mov_b32_e32 v82, v184
	v_mov_b32_e32 v83, v185
	v_mov_b32_e32 v84, v186
	v_mov_b32_e32 v85, v187
	s_waitcnt lgkmcnt(0)
; DI unsigned pack2(float a, float b) { f32x2 v = {a, b}; hwbf16x2 r = __builtin_convertvector(v, hwbf16x2); return __builtin_bit_cast(unsigned, r); }
; DI float bflo(unsigned w) { return __uint_as_float(w << 16); }
; DI float bfhi(unsigned w) { return __uint_as_float(w & 0xffff0000u); }
;     DI void operator()(const f32x4 (&acc)[2][2][4][2], const Unit& u, int wr, int wc, int fr, int fq) const {
;     ...
;             for (int m = 0; m < 4; ++m) { const size_t ro = (size_t)(row0 + ai * HALF + m * 16) * D + col0;
; #pragma unroll
;                 for (int bj = 0; bj < 2; ++bj) {
;                     f32x4 x0, x1;
;                     if constexpr (IB) { const u32x4 w = *(const u32x4*)((const bf16_t*)Xin + ro + bj * HALF);
;                         x0 = (f32x4){bflo(w[0]), bfhi(w[0]), bflo(w[1]), bfhi(w[1])}; x1 = (f32x4){bflo(w[2]), bfhi(w[2]), bflo(w[3]), bfhi(w[3])}; }
;                     else { x0 = *(const f32x4*)((const float*)Xin + ro + bj * HALF); x1 = *(const f32x4*)((const float*)Xin + ro + bj * HALF + 4); }
;                     x0 += acc[ai][bj][m][0] * sc[bj][0]; x1 += acc[ai][bj][m][1] * sc[bj][1];
;                     if constexpr (OB) { u32x4 o; o[0] = pack2(x0[0], x0[1]); o[1] = pack2(x0[2], x0[3]); o[2] = pack2(x1[0], x1[1]); o[3] = pack2(x1[2], x1[3]);
;                         *(u32x4*)((bf16_t*)Xout + ro + bj * HALF) = o; }
	v_lshlrev_b32_e32 v88, 16, v82
	v_and_b32_e32 v89, 0xffff0000, v82
	v_lshlrev_b32_e32 v82, 16, v83
	v_and_b32_e32 v83, 0xffff0000, v83
	v_lshlrev_b32_e32 v90, 16, v84
	v_and_b32_e32 v91, 0xffff0000, v84
	v_lshlrev_b32_e32 v84, 16, v85
	v_and_b32_e32 v85, 0xffff0000, v85
	v_pk_add_f32 v[78:79], v[78:79], v[82:83]
	v_pk_add_f32 v[76:77], v[76:77], v[88:89]
	v_pk_add_f32 v[82:83], v[74:75], v[84:85]
	v_pk_add_f32 v[74:75], v[72:73], v[90:91]
	v_cvt_pk_bf16_f32 v72, v76, v77
	v_cvt_pk_bf16_f32 v73, v78, v79
	v_cvt_pk_bf16_f32 v74, v74, v75
	v_cvt_pk_bf16_f32 v75, v82, v83
	global_store_dwordx4 v[86:87], v[72:75], off
	s_waitcnt vmcnt(15)
	s_nop 1
	v_mov_b32_e32 v72, v188
	v_mov_b32_e32 v73, v189
	v_mov_b32_e32 v74, v190
	v_mov_b32_e32 v75, v191
	s_waitcnt lgkmcnt(0)
	v_lshlrev_b32_e32 v76, 16, v72
	v_and_b32_e32 v77, 0xffff0000, v72
	v_lshlrev_b32_e32 v72, 16, v73
	v_and_b32_e32 v73, 0xffff0000, v73
	v_lshlrev_b32_e32 v78, 16, v74
	v_and_b32_e32 v79, 0xffff0000, v74
	v_lshlrev_b32_e32 v74, 16, v75
	v_and_b32_e32 v75, 0xffff0000, v75
	v_pk_add_f32 v[70:71], v[70:71], v[72:73]
	v_pk_add_f32 v[68:69], v[68:69], v[76:77]
	v_pk_add_f32 v[72:73], v[66:67], v[74:75]
	v_pk_add_f32 v[66:67], v[64:65], v[78:79]
	v_cvt_pk_bf16_f32 v64, v68, v69
	v_cvt_pk_bf16_f32 v65, v70, v71
	v_cvt_pk_bf16_f32 v66, v66, v67
	v_cvt_pk_bf16_f32 v67, v72, v73
	global_store_dwordx4 v[80:81], v[64:67], off offset:256
	s_nop 1
	v_lshl_add_u64 v[64:65], v[144:145], 0, s[2:3]
	s_mov_b32 s2, 0x80000
	v_add_co_u32_e32 v70, vcc, s2, v144
	s_mov_b64 s[2:3], 0x90000
	s_nop 0
	v_addc_co_u32_e32 v71, vcc, 0, v145, vcc
	s_waitcnt vmcnt(15)
	s_nop 1
	v_mov_b32_e32 v66, v192
	v_mov_b32_e32 v67, v193
	v_mov_b32_e32 v68, v194
	v_mov_b32_e32 v69, v195
	s_waitcnt lgkmcnt(0)
	v_lshlrev_b32_e32 v72, 16, v66
	v_and_b32_e32 v73, 0xffff0000, v66
	v_lshlrev_b32_e32 v66, 16, v67
	v_and_b32_e32 v67, 0xffff0000, v67
	v_lshlrev_b32_e32 v74, 16, v68
	v_and_b32_e32 v75, 0xffff0000, v68
	v_lshlrev_b32_e32 v68, 16, v69
	v_and_b32_e32 v69, 0xffff0000, v69
	v_pk_add_f32 v[62:63], v[62:63], v[66:67]
	v_pk_add_f32 v[60:61], v[60:61], v[72:73]
	v_pk_add_f32 v[66:67], v[58:59], v[68:69]
	v_pk_add_f32 v[58:59], v[56:57], v[74:75]
	v_cvt_pk_bf16_f32 v56, v60, v61
	v_cvt_pk_bf16_f32 v57, v62, v63
	v_cvt_pk_bf16_f32 v58, v58, v59
	v_cvt_pk_bf16_f32 v59, v66, v67
	global_store_dwordx4 v[70:71], v[56:59], off
	s_waitcnt vmcnt(15)
	s_nop 1
	v_mov_b32_e32 v56, v198
	v_mov_b32_e32 v57, v199
	v_mov_b32_e32 v58, v200
	v_mov_b32_e32 v59, v201
	s_waitcnt lgkmcnt(0)
	v_lshlrev_b32_e32 v60, 16, v56
	v_and_b32_e32 v61, 0xffff0000, v56
	v_lshlrev_b32_e32 v56, 16, v57
	v_and_b32_e32 v57, 0xffff0000, v57
	v_lshlrev_b32_e32 v62, 16, v58
	v_and_b32_e32 v63, 0xffff0000, v58
	v_lshlrev_b32_e32 v58, 16, v59
	v_and_b32_e32 v59, 0xffff0000, v59
	v_pk_add_f32 v[54:55], v[54:55], v[56:57]
	v_pk_add_f32 v[52:53], v[52:53], v[60:61]
	v_pk_add_f32 v[56:57], v[50:51], v[58:59]
	v_pk_add_f32 v[50:51], v[48:49], v[62:63]
	v_cvt_pk_bf16_f32 v48, v52, v53
	v_cvt_pk_bf16_f32 v49, v54, v55
	v_cvt_pk_bf16_f32 v50, v50, v51
	v_cvt_pk_bf16_f32 v51, v56, v57
	global_store_dwordx4 v[64:65], v[48:51], off offset:256
	s_nop 1
	v_lshl_add_u64 v[48:49], v[144:145], 0, s[2:3]
	s_mov_b32 s2, 0x90000
	v_add_co_u32_e32 v54, vcc, s2, v144
	s_mov_b64 s[2:3], 0xa0000
	s_nop 0
	v_addc_co_u32_e32 v55, vcc, 0, v145, vcc
	s_waitcnt vmcnt(15)
	s_nop 1
	v_mov_b32_e32 v50, v202
	v_mov_b32_e32 v51, v203
	v_mov_b32_e32 v52, v204
	v_mov_b32_e32 v53, v205
	s_waitcnt lgkmcnt(0)
	v_lshlrev_b32_e32 v56, 16, v50
	v_and_b32_e32 v57, 0xffff0000, v50
	v_lshlrev_b32_e32 v50, 16, v51
	v_and_b32_e32 v51, 0xffff0000, v51
	v_lshlrev_b32_e32 v58, 16, v52
	v_and_b32_e32 v59, 0xffff0000, v52
	v_lshlrev_b32_e32 v52, 16, v53
	v_and_b32_e32 v53, 0xffff0000, v53
	v_pk_add_f32 v[46:47], v[46:47], v[50:51]
	v_pk_add_f32 v[44:45], v[44:45], v[56:57]
	v_pk_add_f32 v[50:51], v[42:43], v[52:53]
	v_pk_add_f32 v[42:43], v[40:41], v[58:59]
	v_cvt_pk_bf16_f32 v40, v44, v45
	v_cvt_pk_bf16_f32 v41, v46, v47
	v_cvt_pk_bf16_f32 v42, v42, v43
	v_cvt_pk_bf16_f32 v43, v50, v51
	global_store_dwordx4 v[54:55], v[40:43], off
	s_waitcnt vmcnt(15)
	s_nop 1
	v_mov_b32_e32 v40, v206
	v_mov_b32_e32 v41, v207
	v_mov_b32_e32 v42, v208
	v_mov_b32_e32 v43, v209
	s_waitcnt lgkmcnt(0)
; DI unsigned pack2(float a, float b) { f32x2 v = {a, b}; hwbf16x2 r = __builtin_convertvector(v, hwbf16x2); return __builtin_bit_cast(unsigned, r); }
; DI float bflo(unsigned w) { return __uint_as_float(w << 16); }
; DI float bfhi(unsigned w) { return __uint_as_float(w & 0xffff0000u); }
;     DI void operator()(const f32x4 (&acc)[2][2][4][2], const Unit& u, int wr, int wc, int fr, int fq) const {
;     ...
;             for (int m = 0; m < 4; ++m) { const size_t ro = (size_t)(row0 + ai * HALF + m * 16) * D + col0;
; #pragma unroll
;                 for (int bj = 0; bj < 2; ++bj) {
;                     f32x4 x0, x1;
;                     if constexpr (IB) { const u32x4 w = *(const u32x4*)((const bf16_t*)Xin + ro + bj * HALF);
;                         x0 = (f32x4){bflo(w[0]), bfhi(w[0]), bflo(w[1]), bfhi(w[1])}; x1 = (f32x4){bflo(w[2]), bfhi(w[2]), bflo(w[3]), bfhi(w[3])}; }
;                     else { x0 = *(const f32x4*)((const float*)Xin + ro + bj * HALF); x1 = *(const f32x4*)((const float*)Xin + ro + bj * HALF + 4); }
;                     x0 += acc[ai][bj][m][0] * sc[bj][0]; x1 += acc[ai][bj][m][1] * sc[bj][1];
;                     if constexpr (OB) { u32x4 o; o[0] = pack2(x0[0], x0[1]); o[1] = pack2(x0[2], x0[3]); o[2] = pack2(x1[0], x1[1]); o[3] = pack2(x1[2], x1[3]);
;                         *(u32x4*)((bf16_t*)Xout + ro + bj * HALF) = o; }
	v_lshlrev_b32_e32 v44, 16, v40
	v_and_b32_e32 v45, 0xffff0000, v40
	v_lshlrev_b32_e32 v40, 16, v41
	v_and_b32_e32 v41, 0xffff0000, v41
	v_lshlrev_b32_e32 v46, 16, v42
	v_and_b32_e32 v47, 0xffff0000, v42
	v_lshlrev_b32_e32 v42, 16, v43
	v_and_b32_e32 v43, 0xffff0000, v43
	v_pk_add_f32 v[38:39], v[38:39], v[40:41]
	v_pk_add_f32 v[36:37], v[36:37], v[44:45]
	v_pk_add_f32 v[40:41], v[34:35], v[42:43]
	v_pk_add_f32 v[34:35], v[32:33], v[46:47]
	v_cvt_pk_bf16_f32 v32, v36, v37
	v_cvt_pk_bf16_f32 v33, v38, v39
	v_cvt_pk_bf16_f32 v34, v34, v35
	v_cvt_pk_bf16_f32 v35, v40, v41
	global_store_dwordx4 v[48:49], v[32:35], off offset:256
	s_nop 1
	v_lshl_add_u64 v[32:33], v[144:145], 0, s[2:3]
	s_mov_b32 s2, 0xa0000
	v_add_co_u32_e32 v38, vcc, s2, v144
	s_mov_b64 s[2:3], 0xb0000
	s_nop 0
	v_addc_co_u32_e32 v39, vcc, 0, v145, vcc
	s_waitcnt vmcnt(15)
	s_nop 1
	v_mov_b32_e32 v34, v210
	v_mov_b32_e32 v35, v211
	v_mov_b32_e32 v36, v212
	v_mov_b32_e32 v37, v213
	s_waitcnt lgkmcnt(0)
	v_lshlrev_b32_e32 v40, 16, v34
	v_and_b32_e32 v41, 0xffff0000, v34
	v_lshlrev_b32_e32 v34, 16, v35
	v_and_b32_e32 v35, 0xffff0000, v35
	v_lshlrev_b32_e32 v42, 16, v36
	v_and_b32_e32 v43, 0xffff0000, v36
	v_lshlrev_b32_e32 v36, 16, v37
	v_and_b32_e32 v37, 0xffff0000, v37
	v_pk_add_f32 v[30:31], v[30:31], v[34:35]
	v_pk_add_f32 v[28:29], v[28:29], v[40:41]
	v_pk_add_f32 v[34:35], v[26:27], v[36:37]
	v_pk_add_f32 v[26:27], v[24:25], v[42:43]
	v_cvt_pk_bf16_f32 v24, v28, v29
	v_cvt_pk_bf16_f32 v25, v30, v31
	v_cvt_pk_bf16_f32 v26, v26, v27
	v_cvt_pk_bf16_f32 v27, v34, v35
	global_store_dwordx4 v[38:39], v[24:27], off
	s_waitcnt vmcnt(15)
	s_nop 1
	v_mov_b32_e32 v24, v214
	v_mov_b32_e32 v25, v215
	v_mov_b32_e32 v26, v216
	v_mov_b32_e32 v27, v217
	s_waitcnt lgkmcnt(0)
	v_lshlrev_b32_e32 v28, 16, v24
	v_and_b32_e32 v29, 0xffff0000, v24
	v_lshlrev_b32_e32 v24, 16, v25
	v_and_b32_e32 v25, 0xffff0000, v25
	v_lshlrev_b32_e32 v30, 16, v26
	v_and_b32_e32 v31, 0xffff0000, v26
	v_lshlrev_b32_e32 v26, 16, v27
	v_and_b32_e32 v27, 0xffff0000, v27
	v_pk_add_f32 v[22:23], v[22:23], v[24:25]
	v_pk_add_f32 v[20:21], v[20:21], v[28:29]
	v_pk_add_f32 v[24:25], v[18:19], v[26:27]
	v_pk_add_f32 v[18:19], v[16:17], v[30:31]
	v_cvt_pk_bf16_f32 v16, v20, v21
	v_cvt_pk_bf16_f32 v17, v22, v23
	v_cvt_pk_bf16_f32 v18, v18, v19
	v_cvt_pk_bf16_f32 v19, v24, v25
	global_store_dwordx4 v[32:33], v[16:19], off offset:256
	s_nop 1
	v_lshl_add_u64 v[16:17], v[144:145], 0, s[2:3]
	s_mov_b32 s2, 0xb0000
	v_add_co_u32_e32 v22, vcc, s2, v144
	s_mov_b32 s2, s55
	s_nop 0
	v_addc_co_u32_e32 v23, vcc, 0, v145, vcc
	s_waitcnt vmcnt(15)
	s_nop 1
	v_mov_b32_e32 v18, v248
	v_mov_b32_e32 v19, v249
	v_mov_b32_e32 v20, v250
	v_mov_b32_e32 v21, v251
	s_and_b64 vcc, exec, s[40:41]
	s_waitcnt lgkmcnt(0)
	v_lshlrev_b32_e32 v24, 16, v18
	v_and_b32_e32 v25, 0xffff0000, v18
	v_lshlrev_b32_e32 v18, 16, v19
	v_and_b32_e32 v19, 0xffff0000, v19
	v_lshlrev_b32_e32 v26, 16, v20
	v_and_b32_e32 v27, 0xffff0000, v20
	v_lshlrev_b32_e32 v20, 16, v21
	v_and_b32_e32 v21, 0xffff0000, v21
	v_pk_add_f32 v[14:15], v[14:15], v[18:19]
	v_pk_add_f32 v[12:13], v[12:13], v[24:25]
	v_pk_add_f32 v[18:19], v[10:11], v[20:21]
	v_pk_add_f32 v[10:11], v[8:9], v[26:27]
	v_cvt_pk_bf16_f32 v8, v12, v13
	v_cvt_pk_bf16_f32 v9, v14, v15
	v_cvt_pk_bf16_f32 v10, v10, v11
	v_cvt_pk_bf16_f32 v11, v18, v19
	global_store_dwordx4 v[22:23], v[8:11], off
	s_waitcnt vmcnt(15)
	s_nop 1
	v_mov_b32_e32 v8, v252
	v_mov_b32_e32 v9, v253
	v_mov_b32_e32 v10, v254
	v_mov_b32_e32 v11, v255
	s_waitcnt lgkmcnt(0)
	v_lshlrev_b32_e32 v12, 16, v8
	v_and_b32_e32 v13, 0xffff0000, v8
	v_lshlrev_b32_e32 v8, 16, v9
	v_and_b32_e32 v9, 0xffff0000, v9
	v_lshlrev_b32_e32 v14, 16, v10
	v_and_b32_e32 v15, 0xffff0000, v10
	v_lshlrev_b32_e32 v10, 16, v11
	v_and_b32_e32 v11, 0xffff0000, v11
	v_pk_add_f32 v[6:7], v[6:7], v[8:9]
	v_pk_add_f32 v[4:5], v[4:5], v[12:13]
	v_pk_add_f32 v[8:9], v[2:3], v[10:11]
	v_pk_add_f32 v[2:3], v[0:1], v[14:15]
	v_cvt_pk_bf16_f32 v0, v4, v5
	v_cvt_pk_bf16_f32 v1, v6, v7
	v_cvt_pk_bf16_f32 v2, v2, v3
	v_cvt_pk_bf16_f32 v3, v8, v9
	global_store_dwordx4 v[16:17], v[0:3], off offset:256
	s_cbranch_vccz .LBB1_1232
	s_waitcnt vmcnt(0)
	s_cmpk_gt_u32 s17, 0xff
	s_cbranch_scc1 .LBB1_1243
	s_barrier

; #define PG8_STAGE(bufoff, gbase, voff) do { _Pragma("unroll") for (int _i = 0; _i < 2; ++_i) \
;         __builtin_amdgcn_global_load_lds((const unsigned*)((const char*)(gbase) + (voff)[_i]), (LAS unsigned*)(lds + (bufoff) + ldsw + _i * 8192), 16, 0, 0); } while (0)
; #define PG8_LDA(dst, b, h) do { _Pragma("unroll") for (int m = 0; m < 4; ++m) _Pragma("unroll") for (int k = 0; k < 2; ++k) dst[m][k] = *(const LAS bf16x8*)(lds + PG8_SA(b, h) + aoff + m * 2048 + k * 1024); } while (0)
; #define PG8_LDB(dst, b, h) do { _Pragma("unroll") for (int n = 0; n < 2; ++n) _Pragma("unroll") for (int k = 0; k < 2; ++k) dst[n][k] = *(const LAS bf16x8*)(lds + PG8_SB(b, h) + boff + n * 2048 + k * 1024); } while (0)
; #define PG8_MMA(ai, bj, At, Bt) do { __builtin_amdgcn_s_setprio(1); _Pragma("unroll") for (int m = 0; m < 4; ++m) _Pragma("unroll") for (int n = 0; n < 2; ++n) _Pragma("unroll") for (int k = 0; k < 2; ++k) \
;         acc[ai][bj][m][n] = __builtin_amdgcn_mfma_f32_16x16x32_bf16(Bt[n][k], At[m][k], acc[ai][bj][m][n], 0, 0, 0); __builtin_amdgcn_s_setprio(0); } while (0)
; #define PG8_WAIT_L(n) asm volatile("s_waitcnt lgkmcnt(" #n ")" ::: "memory")
; #define PG8_BAR __builtin_amdgcn_s_barrier()
; #define PG8_SCHED __builtin_amdgcn_sched_barrier(0)
; template <class Map, class Epi>
; DI void gemm_phase(LAS unsigned char* lds, const Map& MP, const Epi& E, const int nM, const int nN, const int K, const int lda, const int ldb) {
;     ...
;             PG8_LDB(B0, 0, 0); PG8_SCHED; PG8_LDA(At, 0, 0); PG8_STAGE(PG8_SA(1, 1), a1 + hstepA, voffA);
;             PG8_WAIT_L(8); PG8_BAR; PG8_WAIT_L(0); PG8_MMA(0, 0, At, B0); PG8_BAR; PG8_SCHED;
;             PG8_LDB(B1, 0, 1); PG8_STAGE(PG8_SB(0, 0), b2, voffB);
;             PG8_BAR; PG8_WAIT_L(0); PG8_MMA(0, 1, At, B1); PG8_BAR;
;             PG8_LDA(At, 0, 1); PG8_STAGE(PG8_SA(0, 0), a2, voffA);
;             PG8_BAR; PG8_WAIT_L(0); PG8_MMA(1, 0, At, B0); PG8_BAR; PG8_SCHED;
.LBB1_1764:
	ds_read_b128 v[152:155], v149
	ds_read_b128 v[156:159], v149 offset:1024
	ds_read_b128 v[160:163], v149 offset:2048
	ds_read_b128 v[164:167], v149 offset:3072
	s_add_u32 s12, s10, 0xfff80080
	s_addc_u32 s13, s11, -1
	s_cmp_eq_u32 s3, 28
	s_cselect_b32 s15, s37, s13
	s_cselect_b32 s14, s38, s12
	s_cselect_b32 s13, s39, s48
	s_cselect_b32 s12, s45, s47
	v_lshl_add_u64 v[144:145], s[10:11], 0, v[138:139]
	s_add_i32 m0, s24, 0xc000
	ds_read_b128 v[168:171], v150
	ds_read_b128 v[172:175], v150 offset:1024
	ds_read_b128 v[176:179], v150 offset:2048
	ds_read_b128 v[180:183], v150 offset:3072
	ds_read_b128 v[184:187], v150 offset:4096
	ds_read_b128 v[188:191], v150 offset:5120
	ds_read_b128 v[192:195], v150 offset:6144
	ds_read_b128 v[198:201], v150 offset:7168
	global_load_lds_dwordx4 v[144:145], off
	v_lshl_add_u64 v[144:145], s[10:11], 0, v[136:137]
	s_add_i32 m0, s24, 0xe000
	s_nop 0
	global_load_lds_dwordx4 v[144:145], off
	s_waitcnt lgkmcnt(8)
	s_barrier
	s_setprio 1
	s_waitcnt lgkmcnt(7)
	v_mfma_f32_16x16x32_bf16 v[124:127], v[152:155], v[168:171], v[124:127]
	v_mfma_f32_16x16x32_bf16 v[120:123], v[160:163], v[168:171], v[120:123]
	s_waitcnt lgkmcnt(5)
	v_mfma_f32_16x16x32_bf16 v[108:111], v[152:155], v[176:179], v[108:111]
	v_mfma_f32_16x16x32_bf16 v[104:107], v[160:163], v[176:179], v[104:107]
	s_waitcnt lgkmcnt(3)
	v_mfma_f32_16x16x32_bf16 v[92:95], v[152:155], v[184:187], v[92:95]
	v_mfma_f32_16x16x32_bf16 v[88:91], v[160:163], v[184:187], v[88:91]
	s_waitcnt lgkmcnt(1)
	v_mfma_f32_16x16x32_bf16 v[76:79], v[152:155], v[192:195], v[76:79]
	v_mfma_f32_16x16x32_bf16 v[72:75], v[160:163], v[192:195], v[72:75]
	v_mfma_f32_16x16x32_bf16 v[124:127], v[156:159], v[172:175], v[124:127]
	v_mfma_f32_16x16x32_bf16 v[120:123], v[164:167], v[172:175], v[120:123]
	v_mfma_f32_16x16x32_bf16 v[108:111], v[156:159], v[180:183], v[108:111]
	v_mfma_f32_16x16x32_bf16 v[104:107], v[164:167], v[180:183], v[104:107]
	v_mfma_f32_16x16x32_bf16 v[92:95], v[156:159], v[188:191], v[92:95]
	v_mfma_f32_16x16x32_bf16 v[88:91], v[164:167], v[188:191], v[88:91]
	s_waitcnt lgkmcnt(0)
	v_mfma_f32_16x16x32_bf16 v[76:79], v[156:159], v[198:201], v[76:79]
	v_mfma_f32_16x16x32_bf16 v[72:75], v[164:167], v[198:201], v[72:75]
	s_setprio 0
	s_barrier
	s_add_i32 s49, s35, s22
	v_lshl_add_u64 v[144:145], s[12:13], 0, v[132:133]
	s_mov_b32 m0, s49
	ds_read_b128 v[202:205], v151
	ds_read_b128 v[206:209], v151 offset:1024
	ds_read_b128 v[210:213], v151 offset:2048
	ds_read_b128 v[214:217], v151 offset:3072
	global_load_lds_dwordx4 v[144:145], off
	v_lshl_add_u64 v[218:219], s[12:13], 0, v[128:129]
	s_add_i32 m0, s49, 0x2000
	s_nop 0
	global_load_lds_dwordx4 v[218:219], off
	s_barrier
	s_setprio 1
	s_waitcnt lgkmcnt(3)
	v_mfma_f32_16x16x32_bf16 v[116:119], v[202:205], v[168:171], v[116:119]
	s_waitcnt lgkmcnt(1)
	v_mfma_f32_16x16x32_bf16 v[112:115], v[210:213], v[168:171], v[112:115]
	v_mfma_f32_16x16x32_bf16 v[100:103], v[202:205], v[176:179], v[100:103]
	v_mfma_f32_16x16x32_bf16 v[96:99], v[210:213], v[176:179], v[96:99]
	v_mfma_f32_16x16x32_bf16 v[84:87], v[202:205], v[184:187], v[84:87]
	v_mfma_f32_16x16x32_bf16 v[80:83], v[210:213], v[184:187], v[80:83]
	v_mfma_f32_16x16x32_bf16 v[68:71], v[202:205], v[192:195], v[68:71]
	v_mfma_f32_16x16x32_bf16 v[64:67], v[210:213], v[192:195], v[64:67]
	v_mfma_f32_16x16x32_bf16 v[116:119], v[206:209], v[172:175], v[116:119]
	s_waitcnt lgkmcnt(0)
	v_mfma_f32_16x16x32_bf16 v[112:115], v[214:217], v[172:175], v[112:115]
	v_mfma_f32_16x16x32_bf16 v[100:103], v[206:209], v[180:183], v[100:103]
	v_mfma_f32_16x16x32_bf16 v[96:99], v[214:217], v[180:183], v[96:99]
	v_mfma_f32_16x16x32_bf16 v[84:87], v[206:209], v[188:191], v[84:87]
	v_mfma_f32_16x16x32_bf16 v[80:83], v[214:217], v[188:191], v[80:83]
	v_mfma_f32_16x16x32_bf16 v[68:71], v[206:209], v[198:201], v[68:71]
	v_mfma_f32_16x16x32_bf16 v[64:67], v[214:217], v[198:201], v[64:67]
	s_setprio 0
	s_mov_b32 m0, s24
	v_lshl_add_u64 v[220:221], s[14:15], 0, v[134:135]
	s_barrier
	ds_read_b128 v[168:171], v150 offset:16384
	ds_read_b128 v[172:175], v150 offset:17408
	ds_read_b128 v[176:179], v150 offset:18432
	ds_read_b128 v[180:183], v150 offset:19456
	ds_read_b128 v[184:187], v150 offset:20480
	ds_read_b128 v[188:191], v150 offset:21504
	ds_read_b128 v[192:195], v150 offset:22528
	ds_read_b128 v[198:201], v150 offset:23552
	global_load_lds_dwordx4 v[220:221], off
	v_lshl_add_u64 v[222:223], s[14:15], 0, v[130:131]
	s_mov_b32 m0, s9
	s_nop 0
	global_load_lds_dwordx4 v[222:223], off
	s_barrier
	s_setprio 1
	s_waitcnt lgkmcnt(7)
	v_mfma_f32_16x16x32_bf16 v[60:63], v[152:155], v[168:171], v[60:63]
	v_mfma_f32_16x16x32_bf16 v[56:59], v[160:163], v[168:171], v[56:59]
	s_waitcnt lgkmcnt(5)
	v_mfma_f32_16x16x32_bf16 v[44:47], v[152:155], v[176:179], v[44:47]
	v_mfma_f32_16x16x32_bf16 v[40:43], v[160:163], v[176:179], v[40:43]
	s_waitcnt lgkmcnt(3)
	v_mfma_f32_16x16x32_bf16 v[28:31], v[152:155], v[184:187], v[28:31]
	v_mfma_f32_16x16x32_bf16 v[24:27], v[160:163], v[184:187], v[24:27]
	s_waitcnt lgkmcnt(1)
	v_mfma_f32_16x16x32_bf16 v[12:15], v[152:155], v[192:195], v[12:15]
	v_mfma_f32_16x16x32_bf16 v[8:11], v[160:163], v[192:195], v[8:11]
	v_mfma_f32_16x16x32_bf16 v[60:63], v[156:159], v[172:175], v[60:63]
	v_mfma_f32_16x16x32_bf16 v[56:59], v[164:167], v[172:175], v[56:59]
	v_mfma_f32_16x16x32_bf16 v[44:47], v[156:159], v[180:183], v[44:47]
	v_mfma_f32_16x16x32_bf16 v[40:43], v[164:167], v[180:183], v[40:43]
	v_mfma_f32_16x16x32_bf16 v[28:31], v[156:159], v[188:191], v[28:31]
	v_mfma_f32_16x16x32_bf16 v[24:27], v[164:167], v[188:191], v[24:27]
	s_waitcnt lgkmcnt(0)
	v_mfma_f32_16x16x32_bf16 v[12:15], v[156:159], v[198:201], v[12:15]
	v_mfma_f32_16x16x32_bf16 v[8:11], v[164:167], v[198:201], v[8:11]
	s_setprio 0
	s_barrier
; #define PG8_STAGE(bufoff, gbase, voff) do { _Pragma("unroll") for (int _i = 0; _i < 2; ++_i) \
;         __builtin_amdgcn_global_load_lds((const unsigned*)((const char*)(gbase) + (voff)[_i]), (LAS unsigned*)(lds + (bufoff) + ldsw + _i * 8192), 16, 0, 0); } while (0)
; #define PG8_LDA(dst, b, h) do { _Pragma("unroll") for (int m = 0; m < 4; ++m) _Pragma("unroll") for (int k = 0; k < 2; ++k) dst[m][k] = *(const LAS bf16x8*)(lds + PG8_SA(b, h) + aoff + m * 2048 + k * 1024); } while (0)
; #define PG8_LDB(dst, b, h) do { _Pragma("unroll") for (int n = 0; n < 2; ++n) _Pragma("unroll") for (int k = 0; k < 2; ++k) dst[n][k] = *(const LAS bf16x8*)(lds + PG8_SB(b, h) + boff + n * 2048 + k * 1024); } while (0)
; #define PG8_MMA(ai, bj, At, Bt) do { __builtin_amdgcn_s_setprio(1); _Pragma("unroll") for (int m = 0; m < 4; ++m) _Pragma("unroll") for (int n = 0; n < 2; ++n) _Pragma("unroll") for (int k = 0; k < 2; ++k) \
;         acc[ai][bj][m][n] = __builtin_amdgcn_mfma_f32_16x16x32_bf16(Bt[n][k], At[m][k], acc[ai][bj][m][n], 0, 0, 0); __builtin_amdgcn_s_setprio(0); } while (0)
; #define PG8_WAIT_V(n) asm volatile("s_waitcnt vmcnt(" #n ")" ::: "memory")
; #define PG8_WAIT_L(n) asm volatile("s_waitcnt lgkmcnt(" #n ")" ::: "memory")
; #define PG8_BAR __builtin_amdgcn_s_barrier()
; #define PG8_SCHED __builtin_amdgcn_sched_barrier(0)
; template <class Map, class Epi>
; DI void gemm_phase(LAS unsigned char* lds, const Map& MP, const Epi& E, const int nM, const int nN, const int K, const int lda, const int ldb) {
;     ...
;             PG8_STAGE(PG8_SB(0, 1), b2 + hstepB, voffB);
;             PG8_WAIT_V(6); PG8_BAR; PG8_MMA(1, 1, At, B1); PG8_BAR;
;             PG8_LDB(B0, 1, 0); PG8_SCHED; PG8_LDA(At, 1, 0); PG8_STAGE(PG8_SA(0, 1), a2 + hstepA, voffA);
;             PG8_WAIT_L(8); PG8_BAR; PG8_WAIT_L(0); PG8_MMA(0, 0, At, B0); PG8_BAR; PG8_SCHED;
;             PG8_LDB(B1, 1, 1); PG8_STAGE(PG8_SB(1, 0), b3, voffB);
;             PG8_BAR; PG8_WAIT_L(0); PG8_MMA(0, 1, At, B1); PG8_BAR;
	s_add_u32 s54, s12, 0x80000
	s_addc_u32 s55, s13, 0
	s_add_i32 s49, s36, s22
	v_lshl_add_u64 v[152:153], s[54:55], 0, v[132:133]
	s_mov_b32 m0, s49
	s_nop 0
	global_load_lds_dwordx4 v[152:153], off
	v_lshl_add_u64 v[152:153], s[54:55], 0, v[128:129]
	s_add_i32 m0, s49, 0x2000
	s_nop 0
	global_load_lds_dwordx4 v[152:153], off
	s_waitcnt vmcnt(6)
	s_barrier
	s_setprio 1
	v_mfma_f32_16x16x32_bf16 v[52:55], v[202:205], v[168:171], v[52:55]
	v_mfma_f32_16x16x32_bf16 v[48:51], v[210:213], v[168:171], v[48:51]
	v_mfma_f32_16x16x32_bf16 v[36:39], v[202:205], v[176:179], v[36:39]
	v_mfma_f32_16x16x32_bf16 v[32:35], v[210:213], v[176:179], v[32:35]
	v_mfma_f32_16x16x32_bf16 v[20:23], v[202:205], v[184:187], v[20:23]
	v_mfma_f32_16x16x32_bf16 v[16:19], v[210:213], v[184:187], v[16:19]
	v_mfma_f32_16x16x32_bf16 v[4:7], v[202:205], v[192:195], v[4:7]
	v_mfma_f32_16x16x32_bf16 v[0:3], v[210:213], v[192:195], v[0:3]
	v_mfma_f32_16x16x32_bf16 v[52:55], v[206:209], v[172:175], v[52:55]
	v_mfma_f32_16x16x32_bf16 v[48:51], v[214:217], v[172:175], v[48:51]
	v_mfma_f32_16x16x32_bf16 v[36:39], v[206:209], v[180:183], v[36:39]
	v_mfma_f32_16x16x32_bf16 v[32:35], v[214:217], v[180:183], v[32:35]
	v_mfma_f32_16x16x32_bf16 v[20:23], v[206:209], v[188:191], v[20:23]
	v_mfma_f32_16x16x32_bf16 v[16:19], v[214:217], v[188:191], v[16:19]
	v_mfma_f32_16x16x32_bf16 v[4:7], v[206:209], v[198:201], v[4:7]
	v_mfma_f32_16x16x32_bf16 v[0:3], v[214:217], v[198:201], v[0:3]
	s_setprio 0
	s_add_i32 s49, 0, 0x18000
	v_add_u32_e32 v164, s49, v148
	s_barrier
	ds_read_b128 v[152:155], v164
	ds_read_b128 v[156:159], v164 offset:1024
	ds_read_b128 v[160:163], v164 offset:2048
	ds_read_b128 v[164:167], v164 offset:3072
	s_add_u32 s14, s14, 0x80000
	s_addc_u32 s15, s15, 0
	s_mov_b32 m0, s25
	v_lshl_add_u64 v[202:203], s[14:15], 0, v[134:135]
	ds_read_b128 v[168:171], v150 offset:32768
	ds_read_b128 v[172:175], v150 offset:33792
	ds_read_b128 v[176:179], v150 offset:34816
	ds_read_b128 v[180:183], v150 offset:35840
	ds_read_b128 v[184:187], v150 offset:36864
	ds_read_b128 v[188:191], v150 offset:37888
	ds_read_b128 v[192:195], v150 offset:38912
	ds_read_b128 v[198:201], v150 offset:39936
	global_load_lds_dwordx4 v[202:203], off
	v_lshl_add_u64 v[202:203], s[14:15], 0, v[130:131]
	s_mov_b32 m0, s26
	s_nop 0
	global_load_lds_dwordx4 v[202:203], off
	s_waitcnt lgkmcnt(8)
	s_barrier
	s_setprio 1
	s_waitcnt lgkmcnt(7)
	v_mfma_f32_16x16x32_bf16 v[124:127], v[152:155], v[168:171], v[124:127]
	v_mfma_f32_16x16x32_bf16 v[120:123], v[160:163], v[168:171], v[120:123]
	s_waitcnt lgkmcnt(5)
	v_mfma_f32_16x16x32_bf16 v[108:111], v[152:155], v[176:179], v[108:111]
	v_mfma_f32_16x16x32_bf16 v[104:107], v[160:163], v[176:179], v[104:107]
	s_waitcnt lgkmcnt(3)
	v_mfma_f32_16x16x32_bf16 v[92:95], v[152:155], v[184:187], v[92:95]
	v_mfma_f32_16x16x32_bf16 v[88:91], v[160:163], v[184:187], v[88:91]
	s_waitcnt lgkmcnt(1)
	v_mfma_f32_16x16x32_bf16 v[76:79], v[152:155], v[192:195], v[76:79]
	v_mfma_f32_16x16x32_bf16 v[72:75], v[160:163], v[192:195], v[72:75]
	v_mfma_f32_16x16x32_bf16 v[124:127], v[156:159], v[172:175], v[124:127]
	v_mfma_f32_16x16x32_bf16 v[120:123], v[164:167], v[172:175], v[120:123]
	v_mfma_f32_16x16x32_bf16 v[108:111], v[156:159], v[180:183], v[108:111]
	v_mfma_f32_16x16x32_bf16 v[104:107], v[164:167], v[180:183], v[104:107]
	v_mfma_f32_16x16x32_bf16 v[92:95], v[156:159], v[188:191], v[92:95]
	v_mfma_f32_16x16x32_bf16 v[88:91], v[164:167], v[188:191], v[88:91]
	s_waitcnt lgkmcnt(0)
	v_mfma_f32_16x16x32_bf16 v[76:79], v[156:159], v[198:201], v[76:79]
	v_mfma_f32_16x16x32_bf16 v[72:75], v[164:167], v[198:201], v[72:75]
	s_setprio 0
	s_barrier
	s_add_i32 s14, 0, 0x1c000
	s_add_i32 s15, s49, s22
	v_add_u32_e32 v196, s14, v148
	v_lshl_add_u64 v[144:145], v[144:145], 0, s[42:43]
	s_mov_b32 m0, s15
	ds_read_b128 v[202:205], v196
	ds_read_b128 v[206:209], v196 offset:1024
	ds_read_b128 v[210:213], v196 offset:2048
	ds_read_b128 v[214:217], v196 offset:3072
	global_load_lds_dwordx4 v[144:145], off
	v_lshl_add_u64 v[144:145], v[218:219], 0, s[42:43]
	s_add_i32 m0, s15, 0x2000
	s_nop 0
	global_load_lds_dwordx4 v[144:145], off
	s_barrier
	s_setprio 1
	s_waitcnt lgkmcnt(3)
	v_mfma_f32_16x16x32_bf16 v[116:119], v[202:205], v[168:171], v[116:119]
	s_waitcnt lgkmcnt(1)
	v_mfma_f32_16x16x32_bf16 v[112:115], v[210:213], v[168:171], v[112:115]
	v_mfma_f32_16x16x32_bf16 v[100:103], v[202:205], v[176:179], v[100:103]
	v_mfma_f32_16x16x32_bf16 v[96:99], v[210:213], v[176:179], v[96:99]
	v_mfma_f32_16x16x32_bf16 v[84:87], v[202:205], v[184:187], v[84:87]
	v_mfma_f32_16x16x32_bf16 v[80:83], v[210:213], v[184:187], v[80:83]
	v_mfma_f32_16x16x32_bf16 v[68:71], v[202:205], v[192:195], v[68:71]
	v_mfma_f32_16x16x32_bf16 v[64:67], v[210:213], v[192:195], v[64:67]
	v_mfma_f32_16x16x32_bf16 v[116:119], v[206:209], v[172:175], v[116:119]
	s_waitcnt lgkmcnt(0)
	v_mfma_f32_16x16x32_bf16 v[112:115], v[214:217], v[172:175], v[112:115]
	v_mfma_f32_16x16x32_bf16 v[100:103], v[206:209], v[180:183], v[100:103]
	v_mfma_f32_16x16x32_bf16 v[96:99], v[214:217], v[180:183], v[96:99]
	v_mfma_f32_16x16x32_bf16 v[84:87], v[206:209], v[188:191], v[84:87]
	v_mfma_f32_16x16x32_bf16 v[80:83], v[214:217], v[188:191], v[80:83]
	v_mfma_f32_16x16x32_bf16 v[68:71], v[206:209], v[198:201], v[68:71]
	v_mfma_f32_16x16x32_bf16 v[64:67], v[214:217], v[198:201], v[64:67]
	s_setprio 0
	s_mov_b32 m0, s30
	v_lshl_add_u64 v[144:145], v[220:221], 0, s[42:43]
	s_barrier
; #define PG8_STAGE(bufoff, gbase, voff) do { _Pragma("unroll") for (int _i = 0; _i < 2; ++_i) \
;         __builtin_amdgcn_global_load_lds((const unsigned*)((const char*)(gbase) + (voff)[_i]), (LAS unsigned*)(lds + (bufoff) + ldsw + _i * 8192), 16, 0, 0); } while (0)
; #define PG8_LDA(dst, b, h) do { _Pragma("unroll") for (int m = 0; m < 4; ++m) _Pragma("unroll") for (int k = 0; k < 2; ++k) dst[m][k] = *(const LAS bf16x8*)(lds + PG8_SA(b, h) + aoff + m * 2048 + k * 1024); } while (0)
; #define PG8_MMA(ai, bj, At, Bt) do { __builtin_amdgcn_s_setprio(1); _Pragma("unroll") for (int m = 0; m < 4; ++m) _Pragma("unroll") for (int n = 0; n < 2; ++n) _Pragma("unroll") for (int k = 0; k < 2; ++k) \
;         acc[ai][bj][m][n] = __builtin_amdgcn_mfma_f32_16x16x32_bf16(Bt[n][k], At[m][k], acc[ai][bj][m][n], 0, 0, 0); __builtin_amdgcn_s_setprio(0); } while (0)
; #define PG8_WAIT_V(n) asm volatile("s_waitcnt vmcnt(" #n ")" ::: "memory")
; #define PG8_WAIT_L(n) asm volatile("s_waitcnt lgkmcnt(" #n ")" ::: "memory")
; #define PG8_BAR __builtin_amdgcn_s_barrier()
;     DI void operator()(const f32x4 (&acc)[2][2][4][2], const Unit& u, int wr, int wc, int fr, int fq) const {
;         const int row0 = u.pm * BM + wr * 64 + fr, col0 = u.pn * BM + wc * 32 + 8 * fq;
;         f32x4 sc[2][2];
; #pragma unroll
;         for (int bj = 0; bj < 2; ++bj)
; #pragma unroll
;             for (int n = 0; n < 2; ++n) sc[bj][n] = scale ? *(const f32x4*)(scale + col0 + bj * HALF + 4 * n) : (f32x4){1.f, 1.f, 1.f, 1.f};
; #pragma unroll
;         for (int ai = 0; ai < 2; ++ai)
; #pragma unroll
;             for (int m = 0; m < 4; ++m) { const size_t ro = (size_t)(row0 + ai * HALF + m * 16) * D + col0;
; #pragma unroll
;                 for (int bj = 0; bj < 2; ++bj) {
;                     f32x4 x0, x1;
;                     if constexpr (IB) { const u32x4 w = *(const u32x4*)((const bf16_t*)Xin + ro + bj * HALF);
; template <class Map, class Epi>
; DI void gemm_phase(LAS unsigned char* lds, const Map& MP, const Epi& E, const int nM, const int nN, const int K, const int lda, const int ldb) {
;     ...
;             PG8_LDA(At, 1, 1); PG8_STAGE(PG8_SA(1, 0), a3, voffA);
;             PG8_BAR; PG8_WAIT_L(0); PG8_MMA(1, 0, At, B0); PG8_BAR; PG8_SCHED;
;             PG8_STAGE(PG8_SB(1, 1), b3 + hstepB, voffB);
;             PG8_WAIT_V(6); PG8_BAR; PG8_MMA(1, 1, At, B1); PG8_BAR;
	ds_read_b128 v[168:171], v150 offset:49152
	ds_read_b128 v[172:175], v150 offset:50176
	ds_read_b128 v[176:179], v150 offset:51200
	ds_read_b128 v[180:183], v150 offset:52224
	ds_read_b128 v[184:187], v150 offset:53248
	ds_read_b128 v[188:191], v150 offset:54272
	ds_read_b128 v[192:195], v150 offset:55296
	ds_read_b128 v[198:201], v150 offset:56320
	global_load_lds_dwordx4 v[144:145], off
	v_lshl_add_u64 v[144:145], v[222:223], 0, s[42:43]
	s_mov_b32 m0, s31
	s_nop 0
	global_load_lds_dwordx4 v[144:145], off
	s_barrier
	s_setprio 1
	s_waitcnt lgkmcnt(7)
	v_mfma_f32_16x16x32_bf16 v[60:63], v[152:155], v[168:171], v[60:63]
	v_mfma_f32_16x16x32_bf16 v[56:59], v[160:163], v[168:171], v[56:59]
	s_waitcnt lgkmcnt(5)
	v_mfma_f32_16x16x32_bf16 v[44:47], v[152:155], v[176:179], v[44:47]
	v_mfma_f32_16x16x32_bf16 v[40:43], v[160:163], v[176:179], v[40:43]
	s_waitcnt lgkmcnt(3)
	v_mfma_f32_16x16x32_bf16 v[28:31], v[152:155], v[184:187], v[28:31]
	v_mfma_f32_16x16x32_bf16 v[24:27], v[160:163], v[184:187], v[24:27]
	s_waitcnt lgkmcnt(1)
	v_mfma_f32_16x16x32_bf16 v[12:15], v[152:155], v[192:195], v[12:15]
	v_mfma_f32_16x16x32_bf16 v[8:11], v[160:163], v[192:195], v[8:11]
	v_mfma_f32_16x16x32_bf16 v[60:63], v[156:159], v[172:175], v[60:63]
	v_mfma_f32_16x16x32_bf16 v[56:59], v[164:167], v[172:175], v[56:59]
	v_mfma_f32_16x16x32_bf16 v[44:47], v[156:159], v[180:183], v[44:47]
	v_mfma_f32_16x16x32_bf16 v[40:43], v[164:167], v[180:183], v[40:43]
	v_mfma_f32_16x16x32_bf16 v[28:31], v[156:159], v[188:191], v[28:31]
	v_mfma_f32_16x16x32_bf16 v[24:27], v[164:167], v[188:191], v[24:27]
	s_waitcnt lgkmcnt(0)
	v_mfma_f32_16x16x32_bf16 v[12:15], v[156:159], v[198:201], v[12:15]
	v_mfma_f32_16x16x32_bf16 v[8:11], v[164:167], v[198:201], v[8:11]
	s_setprio 0
	s_barrier
	s_add_u32 s12, s12, 0x80080
	s_addc_u32 s13, s13, 0
	s_add_i32 s14, s14, s22
	v_lshl_add_u64 v[144:145], s[12:13], 0, v[132:133]
	s_mov_b32 m0, s14
	s_nop 0
	global_load_lds_dwordx4 v[144:145], off
	v_lshl_add_u64 v[144:145], s[12:13], 0, v[128:129]
	s_add_i32 m0, s14, 0x2000
	s_nop 0
	global_load_lds_dwordx4 v[144:145], off
	s_waitcnt vmcnt(6)
	s_barrier
	s_setprio 1
	v_mfma_f32_16x16x32_bf16 v[52:55], v[202:205], v[168:171], v[52:55]
	v_mfma_f32_16x16x32_bf16 v[48:51], v[210:213], v[168:171], v[48:51]
	v_mfma_f32_16x16x32_bf16 v[36:39], v[202:205], v[176:179], v[36:39]
	v_mfma_f32_16x16x32_bf16 v[32:35], v[210:213], v[176:179], v[32:35]
	v_mfma_f32_16x16x32_bf16 v[20:23], v[202:205], v[184:187], v[20:23]
	v_mfma_f32_16x16x32_bf16 v[16:19], v[210:213], v[184:187], v[16:19]
	v_mfma_f32_16x16x32_bf16 v[4:7], v[202:205], v[192:195], v[4:7]
	v_mfma_f32_16x16x32_bf16 v[0:3], v[210:213], v[192:195], v[0:3]
	v_mfma_f32_16x16x32_bf16 v[52:55], v[206:209], v[172:175], v[52:55]
	v_mfma_f32_16x16x32_bf16 v[48:51], v[214:217], v[172:175], v[48:51]
	v_mfma_f32_16x16x32_bf16 v[36:39], v[206:209], v[180:183], v[36:39]
	v_mfma_f32_16x16x32_bf16 v[32:35], v[214:217], v[180:183], v[32:35]
	v_mfma_f32_16x16x32_bf16 v[20:23], v[206:209], v[188:191], v[20:23]
	v_mfma_f32_16x16x32_bf16 v[16:19], v[214:217], v[188:191], v[16:19]
	v_mfma_f32_16x16x32_bf16 v[4:7], v[206:209], v[198:201], v[4:7]
	v_mfma_f32_16x16x32_bf16 v[0:3], v[214:217], v[198:201], v[0:3]
	s_setprio 0
	s_add_i32 s3, s3, 2
	s_add_u32 s47, s47, 0x100
	s_addc_u32 s48, s48, 0
	s_add_u32 s10, s10, 0x100
	s_addc_u32 s11, s11, 0
	s_cmp_gt_u32 s3, 29
	s_barrier
	s_cbranch_scc0 .LBB1_1764
	v_mov_b32_e32 v152, v147
	v_mov_b32_e32 v144, v146
	s_lshl_b32 s2, s2, 8
	s_or_b32 s2, s2, s29
	v_lshl_add_u32 v144, v144, 3, s2
	s_lshl_b32 s2, s8, 8
	s_add_i32 s2, s2, s28
	v_add_u32_e32 v152, s2, v152
	v_ashrrev_i32_e32 v153, 31, v152
	v_lshlrev_b64 v[152:153], 12, v[152:153]
	v_ashrrev_i32_e32 v145, 31, v144
	v_lshl_add_u64 v[152:153], s[4:5], 0, v[152:153]
	v_lshl_add_u64 v[144:145], v[144:145], 1, v[152:153]
	global_load_dwordx4 v[160:163], v[144:145], off
	global_load_dwordx4 v[164:167], v[144:145], off offset:256
	s_mov_b64 s[98:99], 0x10000
	v_lshl_add_u64 v[154:155], v[144:145], 0, s[98:99]
	global_load_dwordx4 v[168:171], v[154:155], off
	global_load_dwordx4 v[172:175], v[154:155], off offset:256
	s_mov_b64 s[98:99], 0x20000
	v_lshl_add_u64 v[154:155], v[144:145], 0, s[98:99]
	global_load_dwordx4 v[176:179], v[154:155], off
	global_load_dwordx4 v[180:183], v[154:155], off offset:256
	s_mov_b64 s[98:99], 0x30000
	v_lshl_add_u64 v[154:155], v[144:145], 0, s[98:99]
	global_load_dwordx4 v[184:187], v[154:155], off
	global_load_dwordx4 v[188:191], v[154:155], off offset:256
	s_mov_b64 s[98:99], 0x80000
	v_lshl_add_u64 v[154:155], v[144:145], 0, s[98:99]
	global_load_dwordx4 v[192:195], v[154:155], off
	global_load_dwordx4 v[198:201], v[154:155], off offset:256
	s_mov_b64 s[98:99], 0x90000
	v_lshl_add_u64 v[154:155], v[144:145], 0, s[98:99]
	global_load_dwordx4 v[202:205], v[154:155], off
	global_load_dwordx4 v[206:209], v[154:155], off offset:256
	s_mov_b64 s[98:99], 0xa0000
	v_lshl_add_u64 v[154:155], v[144:145], 0, s[98:99]
	global_load_dwordx4 v[210:213], v[154:155], off
	global_load_dwordx4 v[214:217], v[154:155], off offset:256
	s_mov_b64 s[98:99], 0xb0000
	v_lshl_add_u64 v[154:155], v[144:145], 0, s[98:99]
	global_load_dwordx4 v[248:251], v[154:155], off
	global_load_dwordx4 v[252:255], v[154:155], off offset:256
	s_waitcnt vmcnt(15)
	s_nop 1
	v_mov_b32_e32 v152, v160
	v_mov_b32_e32 v153, v161
	v_mov_b32_e32 v154, v162
	v_mov_b32_e32 v155, v163
	s_mov_b64 s[2:3], 0x10000
	s_mov_b32 s8, s46
	s_mov_b64 s[10:11], s[6:7]
	s_mov_b64 s[12:13], s[52:53]
	s_waitcnt lgkmcnt(0)
; DI unsigned pack2(float a, float b) { f32x2 v = {a, b}; hwbf16x2 r = __builtin_convertvector(v, hwbf16x2); return __builtin_bit_cast(unsigned, r); }
; DI float bflo(unsigned w) { return __uint_as_float(w << 16); }
; DI float bfhi(unsigned w) { return __uint_as_float(w & 0xffff0000u); }
;     DI void operator()(const f32x4 (&acc)[2][2][4][2], const Unit& u, int wr, int wc, int fr, int fq) const {
;     ...
;             for (int m = 0; m < 4; ++m) { const size_t ro = (size_t)(row0 + ai * HALF + m * 16) * D + col0;
; #pragma unroll
;                 for (int bj = 0; bj < 2; ++bj) {
;                     f32x4 x0, x1;
;                     if constexpr (IB) { const u32x4 w = *(const u32x4*)((const bf16_t*)Xin + ro + bj * HALF);
;                         x0 = (f32x4){bflo(w[0]), bfhi(w[0]), bflo(w[1]), bfhi(w[1])}; x1 = (f32x4){bflo(w[2]), bfhi(w[2]), bflo(w[3]), bfhi(w[3])}; }
;                     else { x0 = *(const f32x4*)((const float*)Xin + ro + bj * HALF); x1 = *(const f32x4*)((const float*)Xin + ro + bj * HALF + 4); }
;                     x0 += acc[ai][bj][m][0] * sc[bj][0]; x1 += acc[ai][bj][m][1] * sc[bj][1];
;                     if constexpr (OB) { u32x4 o; o[0] = pack2(x0[0], x0[1]); o[1] = pack2(x0[2], x0[3]); o[2] = pack2(x1[0], x1[1]); o[3] = pack2(x1[2], x1[3]);
;                         *(u32x4*)((bf16_t*)Xout + ro + bj * HALF) = o; }
;                     else { *(f32x4*)((float*)Xout + ro + bj * HALF) = x0; *(f32x4*)((float*)Xout + ro + bj * HALF + 4) = x1; } } }
	v_lshlrev_b32_e32 v156, 16, v152
	v_and_b32_e32 v157, 0xffff0000, v152
	v_lshlrev_b32_e32 v152, 16, v153
	v_and_b32_e32 v153, 0xffff0000, v153
	v_lshlrev_b32_e32 v158, 16, v154
	v_and_b32_e32 v159, 0xffff0000, v154
	v_lshlrev_b32_e32 v154, 16, v155
	v_and_b32_e32 v155, 0xffff0000, v155
	v_pk_add_f32 v[126:127], v[126:127], v[152:153]
	v_pk_add_f32 v[124:125], v[124:125], v[156:157]
	v_pk_add_f32 v[152:153], v[122:123], v[154:155]
	v_pk_add_f32 v[122:123], v[120:121], v[158:159]
	v_cvt_pk_bf16_f32 v120, v124, v125
	v_cvt_pk_bf16_f32 v121, v126, v127
	v_cvt_pk_bf16_f32 v122, v122, v123
	v_cvt_pk_bf16_f32 v123, v152, v153
	global_store_dwordx4 v[144:145], v[120:123], off
	s_waitcnt vmcnt(15)
	s_nop 1
	v_mov_b32_e32 v120, v164
	v_mov_b32_e32 v121, v165
	v_mov_b32_e32 v122, v166
	v_mov_b32_e32 v123, v167
	s_waitcnt lgkmcnt(0)
	v_lshlrev_b32_e32 v124, 16, v120
	v_and_b32_e32 v125, 0xffff0000, v120
	v_lshlrev_b32_e32 v120, 16, v121
	v_and_b32_e32 v121, 0xffff0000, v121
	v_lshlrev_b32_e32 v126, 16, v122
	v_and_b32_e32 v127, 0xffff0000, v122
	v_lshlrev_b32_e32 v122, 16, v123
	v_and_b32_e32 v123, 0xffff0000, v123
	v_pk_add_f32 v[116:117], v[116:117], v[124:125]
	v_pk_add_f32 v[118:119], v[118:119], v[120:121]
	v_pk_add_f32 v[120:121], v[114:115], v[122:123]
	v_pk_add_f32 v[114:115], v[112:113], v[126:127]
	v_cvt_pk_bf16_f32 v112, v116, v117
	v_lshl_add_u64 v[116:117], v[144:145], 0, s[2:3]
	s_mov_b32 s2, 0x10000
	v_cvt_pk_bf16_f32 v113, v118, v119
	v_add_co_u32_e32 v118, vcc, s2, v144
	v_cvt_pk_bf16_f32 v114, v114, v115
	v_cvt_pk_bf16_f32 v115, v120, v121
	v_addc_co_u32_e32 v119, vcc, 0, v145, vcc
	global_store_dwordx4 v[144:145], v[112:115], off offset:256
	s_waitcnt vmcnt(15)
	s_nop 1
	v_mov_b32_e32 v112, v168
	v_mov_b32_e32 v113, v169
	v_mov_b32_e32 v114, v170
	v_mov_b32_e32 v115, v171
	s_mov_b64 s[2:3], 0x20000
	s_waitcnt lgkmcnt(0)
	v_lshlrev_b32_e32 v120, 16, v112
	v_and_b32_e32 v121, 0xffff0000, v112
	v_lshlrev_b32_e32 v112, 16, v113
	v_and_b32_e32 v113, 0xffff0000, v113
	v_lshlrev_b32_e32 v122, 16, v114
	v_and_b32_e32 v123, 0xffff0000, v114
	v_lshlrev_b32_e32 v114, 16, v115
	v_and_b32_e32 v115, 0xffff0000, v115
	v_pk_add_f32 v[110:111], v[110:111], v[112:113]
	v_pk_add_f32 v[108:109], v[108:109], v[120:121]
	v_pk_add_f32 v[112:113], v[106:107], v[114:115]
	v_pk_add_f32 v[106:107], v[104:105], v[122:123]
	v_cvt_pk_bf16_f32 v104, v108, v109
	v_cvt_pk_bf16_f32 v105, v110, v111
	v_cvt_pk_bf16_f32 v106, v106, v107
	v_cvt_pk_bf16_f32 v107, v112, v113
	global_store_dwordx4 v[118:119], v[104:107], off
	s_waitcnt vmcnt(15)
	s_nop 1
	v_mov_b32_e32 v104, v172
	v_mov_b32_e32 v105, v173
	v_mov_b32_e32 v106, v174
	v_mov_b32_e32 v107, v175
	s_waitcnt lgkmcnt(0)
	v_lshlrev_b32_e32 v108, 16, v104
	v_and_b32_e32 v109, 0xffff0000, v104
	v_lshlrev_b32_e32 v104, 16, v105
	v_and_b32_e32 v105, 0xffff0000, v105
	v_lshlrev_b32_e32 v110, 16, v106
	v_and_b32_e32 v111, 0xffff0000, v106
	v_lshlrev_b32_e32 v106, 16, v107
	v_and_b32_e32 v107, 0xffff0000, v107
	v_pk_add_f32 v[100:101], v[100:101], v[108:109]
	v_pk_add_f32 v[102:103], v[102:103], v[104:105]
	v_pk_add_f32 v[104:105], v[98:99], v[106:107]
	v_pk_add_f32 v[98:99], v[96:97], v[110:111]
	v_cvt_pk_bf16_f32 v96, v100, v101
	v_lshl_add_u64 v[100:101], v[144:145], 0, s[2:3]
	s_mov_b32 s2, 0x20000
	v_cvt_pk_bf16_f32 v97, v102, v103
	v_add_co_u32_e32 v102, vcc, s2, v144
	v_cvt_pk_bf16_f32 v98, v98, v99
	v_cvt_pk_bf16_f32 v99, v104, v105
	v_addc_co_u32_e32 v103, vcc, 0, v145, vcc
	global_store_dwordx4 v[116:117], v[96:99], off offset:256
	s_waitcnt vmcnt(15)
	s_nop 1
	v_mov_b32_e32 v96, v176
	v_mov_b32_e32 v97, v177
	v_mov_b32_e32 v98, v178
	v_mov_b32_e32 v99, v179
	s_mov_b64 s[2:3], 0x30000
	s_waitcnt lgkmcnt(0)
	v_lshlrev_b32_e32 v104, 16, v96
	v_and_b32_e32 v105, 0xffff0000, v96
	v_lshlrev_b32_e32 v96, 16, v97
	v_and_b32_e32 v97, 0xffff0000, v97
	v_lshlrev_b32_e32 v106, 16, v98
	v_and_b32_e32 v107, 0xffff0000, v98
	v_lshlrev_b32_e32 v98, 16, v99
	v_and_b32_e32 v99, 0xffff0000, v99
	v_pk_add_f32 v[94:95], v[94:95], v[96:97]
	v_pk_add_f32 v[92:93], v[92:93], v[104:105]
	v_pk_add_f32 v[96:97], v[90:91], v[98:99]
	v_pk_add_f32 v[90:91], v[88:89], v[106:107]
	v_cvt_pk_bf16_f32 v88, v92, v93
	v_cvt_pk_bf16_f32 v89, v94, v95
	v_cvt_pk_bf16_f32 v90, v90, v91
	v_cvt_pk_bf16_f32 v91, v96, v97
	global_store_dwordx4 v[102:103], v[88:91], off
	s_waitcnt vmcnt(15)
	s_nop 1
	v_mov_b32_e32 v88, v180
	v_mov_b32_e32 v89, v181
	v_mov_b32_e32 v90, v182
	v_mov_b32_e32 v91, v183
	s_waitcnt lgkmcnt(0)
	v_lshlrev_b32_e32 v92, 16, v88
	v_and_b32_e32 v93, 0xffff0000, v88
	v_lshlrev_b32_e32 v88, 16, v89
	v_and_b32_e32 v89, 0xffff0000, v89
	v_lshlrev_b32_e32 v94, 16, v90
	v_and_b32_e32 v95, 0xffff0000, v90
	v_lshlrev_b32_e32 v90, 16, v91
	v_and_b32_e32 v91, 0xffff0000, v91
	v_pk_add_f32 v[86:87], v[86:87], v[88:89]
	v_pk_add_f32 v[84:85], v[84:85], v[92:93]
	v_pk_add_f32 v[88:89], v[82:83], v[90:91]
	v_pk_add_f32 v[82:83], v[80:81], v[94:95]
	v_cvt_pk_bf16_f32 v80, v84, v85
	v_cvt_pk_bf16_f32 v81, v86, v87
	v_cvt_pk_bf16_f32 v82, v82, v83
	v_cvt_pk_bf16_f32 v83, v88, v89
	global_store_dwordx4 v[100:101], v[80:83], off offset:256
	s_nop 1
	v_lshl_add_u64 v[80:81], v[144:145], 0, s[2:3]
	s_mov_b32 s2, 0x30000
	v_add_co_u32_e32 v86, vcc, s2, v144
	s_mov_b64 s[2:3], 0x80000
	s_nop 0
	v_addc_co_u32_e32 v87, vcc, 0, v145, vcc
	s_waitcnt vmcnt(15)
	s_nop 1
	v_mov_b32_e32 v82, v184
	v_mov_b32_e32 v83, v185
	v_mov_b32_e32 v84, v186
	v_mov_b32_e32 v85, v187
	s_waitcnt lgkmcnt(0)
; DI unsigned pack2(float a, float b) { f32x2 v = {a, b}; hwbf16x2 r = __builtin_convertvector(v, hwbf16x2); return __builtin_bit_cast(unsigned, r); }
; DI float bflo(unsigned w) { return __uint_as_float(w << 16); }
; DI float bfhi(unsigned w) { return __uint_as_float(w & 0xffff0000u); }
;     DI void operator()(const f32x4 (&acc)[2][2][4][2], const Unit& u, int wr, int wc, int fr, int fq) const {
;     ...
;             for (int m = 0; m < 4; ++m) { const size_t ro = (size_t)(row0 + ai * HALF + m * 16) * D + col0;
; #pragma unroll
;                 for (int bj = 0; bj < 2; ++bj) {
;                     f32x4 x0, x1;
;                     if constexpr (IB) { const u32x4 w = *(const u32x4*)((const bf16_t*)Xin + ro + bj * HALF);
;                         x0 = (f32x4){bflo(w[0]), bfhi(w[0]), bflo(w[1]), bfhi(w[1])}; x1 = (f32x4){bflo(w[2]), bfhi(w[2]), bflo(w[3]), bfhi(w[3])}; }
;                     else { x0 = *(const f32x4*)((const float*)Xin + ro + bj * HALF); x1 = *(const f32x4*)((const float*)Xin + ro + bj * HALF + 4); }
;                     x0 += acc[ai][bj][m][0] * sc[bj][0]; x1 += acc[ai][bj][m][1] * sc[bj][1];
;                     if constexpr (OB) { u32x4 o; o[0] = pack2(x0[0], x0[1]); o[1] = pack2(x0[2], x0[3]); o[2] = pack2(x1[0], x1[1]); o[3] = pack2(x1[2], x1[3]);
;                         *(u32x4*)((bf16_t*)Xout + ro + bj * HALF) = o; }
;                     else { *(f32x4*)((float*)Xout + ro + bj * HALF) = x0; *(f32x4*)((float*)Xout + ro + bj * HALF + 4) = x1; } } }
	v_lshlrev_b32_e32 v88, 16, v82
	v_and_b32_e32 v89, 0xffff0000, v82
	v_lshlrev_b32_e32 v82, 16, v83
	v_and_b32_e32 v83, 0xffff0000, v83
	v_lshlrev_b32_e32 v90, 16, v84
	v_and_b32_e32 v91, 0xffff0000, v84
	v_lshlrev_b32_e32 v84, 16, v85
	v_and_b32_e32 v85, 0xffff0000, v85
	v_pk_add_f32 v[78:79], v[78:79], v[82:83]
	v_pk_add_f32 v[76:77], v[76:77], v[88:89]
	v_pk_add_f32 v[82:83], v[74:75], v[84:85]
	v_pk_add_f32 v[74:75], v[72:73], v[90:91]
	v_cvt_pk_bf16_f32 v72, v76, v77
	v_cvt_pk_bf16_f32 v73, v78, v79
	v_cvt_pk_bf16_f32 v74, v74, v75
	v_cvt_pk_bf16_f32 v75, v82, v83
	global_store_dwordx4 v[86:87], v[72:75], off
	s_waitcnt vmcnt(15)
	s_nop 1
	v_mov_b32_e32 v72, v188
	v_mov_b32_e32 v73, v189
	v_mov_b32_e32 v74, v190
	v_mov_b32_e32 v75, v191
	s_waitcnt lgkmcnt(0)
	v_lshlrev_b32_e32 v76, 16, v72
	v_and_b32_e32 v77, 0xffff0000, v72
	v_lshlrev_b32_e32 v72, 16, v73
	v_and_b32_e32 v73, 0xffff0000, v73
	v_lshlrev_b32_e32 v78, 16, v74
	v_and_b32_e32 v79, 0xffff0000, v74
	v_lshlrev_b32_e32 v74, 16, v75
	v_and_b32_e32 v75, 0xffff0000, v75
	v_pk_add_f32 v[70:71], v[70:71], v[72:73]
	v_pk_add_f32 v[68:69], v[68:69], v[76:77]
	v_pk_add_f32 v[72:73], v[66:67], v[74:75]
	v_pk_add_f32 v[66:67], v[64:65], v[78:79]
	v_cvt_pk_bf16_f32 v64, v68, v69
	v_cvt_pk_bf16_f32 v65, v70, v71
	v_cvt_pk_bf16_f32 v66, v66, v67
	v_cvt_pk_bf16_f32 v67, v72, v73
	global_store_dwordx4 v[80:81], v[64:67], off offset:256
	s_nop 1
	v_lshl_add_u64 v[64:65], v[144:145], 0, s[2:3]
	s_mov_b32 s2, 0x80000
	v_add_co_u32_e32 v70, vcc, s2, v144
	s_mov_b64 s[2:3], 0x90000
	s_nop 0
	v_addc_co_u32_e32 v71, vcc, 0, v145, vcc
	s_waitcnt vmcnt(15)
	s_nop 1
	v_mov_b32_e32 v66, v192
	v_mov_b32_e32 v67, v193
	v_mov_b32_e32 v68, v194
	v_mov_b32_e32 v69, v195
	s_waitcnt lgkmcnt(0)
	v_lshlrev_b32_e32 v72, 16, v66
	v_and_b32_e32 v73, 0xffff0000, v66
	v_lshlrev_b32_e32 v66, 16, v67
	v_and_b32_e32 v67, 0xffff0000, v67
	v_lshlrev_b32_e32 v74, 16, v68
	v_and_b32_e32 v75, 0xffff0000, v68
	v_lshlrev_b32_e32 v68, 16, v69
	v_and_b32_e32 v69, 0xffff0000, v69
	v_pk_add_f32 v[62:63], v[62:63], v[66:67]
	v_pk_add_f32 v[60:61], v[60:61], v[72:73]
	v_pk_add_f32 v[66:67], v[58:59], v[68:69]
	v_pk_add_f32 v[58:59], v[56:57], v[74:75]
	v_cvt_pk_bf16_f32 v56, v60, v61
	v_cvt_pk_bf16_f32 v57, v62, v63
	v_cvt_pk_bf16_f32 v58, v58, v59
	v_cvt_pk_bf16_f32 v59, v66, v67
	global_store_dwordx4 v[70:71], v[56:59], off
	s_waitcnt vmcnt(15)
	s_nop 1
	v_mov_b32_e32 v56, v198
	v_mov_b32_e32 v57, v199
	v_mov_b32_e32 v58, v200
	v_mov_b32_e32 v59, v201
	s_waitcnt lgkmcnt(0)
	v_lshlrev_b32_e32 v60, 16, v56
	v_and_b32_e32 v61, 0xffff0000, v56
	v_lshlrev_b32_e32 v56, 16, v57
	v_and_b32_e32 v57, 0xffff0000, v57
	v_lshlrev_b32_e32 v62, 16, v58
	v_and_b32_e32 v63, 0xffff0000, v58
	v_lshlrev_b32_e32 v58, 16, v59
	v_and_b32_e32 v59, 0xffff0000, v59
	v_pk_add_f32 v[54:55], v[54:55], v[56:57]
	v_pk_add_f32 v[52:53], v[52:53], v[60:61]
	v_pk_add_f32 v[56:57], v[50:51], v[58:59]
	v_pk_add_f32 v[50:51], v[48:49], v[62:63]
	v_cvt_pk_bf16_f32 v48, v52, v53
	v_cvt_pk_bf16_f32 v49, v54, v55
	v_cvt_pk_bf16_f32 v50, v50, v51
	v_cvt_pk_bf16_f32 v51, v56, v57
	global_store_dwordx4 v[64:65], v[48:51], off offset:256
	s_nop 1
	v_lshl_add_u64 v[48:49], v[144:145], 0, s[2:3]
	s_mov_b32 s2, 0x90000
	v_add_co_u32_e32 v54, vcc, s2, v144
	s_mov_b64 s[2:3], 0xa0000
	s_nop 0
	v_addc_co_u32_e32 v55, vcc, 0, v145, vcc
	s_waitcnt vmcnt(15)
	s_nop 1
	v_mov_b32_e32 v50, v202
	v_mov_b32_e32 v51, v203
	v_mov_b32_e32 v52, v204
	v_mov_b32_e32 v53, v205
	s_waitcnt lgkmcnt(0)
	v_lshlrev_b32_e32 v56, 16, v50
	v_and_b32_e32 v57, 0xffff0000, v50
	v_lshlrev_b32_e32 v50, 16, v51
	v_and_b32_e32 v51, 0xffff0000, v51
	v_lshlrev_b32_e32 v58, 16, v52
	v_and_b32_e32 v59, 0xffff0000, v52
	v_lshlrev_b32_e32 v52, 16, v53
	v_and_b32_e32 v53, 0xffff0000, v53
	v_pk_add_f32 v[46:47], v[46:47], v[50:51]
	v_pk_add_f32 v[44:45], v[44:45], v[56:57]
	v_pk_add_f32 v[50:51], v[42:43], v[52:53]
	v_pk_add_f32 v[42:43], v[40:41], v[58:59]
	v_cvt_pk_bf16_f32 v40, v44, v45
	v_cvt_pk_bf16_f32 v41, v46, v47
	v_cvt_pk_bf16_f32 v42, v42, v43
	v_cvt_pk_bf16_f32 v43, v50, v51
	global_store_dwordx4 v[54:55], v[40:43], off
	s_waitcnt vmcnt(15)
	s_nop 1
	v_mov_b32_e32 v40, v206
	v_mov_b32_e32 v41, v207
	v_mov_b32_e32 v42, v208
	v_mov_b32_e32 v43, v209
	s_waitcnt lgkmcnt(0)
; DI unsigned pack2(float a, float b) { f32x2 v = {a, b}; hwbf16x2 r = __builtin_convertvector(v, hwbf16x2); return __builtin_bit_cast(unsigned, r); }
; DI float bflo(unsigned w) { return __uint_as_float(w << 16); }
; DI float bfhi(unsigned w) { return __uint_as_float(w & 0xffff0000u); }
; #define PG8_WAIT_V(n) asm volatile("s_waitcnt vmcnt(" #n ")" ::: "memory")
; #define PG8_BAR __builtin_amdgcn_s_barrier()
;     DI void operator()(const f32x4 (&acc)[2][2][4][2], const Unit& u, int wr, int wc, int fr, int fq) const {
;     ...
;             for (int m = 0; m < 4; ++m) { const size_t ro = (size_t)(row0 + ai * HALF + m * 16) * D + col0;
; #pragma unroll
;                 for (int bj = 0; bj < 2; ++bj) {
;                     f32x4 x0, x1;
;                     if constexpr (IB) { const u32x4 w = *(const u32x4*)((const bf16_t*)Xin + ro + bj * HALF);
;                         x0 = (f32x4){bflo(w[0]), bfhi(w[0]), bflo(w[1]), bfhi(w[1])}; x1 = (f32x4){bflo(w[2]), bfhi(w[2]), bflo(w[3]), bfhi(w[3])}; }
;                     else { x0 = *(const f32x4*)((const float*)Xin + ro + bj * HALF); x1 = *(const f32x4*)((const float*)Xin + ro + bj * HALF + 4); }
;                     x0 += acc[ai][bj][m][0] * sc[bj][0]; x1 += acc[ai][bj][m][1] * sc[bj][1];
;                     if constexpr (OB) { u32x4 o; o[0] = pack2(x0[0], x0[1]); o[1] = pack2(x0[2], x0[3]); o[2] = pack2(x1[0], x1[1]); o[3] = pack2(x1[2], x1[3]);
;                         *(u32x4*)((bf16_t*)Xout + ro + bj * HALF) = o; }
;                     else { *(f32x4*)((float*)Xout + ro + bj * HALF) = x0; *(f32x4*)((float*)Xout + ro + bj * HALF + 4) = x1; } } }
; template <class Map, class Epi>
; DI void gemm_phase(LAS unsigned char* lds, const Map& MP, const Epi& E, const int nM, const int nN, const int K, const int lda, const int ldb) {
;     ...
;         if (!has_next) break;
;     ...
;     PG8_WAIT_V(0);
;     if (wr == 0) PG8_BAR;
;     PG8_BAR;
	v_lshlrev_b32_e32 v44, 16, v40
	v_and_b32_e32 v45, 0xffff0000, v40
	v_lshlrev_b32_e32 v40, 16, v41
	v_and_b32_e32 v41, 0xffff0000, v41
	v_lshlrev_b32_e32 v46, 16, v42
	v_and_b32_e32 v47, 0xffff0000, v42
	v_lshlrev_b32_e32 v42, 16, v43
	v_and_b32_e32 v43, 0xffff0000, v43
	v_pk_add_f32 v[38:39], v[38:39], v[40:41]
	v_pk_add_f32 v[36:37], v[36:37], v[44:45]
	v_pk_add_f32 v[40:41], v[34:35], v[42:43]
	v_pk_add_f32 v[34:35], v[32:33], v[46:47]
	v_cvt_pk_bf16_f32 v32, v36, v37
	v_cvt_pk_bf16_f32 v33, v38, v39
	v_cvt_pk_bf16_f32 v34, v34, v35
	v_cvt_pk_bf16_f32 v35, v40, v41
	global_store_dwordx4 v[48:49], v[32:35], off offset:256
	s_nop 1
	v_lshl_add_u64 v[32:33], v[144:145], 0, s[2:3]
	s_mov_b32 s2, 0xa0000
	v_add_co_u32_e32 v38, vcc, s2, v144
	s_mov_b64 s[2:3], 0xb0000
	s_nop 0
	v_addc_co_u32_e32 v39, vcc, 0, v145, vcc
	s_waitcnt vmcnt(15)
	s_nop 1
	v_mov_b32_e32 v34, v210
	v_mov_b32_e32 v35, v211
	v_mov_b32_e32 v36, v212
	v_mov_b32_e32 v37, v213
	s_waitcnt lgkmcnt(0)
	v_lshlrev_b32_e32 v40, 16, v34
	v_and_b32_e32 v41, 0xffff0000, v34
	v_lshlrev_b32_e32 v34, 16, v35
	v_and_b32_e32 v35, 0xffff0000, v35
	v_lshlrev_b32_e32 v42, 16, v36
	v_and_b32_e32 v43, 0xffff0000, v36
	v_lshlrev_b32_e32 v36, 16, v37
	v_and_b32_e32 v37, 0xffff0000, v37
	v_pk_add_f32 v[30:31], v[30:31], v[34:35]
	v_pk_add_f32 v[28:29], v[28:29], v[40:41]
	v_pk_add_f32 v[34:35], v[26:27], v[36:37]
	v_pk_add_f32 v[26:27], v[24:25], v[42:43]
	v_cvt_pk_bf16_f32 v24, v28, v29
	v_cvt_pk_bf16_f32 v25, v30, v31
	v_cvt_pk_bf16_f32 v26, v26, v27
	v_cvt_pk_bf16_f32 v27, v34, v35
	global_store_dwordx4 v[38:39], v[24:27], off
	s_waitcnt vmcnt(15)
	s_nop 1
	v_mov_b32_e32 v24, v214
	v_mov_b32_e32 v25, v215
	v_mov_b32_e32 v26, v216
	v_mov_b32_e32 v27, v217
	s_waitcnt lgkmcnt(0)
	v_lshlrev_b32_e32 v28, 16, v24
	v_and_b32_e32 v29, 0xffff0000, v24
	v_lshlrev_b32_e32 v24, 16, v25
	v_and_b32_e32 v25, 0xffff0000, v25
	v_lshlrev_b32_e32 v30, 16, v26
	v_and_b32_e32 v31, 0xffff0000, v26
	v_lshlrev_b32_e32 v26, 16, v27
	v_and_b32_e32 v27, 0xffff0000, v27
	v_pk_add_f32 v[22:23], v[22:23], v[24:25]
	v_pk_add_f32 v[20:21], v[20:21], v[28:29]
	v_pk_add_f32 v[24:25], v[18:19], v[26:27]
	v_pk_add_f32 v[18:19], v[16:17], v[30:31]
	v_cvt_pk_bf16_f32 v16, v20, v21
	v_cvt_pk_bf16_f32 v17, v22, v23
	v_cvt_pk_bf16_f32 v18, v18, v19
	v_cvt_pk_bf16_f32 v19, v24, v25
	global_store_dwordx4 v[32:33], v[16:19], off offset:256
	s_nop 1
	v_lshl_add_u64 v[16:17], v[144:145], 0, s[2:3]
	s_mov_b32 s2, 0xb0000
	v_add_co_u32_e32 v22, vcc, s2, v144
	s_mov_b32 s2, s44
	s_nop 0
	v_addc_co_u32_e32 v23, vcc, 0, v145, vcc
	s_waitcnt vmcnt(15)
	s_nop 1
	v_mov_b32_e32 v18, v248
	v_mov_b32_e32 v19, v249
	v_mov_b32_e32 v20, v250
	v_mov_b32_e32 v21, v251
	s_and_b64 vcc, exec, s[40:41]
	s_waitcnt lgkmcnt(0)
	v_lshlrev_b32_e32 v24, 16, v18
	v_and_b32_e32 v25, 0xffff0000, v18
	v_lshlrev_b32_e32 v18, 16, v19
	v_and_b32_e32 v19, 0xffff0000, v19
	v_lshlrev_b32_e32 v26, 16, v20
	v_and_b32_e32 v27, 0xffff0000, v20
	v_lshlrev_b32_e32 v20, 16, v21
	v_and_b32_e32 v21, 0xffff0000, v21
	v_pk_add_f32 v[14:15], v[14:15], v[18:19]
	v_pk_add_f32 v[12:13], v[12:13], v[24:25]
	v_pk_add_f32 v[18:19], v[10:11], v[20:21]
	v_pk_add_f32 v[10:11], v[8:9], v[26:27]
	v_cvt_pk_bf16_f32 v8, v12, v13
	v_cvt_pk_bf16_f32 v9, v14, v15
	v_cvt_pk_bf16_f32 v10, v10, v11
	v_cvt_pk_bf16_f32 v11, v18, v19
	global_store_dwordx4 v[22:23], v[8:11], off
	s_waitcnt vmcnt(15)
	s_nop 1
	v_mov_b32_e32 v8, v252
	v_mov_b32_e32 v9, v253
	v_mov_b32_e32 v10, v254
	v_mov_b32_e32 v11, v255
	s_waitcnt lgkmcnt(0)
	v_lshlrev_b32_e32 v12, 16, v8
	v_and_b32_e32 v13, 0xffff0000, v8
	v_lshlrev_b32_e32 v8, 16, v9
	v_and_b32_e32 v9, 0xffff0000, v9
	v_lshlrev_b32_e32 v14, 16, v10
	v_and_b32_e32 v15, 0xffff0000, v10
	v_lshlrev_b32_e32 v10, 16, v11
	v_and_b32_e32 v11, 0xffff0000, v11
	v_pk_add_f32 v[6:7], v[6:7], v[8:9]
	v_pk_add_f32 v[4:5], v[4:5], v[12:13]
	v_pk_add_f32 v[8:9], v[2:3], v[10:11]
	v_pk_add_f32 v[2:3], v[0:1], v[14:15]
	v_cvt_pk_bf16_f32 v0, v4, v5
	v_cvt_pk_bf16_f32 v1, v6, v7
	v_cvt_pk_bf16_f32 v2, v2, v3
	v_cvt_pk_bf16_f32 v3, v8, v9
	global_store_dwordx4 v[16:17], v[0:3], off offset:256
	s_cbranch_vccz .LBB1_1761
	s_waitcnt vmcnt(0)
	s_cmpk_gt_u32 s17, 0xff
	s_cbranch_scc1 .LBB1_1768
	s_barrier

; #define PG8_STAGE(bufoff, gbase, voff) do { _Pragma("unroll") for (int _i = 0; _i < 2; ++_i) \
;         __builtin_amdgcn_global_load_lds((const unsigned*)((const char*)(gbase) + (voff)[_i]), (LAS unsigned*)(lds + (bufoff) + ldsw + _i * 8192), 16, 0, 0); } while (0)
; #define PG8_LDA(dst, b, h) do { _Pragma("unroll") for (int m = 0; m < 4; ++m) _Pragma("unroll") for (int k = 0; k < 2; ++k) dst[m][k] = *(const LAS bf16x8*)(lds + PG8_SA(b, h) + aoff + m * 2048 + k * 1024); } while (0)
; #define PG8_LDB(dst, b, h) do { _Pragma("unroll") for (int n = 0; n < 2; ++n) _Pragma("unroll") for (int k = 0; k < 2; ++k) dst[n][k] = *(const LAS bf16x8*)(lds + PG8_SB(b, h) + boff + n * 2048 + k * 1024); } while (0)
; #define PG8_MMA(ai, bj, At, Bt) do { __builtin_amdgcn_s_setprio(1); _Pragma("unroll") for (int m = 0; m < 4; ++m) _Pragma("unroll") for (int n = 0; n < 2; ++n) _Pragma("unroll") for (int k = 0; k < 2; ++k) \
;         acc[ai][bj][m][n] = __builtin_amdgcn_mfma_f32_16x16x32_bf16(Bt[n][k], At[m][k], acc[ai][bj][m][n], 0, 0, 0); __builtin_amdgcn_s_setprio(0); } while (0)
; #define PG8_WAIT_V(n) asm volatile("s_waitcnt vmcnt(" #n ")" ::: "memory")
; #define PG8_WAIT_L(n) asm volatile("s_waitcnt lgkmcnt(" #n ")" ::: "memory")
; #define PG8_BAR __builtin_amdgcn_s_barrier()
; #define PG8_SCHED __builtin_amdgcn_sched_barrier(0)
; template <class Map, class Epi>
; DI void gemm_phase(LAS unsigned char* lds, const Map& MP, const Epi& E, const int nM, const int nN, const int K, const int lda, const int ldb) {
;     ...
;             PG8_LDB(B0, 0, 0); PG8_SCHED; PG8_LDA(At, 0, 0); PG8_STAGE(PG8_SA(1, 1), a1 + hstepA, voffA);
;             PG8_WAIT_L(8); PG8_BAR; PG8_WAIT_L(0); PG8_MMA(0, 0, At, B0); PG8_BAR; PG8_SCHED;
;             PG8_LDB(B1, 0, 1); PG8_STAGE(PG8_SB(0, 0), b2, voffB);
;             PG8_BAR; PG8_WAIT_L(0); PG8_MMA(0, 1, At, B1); PG8_BAR;
;             PG8_LDA(At, 0, 1); PG8_STAGE(PG8_SA(0, 0), a2, voffA);
;             PG8_BAR; PG8_WAIT_L(0); PG8_MMA(1, 0, At, B0); PG8_BAR; PG8_SCHED;
;             PG8_STAGE(PG8_SB(0, 1), b2 + hstepB, voffB);
;             PG8_WAIT_V(6); PG8_BAR; PG8_MMA(1, 1, At, B1); PG8_BAR;
.LBB1_2078:
	ds_read_b128 v[152:155], v149
	ds_read_b128 v[156:159], v149 offset:1024
	ds_read_b128 v[160:163], v149 offset:2048
	ds_read_b128 v[164:167], v149 offset:3072
	s_add_u32 s10, s8, 0x100
	s_addc_u32 s11, s9, 0
	s_cmpk_eq_i32 s3, 0x54
	s_cselect_b32 s15, s43, s11
	s_cselect_b32 s14, s42, s10
	s_cselect_b32 s13, s7, s44
	s_cselect_b32 s12, s6, s39
	v_lshl_add_u64 v[144:145], s[8:9], 0, v[138:139]
	s_add_i32 m0, s24, 0xc000
	ds_read_b128 v[168:171], v150
	ds_read_b128 v[172:175], v150 offset:1024
	ds_read_b128 v[176:179], v150 offset:2048
	ds_read_b128 v[180:183], v150 offset:3072
	ds_read_b128 v[184:187], v150 offset:4096
	ds_read_b128 v[188:191], v150 offset:5120
	ds_read_b128 v[192:195], v150 offset:6144
	ds_read_b128 v[198:201], v150 offset:7168
	global_load_lds_dwordx4 v[144:145], off
	v_lshl_add_u64 v[144:145], s[8:9], 0, v[136:137]
	s_add_i32 m0, s24, 0xe000
	s_nop 0
	global_load_lds_dwordx4 v[144:145], off
	s_waitcnt lgkmcnt(8)
	s_barrier
	s_setprio 1
	s_waitcnt lgkmcnt(7)
	v_mfma_f32_16x16x32_bf16 v[124:127], v[152:155], v[168:171], v[124:127]
	v_mfma_f32_16x16x32_bf16 v[120:123], v[160:163], v[168:171], v[120:123]
	s_waitcnt lgkmcnt(5)
	v_mfma_f32_16x16x32_bf16 v[108:111], v[152:155], v[176:179], v[108:111]
	v_mfma_f32_16x16x32_bf16 v[104:107], v[160:163], v[176:179], v[104:107]
	s_waitcnt lgkmcnt(3)
	v_mfma_f32_16x16x32_bf16 v[92:95], v[152:155], v[184:187], v[92:95]
	v_mfma_f32_16x16x32_bf16 v[88:91], v[160:163], v[184:187], v[88:91]
	s_waitcnt lgkmcnt(1)
	v_mfma_f32_16x16x32_bf16 v[76:79], v[152:155], v[192:195], v[76:79]
	v_mfma_f32_16x16x32_bf16 v[72:75], v[160:163], v[192:195], v[72:75]
	v_mfma_f32_16x16x32_bf16 v[124:127], v[156:159], v[172:175], v[124:127]
	v_mfma_f32_16x16x32_bf16 v[120:123], v[164:167], v[172:175], v[120:123]
	v_mfma_f32_16x16x32_bf16 v[108:111], v[156:159], v[180:183], v[108:111]
	v_mfma_f32_16x16x32_bf16 v[104:107], v[164:167], v[180:183], v[104:107]
	v_mfma_f32_16x16x32_bf16 v[92:95], v[156:159], v[188:191], v[92:95]
	v_mfma_f32_16x16x32_bf16 v[88:91], v[164:167], v[188:191], v[88:91]
	s_waitcnt lgkmcnt(0)
	v_mfma_f32_16x16x32_bf16 v[76:79], v[156:159], v[198:201], v[76:79]
	v_mfma_f32_16x16x32_bf16 v[72:75], v[164:167], v[198:201], v[72:75]
	s_setprio 0
	s_barrier
	s_add_i32 s8, s35, s22
	v_lshl_add_u64 v[144:145], s[12:13], 0, v[132:133]
	s_mov_b32 m0, s8
	ds_read_b128 v[202:205], v151
	ds_read_b128 v[206:209], v151 offset:1024
	ds_read_b128 v[210:213], v151 offset:2048
	ds_read_b128 v[214:217], v151 offset:3072
	global_load_lds_dwordx4 v[144:145], off
	v_lshl_add_u64 v[218:219], s[12:13], 0, v[128:129]
	s_add_i32 m0, s8, 0x2000
	s_nop 0
	global_load_lds_dwordx4 v[218:219], off
	s_barrier
	s_setprio 1
	s_waitcnt lgkmcnt(3)
	v_mfma_f32_16x16x32_bf16 v[116:119], v[202:205], v[168:171], v[116:119]
	s_waitcnt lgkmcnt(1)
	v_mfma_f32_16x16x32_bf16 v[112:115], v[210:213], v[168:171], v[112:115]
	v_mfma_f32_16x16x32_bf16 v[100:103], v[202:205], v[176:179], v[100:103]
	v_mfma_f32_16x16x32_bf16 v[96:99], v[210:213], v[176:179], v[96:99]
	v_mfma_f32_16x16x32_bf16 v[84:87], v[202:205], v[184:187], v[84:87]
	v_mfma_f32_16x16x32_bf16 v[80:83], v[210:213], v[184:187], v[80:83]
	v_mfma_f32_16x16x32_bf16 v[68:71], v[202:205], v[192:195], v[68:71]
	v_mfma_f32_16x16x32_bf16 v[64:67], v[210:213], v[192:195], v[64:67]
	v_mfma_f32_16x16x32_bf16 v[116:119], v[206:209], v[172:175], v[116:119]
	s_waitcnt lgkmcnt(0)
	v_mfma_f32_16x16x32_bf16 v[112:115], v[214:217], v[172:175], v[112:115]
	v_mfma_f32_16x16x32_bf16 v[100:103], v[206:209], v[180:183], v[100:103]
	v_mfma_f32_16x16x32_bf16 v[96:99], v[214:217], v[180:183], v[96:99]
	v_mfma_f32_16x16x32_bf16 v[84:87], v[206:209], v[188:191], v[84:87]
	v_mfma_f32_16x16x32_bf16 v[80:83], v[214:217], v[188:191], v[80:83]
	v_mfma_f32_16x16x32_bf16 v[68:71], v[206:209], v[198:201], v[68:71]
	v_mfma_f32_16x16x32_bf16 v[64:67], v[214:217], v[198:201], v[64:67]
	s_setprio 0
	s_mov_b32 m0, s24
	v_lshl_add_u64 v[220:221], s[14:15], 0, v[134:135]
	s_barrier
	ds_read_b128 v[168:171], v150 offset:16384
	ds_read_b128 v[172:175], v150 offset:17408
	ds_read_b128 v[176:179], v150 offset:18432
	ds_read_b128 v[180:183], v150 offset:19456
	ds_read_b128 v[184:187], v150 offset:20480
	ds_read_b128 v[188:191], v150 offset:21504
	ds_read_b128 v[192:195], v150 offset:22528
	ds_read_b128 v[198:201], v150 offset:23552
	global_load_lds_dwordx4 v[220:221], off
	v_lshl_add_u64 v[222:223], s[14:15], 0, v[130:131]
	s_mov_b32 m0, s25
	s_nop 0
	global_load_lds_dwordx4 v[222:223], off
	s_barrier
	s_setprio 1
	s_waitcnt lgkmcnt(7)
	v_mfma_f32_16x16x32_bf16 v[60:63], v[152:155], v[168:171], v[60:63]
	v_mfma_f32_16x16x32_bf16 v[56:59], v[160:163], v[168:171], v[56:59]
	s_waitcnt lgkmcnt(5)
	v_mfma_f32_16x16x32_bf16 v[44:47], v[152:155], v[176:179], v[44:47]
	v_mfma_f32_16x16x32_bf16 v[40:43], v[160:163], v[176:179], v[40:43]
	s_waitcnt lgkmcnt(3)
	v_mfma_f32_16x16x32_bf16 v[28:31], v[152:155], v[184:187], v[28:31]
	v_mfma_f32_16x16x32_bf16 v[24:27], v[160:163], v[184:187], v[24:27]
	s_waitcnt lgkmcnt(1)
	v_mfma_f32_16x16x32_bf16 v[12:15], v[152:155], v[192:195], v[12:15]
	v_mfma_f32_16x16x32_bf16 v[8:11], v[160:163], v[192:195], v[8:11]
	v_mfma_f32_16x16x32_bf16 v[60:63], v[156:159], v[172:175], v[60:63]
	v_mfma_f32_16x16x32_bf16 v[56:59], v[164:167], v[172:175], v[56:59]
	v_mfma_f32_16x16x32_bf16 v[44:47], v[156:159], v[180:183], v[44:47]
	v_mfma_f32_16x16x32_bf16 v[40:43], v[164:167], v[180:183], v[40:43]
	v_mfma_f32_16x16x32_bf16 v[28:31], v[156:159], v[188:191], v[28:31]
	v_mfma_f32_16x16x32_bf16 v[24:27], v[164:167], v[188:191], v[24:27]
	s_waitcnt lgkmcnt(0)
	v_mfma_f32_16x16x32_bf16 v[12:15], v[156:159], v[198:201], v[12:15]
	v_mfma_f32_16x16x32_bf16 v[8:11], v[164:167], v[198:201], v[8:11]
	s_setprio 0
	s_barrier
; #define PG8_STAGE(bufoff, gbase, voff) do { _Pragma("unroll") for (int _i = 0; _i < 2; ++_i) \
;         __builtin_amdgcn_global_load_lds((const unsigned*)((const char*)(gbase) + (voff)[_i]), (LAS unsigned*)(lds + (bufoff) + ldsw + _i * 8192), 16, 0, 0); } while (0)
; #define PG8_LDA(dst, b, h) do { _Pragma("unroll") for (int m = 0; m < 4; ++m) _Pragma("unroll") for (int k = 0; k < 2; ++k) dst[m][k] = *(const LAS bf16x8*)(lds + PG8_SA(b, h) + aoff + m * 2048 + k * 1024); } while (0)
; #define PG8_LDB(dst, b, h) do { _Pragma("unroll") for (int n = 0; n < 2; ++n) _Pragma("unroll") for (int k = 0; k < 2; ++k) dst[n][k] = *(const LAS bf16x8*)(lds + PG8_SB(b, h) + boff + n * 2048 + k * 1024); } while (0)
; #define PG8_MMA(ai, bj, At, Bt) do { __builtin_amdgcn_s_setprio(1); _Pragma("unroll") for (int m = 0; m < 4; ++m) _Pragma("unroll") for (int n = 0; n < 2; ++n) _Pragma("unroll") for (int k = 0; k < 2; ++k) \
;         acc[ai][bj][m][n] = __builtin_amdgcn_mfma_f32_16x16x32_bf16(Bt[n][k], At[m][k], acc[ai][bj][m][n], 0, 0, 0); __builtin_amdgcn_s_setprio(0); } while (0)
; #define PG8_WAIT_V(n) asm volatile("s_waitcnt vmcnt(" #n ")" ::: "memory")
; #define PG8_WAIT_L(n) asm volatile("s_waitcnt lgkmcnt(" #n ")" ::: "memory")
; #define PG8_BAR __builtin_amdgcn_s_barrier()
; #define PG8_SCHED __builtin_amdgcn_sched_barrier(0)
; template <class Map, class Epi>
; DI void gemm_phase(LAS unsigned char* lds, const Map& MP, const Epi& E, const int nM, const int nN, const int K, const int lda, const int ldb) {
;     ...
;             PG8_WAIT_V(6); PG8_BAR; PG8_MMA(1, 1, At, B1); PG8_BAR;
;             PG8_LDB(B0, 1, 0); PG8_SCHED; PG8_LDA(At, 1, 0); PG8_STAGE(PG8_SA(0, 1), a2 + hstepA, voffA);
;             PG8_WAIT_L(8); PG8_BAR; PG8_WAIT_L(0); PG8_MMA(0, 0, At, B0); PG8_BAR; PG8_SCHED;
;             PG8_LDB(B1, 1, 1); PG8_STAGE(PG8_SB(1, 0), b3, voffB);
;             PG8_BAR; PG8_WAIT_L(0); PG8_MMA(0, 1, At, B1); PG8_BAR;
;             PG8_LDA(At, 1, 1); PG8_STAGE(PG8_SA(1, 0), a3, voffA);
;             PG8_BAR; PG8_WAIT_L(0); PG8_MMA(1, 0, At, B0); PG8_BAR; PG8_SCHED;
	s_add_u32 s8, s12, 0x160000
	s_addc_u32 s9, s13, 0
	s_add_i32 s45, s36, s22
	v_lshl_add_u64 v[152:153], s[8:9], 0, v[132:133]
	s_mov_b32 m0, s45
	s_nop 0
	global_load_lds_dwordx4 v[152:153], off
	v_lshl_add_u64 v[152:153], s[8:9], 0, v[128:129]
	s_add_i32 m0, s45, 0x2000
	s_nop 0
	global_load_lds_dwordx4 v[152:153], off
	s_waitcnt vmcnt(6)
	s_barrier
	s_setprio 1
	v_mfma_f32_16x16x32_bf16 v[52:55], v[202:205], v[168:171], v[52:55]
	v_mfma_f32_16x16x32_bf16 v[48:51], v[210:213], v[168:171], v[48:51]
	v_mfma_f32_16x16x32_bf16 v[36:39], v[202:205], v[176:179], v[36:39]
	v_mfma_f32_16x16x32_bf16 v[32:35], v[210:213], v[176:179], v[32:35]
	v_mfma_f32_16x16x32_bf16 v[20:23], v[202:205], v[184:187], v[20:23]
	v_mfma_f32_16x16x32_bf16 v[16:19], v[210:213], v[184:187], v[16:19]
	v_mfma_f32_16x16x32_bf16 v[4:7], v[202:205], v[192:195], v[4:7]
	v_mfma_f32_16x16x32_bf16 v[0:3], v[210:213], v[192:195], v[0:3]
	v_mfma_f32_16x16x32_bf16 v[52:55], v[206:209], v[172:175], v[52:55]
	v_mfma_f32_16x16x32_bf16 v[48:51], v[214:217], v[172:175], v[48:51]
	v_mfma_f32_16x16x32_bf16 v[36:39], v[206:209], v[180:183], v[36:39]
	v_mfma_f32_16x16x32_bf16 v[32:35], v[214:217], v[180:183], v[32:35]
	v_mfma_f32_16x16x32_bf16 v[20:23], v[206:209], v[188:191], v[20:23]
	v_mfma_f32_16x16x32_bf16 v[16:19], v[214:217], v[188:191], v[16:19]
	v_mfma_f32_16x16x32_bf16 v[4:7], v[206:209], v[198:201], v[4:7]
	v_mfma_f32_16x16x32_bf16 v[0:3], v[214:217], v[198:201], v[0:3]
	s_setprio 0
	s_add_i32 s45, 0, 0x18000
	v_add_u32_e32 v164, s45, v148
	s_barrier
	ds_read_b128 v[152:155], v164
	ds_read_b128 v[156:159], v164 offset:1024
	ds_read_b128 v[160:163], v164 offset:2048
	ds_read_b128 v[164:167], v164 offset:3072
	s_add_u32 s8, s14, 0x160000
	s_addc_u32 s9, s15, 0
	s_mov_b32 m0, s26
	v_lshl_add_u64 v[202:203], s[8:9], 0, v[134:135]
	ds_read_b128 v[168:171], v150 offset:32768
	ds_read_b128 v[172:175], v150 offset:33792
	ds_read_b128 v[176:179], v150 offset:34816
	ds_read_b128 v[180:183], v150 offset:35840
	ds_read_b128 v[184:187], v150 offset:36864
	ds_read_b128 v[188:191], v150 offset:37888
	ds_read_b128 v[192:195], v150 offset:38912
	ds_read_b128 v[198:201], v150 offset:39936
	global_load_lds_dwordx4 v[202:203], off
	v_lshl_add_u64 v[202:203], s[8:9], 0, v[130:131]
	s_mov_b32 m0, s27
	s_nop 0
	global_load_lds_dwordx4 v[202:203], off
	s_waitcnt lgkmcnt(8)
	s_barrier
	s_setprio 1
	s_waitcnt lgkmcnt(7)
	v_mfma_f32_16x16x32_bf16 v[124:127], v[152:155], v[168:171], v[124:127]
	v_mfma_f32_16x16x32_bf16 v[120:123], v[160:163], v[168:171], v[120:123]
	s_waitcnt lgkmcnt(5)
	v_mfma_f32_16x16x32_bf16 v[108:111], v[152:155], v[176:179], v[108:111]
	v_mfma_f32_16x16x32_bf16 v[104:107], v[160:163], v[176:179], v[104:107]
	s_waitcnt lgkmcnt(3)
	v_mfma_f32_16x16x32_bf16 v[92:95], v[152:155], v[184:187], v[92:95]
	v_mfma_f32_16x16x32_bf16 v[88:91], v[160:163], v[184:187], v[88:91]
	s_waitcnt lgkmcnt(1)
	v_mfma_f32_16x16x32_bf16 v[76:79], v[152:155], v[192:195], v[76:79]
	v_mfma_f32_16x16x32_bf16 v[72:75], v[160:163], v[192:195], v[72:75]
	v_mfma_f32_16x16x32_bf16 v[124:127], v[156:159], v[172:175], v[124:127]
	v_mfma_f32_16x16x32_bf16 v[120:123], v[164:167], v[172:175], v[120:123]
	v_mfma_f32_16x16x32_bf16 v[108:111], v[156:159], v[180:183], v[108:111]
	v_mfma_f32_16x16x32_bf16 v[104:107], v[164:167], v[180:183], v[104:107]
	v_mfma_f32_16x16x32_bf16 v[92:95], v[156:159], v[188:191], v[92:95]
	v_mfma_f32_16x16x32_bf16 v[88:91], v[164:167], v[188:191], v[88:91]
	s_waitcnt lgkmcnt(0)
	v_mfma_f32_16x16x32_bf16 v[76:79], v[156:159], v[198:201], v[76:79]
	v_mfma_f32_16x16x32_bf16 v[72:75], v[164:167], v[198:201], v[72:75]
	s_setprio 0
	s_barrier
	s_add_i32 s14, 0, 0x1c000
	s_add_i32 s8, s45, s22
	v_add_u32_e32 v196, s14, v148
	v_lshl_add_u64 v[144:145], v[144:145], 0, s[46:47]
	s_mov_b32 m0, s8
	ds_read_b128 v[202:205], v196
	ds_read_b128 v[206:209], v196 offset:1024
	ds_read_b128 v[210:213], v196 offset:2048
	ds_read_b128 v[214:217], v196 offset:3072
	global_load_lds_dwordx4 v[144:145], off
	v_lshl_add_u64 v[144:145], v[218:219], 0, s[46:47]
	s_add_i32 m0, s8, 0x2000
	s_nop 0
	global_load_lds_dwordx4 v[144:145], off
	s_barrier
	s_setprio 1
	s_waitcnt lgkmcnt(3)
	v_mfma_f32_16x16x32_bf16 v[116:119], v[202:205], v[168:171], v[116:119]
	s_waitcnt lgkmcnt(1)
	v_mfma_f32_16x16x32_bf16 v[112:115], v[210:213], v[168:171], v[112:115]
	v_mfma_f32_16x16x32_bf16 v[100:103], v[202:205], v[176:179], v[100:103]
	v_mfma_f32_16x16x32_bf16 v[96:99], v[210:213], v[176:179], v[96:99]
	v_mfma_f32_16x16x32_bf16 v[84:87], v[202:205], v[184:187], v[84:87]
	v_mfma_f32_16x16x32_bf16 v[80:83], v[210:213], v[184:187], v[80:83]
	v_mfma_f32_16x16x32_bf16 v[68:71], v[202:205], v[192:195], v[68:71]
	v_mfma_f32_16x16x32_bf16 v[64:67], v[210:213], v[192:195], v[64:67]
	v_mfma_f32_16x16x32_bf16 v[116:119], v[206:209], v[172:175], v[116:119]
	s_waitcnt lgkmcnt(0)
	v_mfma_f32_16x16x32_bf16 v[112:115], v[214:217], v[172:175], v[112:115]
	v_mfma_f32_16x16x32_bf16 v[100:103], v[206:209], v[180:183], v[100:103]
	v_mfma_f32_16x16x32_bf16 v[96:99], v[214:217], v[180:183], v[96:99]
	v_mfma_f32_16x16x32_bf16 v[84:87], v[206:209], v[188:191], v[84:87]
	v_mfma_f32_16x16x32_bf16 v[80:83], v[214:217], v[188:191], v[80:83]
	v_mfma_f32_16x16x32_bf16 v[68:71], v[206:209], v[198:201], v[68:71]
	v_mfma_f32_16x16x32_bf16 v[64:67], v[214:217], v[198:201], v[64:67]
	s_setprio 0
	s_mov_b32 m0, s30
	v_lshl_add_u64 v[144:145], v[220:221], 0, s[46:47]
	s_barrier
; #define PG8_STAGE(bufoff, gbase, voff) do { _Pragma("unroll") for (int _i = 0; _i < 2; ++_i) \
;         __builtin_amdgcn_global_load_lds((const unsigned*)((const char*)(gbase) + (voff)[_i]), (LAS unsigned*)(lds + (bufoff) + ldsw + _i * 8192), 16, 0, 0); } while (0)
; #define PG8_MMA(ai, bj, At, Bt) do { __builtin_amdgcn_s_setprio(1); _Pragma("unroll") for (int m = 0; m < 4; ++m) _Pragma("unroll") for (int n = 0; n < 2; ++n) _Pragma("unroll") for (int k = 0; k < 2; ++k) \
;         acc[ai][bj][m][n] = __builtin_amdgcn_mfma_f32_16x16x32_bf16(Bt[n][k], At[m][k], acc[ai][bj][m][n], 0, 0, 0); __builtin_amdgcn_s_setprio(0); } while (0)
; #define PG8_WAIT_V(n) asm volatile("s_waitcnt vmcnt(" #n ")" ::: "memory")
; #define PG8_WAIT_L(n) asm volatile("s_waitcnt lgkmcnt(" #n ")" ::: "memory")
; #define PG8_BAR __builtin_amdgcn_s_barrier()
; #define PG8_SCHED __builtin_amdgcn_sched_barrier(0)
;     DI void operator()(const f32x4 (&acc)[2][2][4][2], const Unit& u, int wr, int wc, int fr, int fq) const {
;         const int row0 = u.pm * BM + wr * 64 + fr, col0 = u.pn * BM + wc * 32 + 8 * fq;
;         f32x4 sc[2][2];
; #pragma unroll
;         for (int bj = 0; bj < 2; ++bj)
; #pragma unroll
;             for (int n = 0; n < 2; ++n) sc[bj][n] = scale ? *(const f32x4*)(scale + col0 + bj * HALF + 4 * n) : (f32x4){1.f, 1.f, 1.f, 1.f};
; #pragma unroll
;         for (int ai = 0; ai < 2; ++ai)
; #pragma unroll
;             for (int m = 0; m < 4; ++m) { const size_t ro = (size_t)(row0 + ai * HALF + m * 16) * D + col0;
; #pragma unroll
;                 for (int bj = 0; bj < 2; ++bj) {
;                     f32x4 x0, x1;
;                     if constexpr (IB) { const u32x4 w = *(const u32x4*)((const bf16_t*)Xin + ro + bj * HALF);
; template <class Map, class Epi>
; DI void gemm_phase(LAS unsigned char* lds, const Map& MP, const Epi& E, const int nM, const int nN, const int K, const int lda, const int ldb) {
;     ...
;             PG8_BAR; PG8_WAIT_L(0); PG8_MMA(1, 0, At, B0); PG8_BAR; PG8_SCHED;
;             PG8_STAGE(PG8_SB(1, 1), b3 + hstepB, voffB);
;             PG8_WAIT_V(6); PG8_BAR; PG8_MMA(1, 1, At, B1); PG8_BAR;
	ds_read_b128 v[168:171], v150 offset:49152
	ds_read_b128 v[172:175], v150 offset:50176
	ds_read_b128 v[176:179], v150 offset:51200
	ds_read_b128 v[180:183], v150 offset:52224
	ds_read_b128 v[184:187], v150 offset:53248
	ds_read_b128 v[188:191], v150 offset:54272
	ds_read_b128 v[192:195], v150 offset:55296
	ds_read_b128 v[198:201], v150 offset:56320
	global_load_lds_dwordx4 v[144:145], off
	v_lshl_add_u64 v[144:145], v[222:223], 0, s[46:47]
	s_mov_b32 m0, s31
	s_nop 0
	global_load_lds_dwordx4 v[144:145], off
	s_barrier
	s_setprio 1
	s_waitcnt lgkmcnt(7)
	v_mfma_f32_16x16x32_bf16 v[60:63], v[152:155], v[168:171], v[60:63]
	v_mfma_f32_16x16x32_bf16 v[56:59], v[160:163], v[168:171], v[56:59]
	s_waitcnt lgkmcnt(5)
	v_mfma_f32_16x16x32_bf16 v[44:47], v[152:155], v[176:179], v[44:47]
	v_mfma_f32_16x16x32_bf16 v[40:43], v[160:163], v[176:179], v[40:43]
	s_waitcnt lgkmcnt(3)
	v_mfma_f32_16x16x32_bf16 v[28:31], v[152:155], v[184:187], v[28:31]
	v_mfma_f32_16x16x32_bf16 v[24:27], v[160:163], v[184:187], v[24:27]
	s_waitcnt lgkmcnt(1)
	v_mfma_f32_16x16x32_bf16 v[12:15], v[152:155], v[192:195], v[12:15]
	v_mfma_f32_16x16x32_bf16 v[8:11], v[160:163], v[192:195], v[8:11]
	v_mfma_f32_16x16x32_bf16 v[60:63], v[156:159], v[172:175], v[60:63]
	v_mfma_f32_16x16x32_bf16 v[56:59], v[164:167], v[172:175], v[56:59]
	v_mfma_f32_16x16x32_bf16 v[44:47], v[156:159], v[180:183], v[44:47]
	v_mfma_f32_16x16x32_bf16 v[40:43], v[164:167], v[180:183], v[40:43]
	v_mfma_f32_16x16x32_bf16 v[28:31], v[156:159], v[188:191], v[28:31]
	v_mfma_f32_16x16x32_bf16 v[24:27], v[164:167], v[188:191], v[24:27]
	s_waitcnt lgkmcnt(0)
	v_mfma_f32_16x16x32_bf16 v[12:15], v[156:159], v[198:201], v[12:15]
	v_mfma_f32_16x16x32_bf16 v[8:11], v[164:167], v[198:201], v[8:11]
	s_setprio 0
	s_barrier
	s_add_u32 s8, s12, 0x160080
	s_addc_u32 s9, s13, 0
	s_add_i32 s12, s14, s22
	v_lshl_add_u64 v[144:145], s[8:9], 0, v[132:133]
	s_mov_b32 m0, s12
	s_nop 0
	global_load_lds_dwordx4 v[144:145], off
	v_lshl_add_u64 v[144:145], s[8:9], 0, v[128:129]
	s_add_i32 m0, s12, 0x2000
	s_nop 0
	global_load_lds_dwordx4 v[144:145], off
	s_waitcnt vmcnt(6)
	s_barrier
	s_setprio 1
	v_mfma_f32_16x16x32_bf16 v[52:55], v[202:205], v[168:171], v[52:55]
	v_mfma_f32_16x16x32_bf16 v[48:51], v[210:213], v[168:171], v[48:51]
	v_mfma_f32_16x16x32_bf16 v[36:39], v[202:205], v[176:179], v[36:39]
	v_mfma_f32_16x16x32_bf16 v[32:35], v[210:213], v[176:179], v[32:35]
	v_mfma_f32_16x16x32_bf16 v[20:23], v[202:205], v[184:187], v[20:23]
	v_mfma_f32_16x16x32_bf16 v[16:19], v[210:213], v[184:187], v[16:19]
	v_mfma_f32_16x16x32_bf16 v[4:7], v[202:205], v[192:195], v[4:7]
	v_mfma_f32_16x16x32_bf16 v[0:3], v[210:213], v[192:195], v[0:3]
	v_mfma_f32_16x16x32_bf16 v[52:55], v[206:209], v[172:175], v[52:55]
	v_mfma_f32_16x16x32_bf16 v[48:51], v[214:217], v[172:175], v[48:51]
	v_mfma_f32_16x16x32_bf16 v[36:39], v[206:209], v[180:183], v[36:39]
	v_mfma_f32_16x16x32_bf16 v[32:35], v[214:217], v[180:183], v[32:35]
	v_mfma_f32_16x16x32_bf16 v[20:23], v[206:209], v[188:191], v[20:23]
	v_mfma_f32_16x16x32_bf16 v[16:19], v[214:217], v[188:191], v[16:19]
	v_mfma_f32_16x16x32_bf16 v[4:7], v[206:209], v[198:201], v[4:7]
	v_mfma_f32_16x16x32_bf16 v[0:3], v[214:217], v[198:201], v[0:3]
	s_setprio 0
	s_add_i32 s3, s3, 2
	s_add_u32 s39, s39, 0x100
	s_addc_u32 s44, s44, 0
	s_cmpk_gt_u32 s3, 0x55
	s_mov_b64 s[8:9], s[10:11]
	s_barrier
	s_cbranch_scc0 .LBB1_2078
	v_mov_b32_e32 v152, v147
	v_mov_b32_e32 v144, v146
	s_lshl_b32 s2, s2, 8
	s_add_i32 s2, s2, s29
	s_lshl_b32 s3, s38, 8
	v_add_u32_e32 v152, s2, v152
	s_or_b32 s3, s3, s52
	v_ashrrev_i32_e32 v153, 31, v152
	v_lshl_add_u32 v144, v144, 3, s3
	v_lshlrev_b64 v[152:153], 12, v[152:153]
	v_ashrrev_i32_e32 v145, 31, v144
	v_lshl_add_u64 v[152:153], s[4:5], 0, v[152:153]
	v_lshl_add_u64 v[144:145], v[144:145], 1, v[152:153]
	global_load_dwordx4 v[160:163], v[144:145], off
	global_load_dwordx4 v[164:167], v[144:145], off offset:256
	s_mov_b64 s[98:99], 0x10000
	v_lshl_add_u64 v[154:155], v[144:145], 0, s[98:99]
	global_load_dwordx4 v[168:171], v[154:155], off
	global_load_dwordx4 v[172:175], v[154:155], off offset:256
	s_mov_b64 s[98:99], 0x20000
	v_lshl_add_u64 v[154:155], v[144:145], 0, s[98:99]
	global_load_dwordx4 v[176:179], v[154:155], off
	global_load_dwordx4 v[180:183], v[154:155], off offset:256
	s_mov_b64 s[98:99], 0x30000
	v_lshl_add_u64 v[154:155], v[144:145], 0, s[98:99]
	global_load_dwordx4 v[184:187], v[154:155], off
	global_load_dwordx4 v[188:191], v[154:155], off offset:256
	s_mov_b64 s[98:99], 0x80000
	v_lshl_add_u64 v[154:155], v[144:145], 0, s[98:99]
	global_load_dwordx4 v[192:195], v[154:155], off
	global_load_dwordx4 v[198:201], v[154:155], off offset:256
	s_mov_b64 s[98:99], 0x90000
	v_lshl_add_u64 v[154:155], v[144:145], 0, s[98:99]
	global_load_dwordx4 v[202:205], v[154:155], off
	global_load_dwordx4 v[206:209], v[154:155], off offset:256
	s_mov_b64 s[98:99], 0xa0000
	v_lshl_add_u64 v[154:155], v[144:145], 0, s[98:99]
	global_load_dwordx4 v[210:213], v[154:155], off
	global_load_dwordx4 v[214:217], v[154:155], off offset:256
	s_mov_b64 s[98:99], 0xb0000
	v_lshl_add_u64 v[154:155], v[144:145], 0, s[98:99]
	global_load_dwordx4 v[248:251], v[154:155], off
	global_load_dwordx4 v[252:255], v[154:155], off offset:256
	s_waitcnt vmcnt(15)
	s_nop 1
	v_mov_b32_e32 v152, v160
	v_mov_b32_e32 v153, v161
	v_mov_b32_e32 v154, v162
	v_mov_b32_e32 v155, v163
	s_mov_b64 s[2:3], 0x10000
	s_mov_b32 s38, s37
	s_mov_b64 s[10:11], s[6:7]
	s_mov_b64 s[8:9], s[42:43]
	s_waitcnt lgkmcnt(0)
; DI unsigned pack2(float a, float b) { f32x2 v = {a, b}; hwbf16x2 r = __builtin_convertvector(v, hwbf16x2); return __builtin_bit_cast(unsigned, r); }
; DI float bflo(unsigned w) { return __uint_as_float(w << 16); }
; DI float bfhi(unsigned w) { return __uint_as_float(w & 0xffff0000u); }
;     DI void operator()(const f32x4 (&acc)[2][2][4][2], const Unit& u, int wr, int wc, int fr, int fq) const {
;     ...
;             for (int m = 0; m < 4; ++m) { const size_t ro = (size_t)(row0 + ai * HALF + m * 16) * D + col0;
; #pragma unroll
;                 for (int bj = 0; bj < 2; ++bj) {
;                     f32x4 x0, x1;
;                     if constexpr (IB) { const u32x4 w = *(const u32x4*)((const bf16_t*)Xin + ro + bj * HALF);
;                         x0 = (f32x4){bflo(w[0]), bfhi(w[0]), bflo(w[1]), bfhi(w[1])}; x1 = (f32x4){bflo(w[2]), bfhi(w[2]), bflo(w[3]), bfhi(w[3])}; }
;                     else { x0 = *(const f32x4*)((const float*)Xin + ro + bj * HALF); x1 = *(const f32x4*)((const float*)Xin + ro + bj * HALF + 4); }
;                     x0 += acc[ai][bj][m][0] * sc[bj][0]; x1 += acc[ai][bj][m][1] * sc[bj][1];
;                     if constexpr (OB) { u32x4 o; o[0] = pack2(x0[0], x0[1]); o[1] = pack2(x0[2], x0[3]); o[2] = pack2(x1[0], x1[1]); o[3] = pack2(x1[2], x1[3]);
;                         *(u32x4*)((bf16_t*)Xout + ro + bj * HALF) = o; }
;                     else { *(f32x4*)((float*)Xout + ro + bj * HALF) = x0; *(f32x4*)((float*)Xout + ro + bj * HALF + 4) = x1; } } }
	v_lshlrev_b32_e32 v156, 16, v152
	v_and_b32_e32 v157, 0xffff0000, v152
	v_lshlrev_b32_e32 v152, 16, v153
	v_and_b32_e32 v153, 0xffff0000, v153
	v_lshlrev_b32_e32 v158, 16, v154
	v_and_b32_e32 v159, 0xffff0000, v154
	v_lshlrev_b32_e32 v154, 16, v155
	v_and_b32_e32 v155, 0xffff0000, v155
	v_pk_add_f32 v[126:127], v[126:127], v[152:153]
	v_pk_add_f32 v[124:125], v[124:125], v[156:157]
	v_pk_add_f32 v[152:153], v[122:123], v[154:155]
	v_pk_add_f32 v[122:123], v[120:121], v[158:159]
	v_cvt_pk_bf16_f32 v120, v124, v125
	v_cvt_pk_bf16_f32 v121, v126, v127
	v_cvt_pk_bf16_f32 v122, v122, v123
	v_cvt_pk_bf16_f32 v123, v152, v153
	global_store_dwordx4 v[144:145], v[120:123], off
	s_waitcnt vmcnt(15)
	s_nop 1
	v_mov_b32_e32 v120, v164
	v_mov_b32_e32 v121, v165
	v_mov_b32_e32 v122, v166
	v_mov_b32_e32 v123, v167
	s_waitcnt lgkmcnt(0)
	v_lshlrev_b32_e32 v124, 16, v120
	v_and_b32_e32 v125, 0xffff0000, v120
	v_lshlrev_b32_e32 v120, 16, v121
	v_and_b32_e32 v121, 0xffff0000, v121
	v_lshlrev_b32_e32 v126, 16, v122
	v_and_b32_e32 v127, 0xffff0000, v122
	v_lshlrev_b32_e32 v122, 16, v123
	v_and_b32_e32 v123, 0xffff0000, v123
	v_pk_add_f32 v[116:117], v[116:117], v[124:125]
	v_pk_add_f32 v[118:119], v[118:119], v[120:121]
	v_pk_add_f32 v[120:121], v[114:115], v[122:123]
	v_pk_add_f32 v[114:115], v[112:113], v[126:127]
	v_cvt_pk_bf16_f32 v112, v116, v117
	v_lshl_add_u64 v[116:117], v[144:145], 0, s[2:3]
	s_mov_b32 s2, 0x10000
	v_cvt_pk_bf16_f32 v113, v118, v119
	v_add_co_u32_e32 v118, vcc, s2, v144
	v_cvt_pk_bf16_f32 v114, v114, v115
	v_cvt_pk_bf16_f32 v115, v120, v121
	v_addc_co_u32_e32 v119, vcc, 0, v145, vcc
	global_store_dwordx4 v[144:145], v[112:115], off offset:256
	s_waitcnt vmcnt(15)
	s_nop 1
	v_mov_b32_e32 v112, v168
	v_mov_b32_e32 v113, v169
	v_mov_b32_e32 v114, v170
	v_mov_b32_e32 v115, v171
	s_mov_b64 s[2:3], 0x20000
	s_waitcnt lgkmcnt(0)
	v_lshlrev_b32_e32 v120, 16, v112
	v_and_b32_e32 v121, 0xffff0000, v112
	v_lshlrev_b32_e32 v112, 16, v113
	v_and_b32_e32 v113, 0xffff0000, v113
	v_lshlrev_b32_e32 v122, 16, v114
	v_and_b32_e32 v123, 0xffff0000, v114
	v_lshlrev_b32_e32 v114, 16, v115
	v_and_b32_e32 v115, 0xffff0000, v115
	v_pk_add_f32 v[110:111], v[110:111], v[112:113]
	v_pk_add_f32 v[108:109], v[108:109], v[120:121]
	v_pk_add_f32 v[112:113], v[106:107], v[114:115]
	v_pk_add_f32 v[106:107], v[104:105], v[122:123]
	v_cvt_pk_bf16_f32 v104, v108, v109
	v_cvt_pk_bf16_f32 v105, v110, v111
	v_cvt_pk_bf16_f32 v106, v106, v107
	v_cvt_pk_bf16_f32 v107, v112, v113
	global_store_dwordx4 v[118:119], v[104:107], off
	s_waitcnt vmcnt(15)
	s_nop 1
	v_mov_b32_e32 v104, v172
	v_mov_b32_e32 v105, v173
	v_mov_b32_e32 v106, v174
	v_mov_b32_e32 v107, v175
	s_waitcnt lgkmcnt(0)
	v_lshlrev_b32_e32 v108, 16, v104
	v_and_b32_e32 v109, 0xffff0000, v104
	v_lshlrev_b32_e32 v104, 16, v105
	v_and_b32_e32 v105, 0xffff0000, v105
	v_lshlrev_b32_e32 v110, 16, v106
	v_and_b32_e32 v111, 0xffff0000, v106
	v_lshlrev_b32_e32 v106, 16, v107
	v_and_b32_e32 v107, 0xffff0000, v107
	v_pk_add_f32 v[100:101], v[100:101], v[108:109]
	v_pk_add_f32 v[102:103], v[102:103], v[104:105]
	v_pk_add_f32 v[104:105], v[98:99], v[106:107]
	v_pk_add_f32 v[98:99], v[96:97], v[110:111]
	v_cvt_pk_bf16_f32 v96, v100, v101
	v_lshl_add_u64 v[100:101], v[144:145], 0, s[2:3]
	s_mov_b32 s2, 0x20000
	v_cvt_pk_bf16_f32 v97, v102, v103
	v_add_co_u32_e32 v102, vcc, s2, v144
	v_cvt_pk_bf16_f32 v98, v98, v99
	v_cvt_pk_bf16_f32 v99, v104, v105
	v_addc_co_u32_e32 v103, vcc, 0, v145, vcc
	global_store_dwordx4 v[116:117], v[96:99], off offset:256
	s_waitcnt vmcnt(15)
	s_nop 1
	v_mov_b32_e32 v96, v176
	v_mov_b32_e32 v97, v177
	v_mov_b32_e32 v98, v178
	v_mov_b32_e32 v99, v179
	s_mov_b64 s[2:3], 0x30000
	s_waitcnt lgkmcnt(0)
	v_lshlrev_b32_e32 v104, 16, v96
	v_and_b32_e32 v105, 0xffff0000, v96
	v_lshlrev_b32_e32 v96, 16, v97
	v_and_b32_e32 v97, 0xffff0000, v97
	v_lshlrev_b32_e32 v106, 16, v98
	v_and_b32_e32 v107, 0xffff0000, v98
	v_lshlrev_b32_e32 v98, 16, v99
	v_and_b32_e32 v99, 0xffff0000, v99
	v_pk_add_f32 v[94:95], v[94:95], v[96:97]
	v_pk_add_f32 v[92:93], v[92:93], v[104:105]
	v_pk_add_f32 v[96:97], v[90:91], v[98:99]
	v_pk_add_f32 v[90:91], v[88:89], v[106:107]
	v_cvt_pk_bf16_f32 v88, v92, v93
	v_cvt_pk_bf16_f32 v89, v94, v95
	v_cvt_pk_bf16_f32 v90, v90, v91
	v_cvt_pk_bf16_f32 v91, v96, v97
	global_store_dwordx4 v[102:103], v[88:91], off
	s_waitcnt vmcnt(15)
	s_nop 1
	v_mov_b32_e32 v88, v180
	v_mov_b32_e32 v89, v181
	v_mov_b32_e32 v90, v182
	v_mov_b32_e32 v91, v183
	s_waitcnt lgkmcnt(0)
	v_lshlrev_b32_e32 v92, 16, v88
	v_and_b32_e32 v93, 0xffff0000, v88
	v_lshlrev_b32_e32 v88, 16, v89
	v_and_b32_e32 v89, 0xffff0000, v89
	v_lshlrev_b32_e32 v94, 16, v90
	v_and_b32_e32 v95, 0xffff0000, v90
	v_lshlrev_b32_e32 v90, 16, v91
	v_and_b32_e32 v91, 0xffff0000, v91
	v_pk_add_f32 v[86:87], v[86:87], v[88:89]
	v_pk_add_f32 v[84:85], v[84:85], v[92:93]
	v_pk_add_f32 v[88:89], v[82:83], v[90:91]
	v_pk_add_f32 v[82:83], v[80:81], v[94:95]
	v_cvt_pk_bf16_f32 v80, v84, v85
	v_cvt_pk_bf16_f32 v81, v86, v87
	v_cvt_pk_bf16_f32 v82, v82, v83
	v_cvt_pk_bf16_f32 v83, v88, v89
	global_store_dwordx4 v[100:101], v[80:83], off offset:256
	s_nop 1
	v_lshl_add_u64 v[80:81], v[144:145], 0, s[2:3]
	s_mov_b32 s2, 0x30000
	v_add_co_u32_e32 v86, vcc, s2, v144
	s_mov_b64 s[2:3], 0x80000
	s_nop 0
	v_addc_co_u32_e32 v87, vcc, 0, v145, vcc
	s_waitcnt vmcnt(15)
	s_nop 1
	v_mov_b32_e32 v82, v184
	v_mov_b32_e32 v83, v185
	v_mov_b32_e32 v84, v186
	v_mov_b32_e32 v85, v187
	s_waitcnt lgkmcnt(0)
; DI unsigned pack2(float a, float b) { f32x2 v = {a, b}; hwbf16x2 r = __builtin_convertvector(v, hwbf16x2); return __builtin_bit_cast(unsigned, r); }
; DI float bflo(unsigned w) { return __uint_as_float(w << 16); }
; DI float bfhi(unsigned w) { return __uint_as_float(w & 0xffff0000u); }
;     DI void operator()(const f32x4 (&acc)[2][2][4][2], const Unit& u, int wr, int wc, int fr, int fq) const {
;     ...
;             for (int m = 0; m < 4; ++m) { const size_t ro = (size_t)(row0 + ai * HALF + m * 16) * D + col0;
; #pragma unroll
;                 for (int bj = 0; bj < 2; ++bj) {
;                     f32x4 x0, x1;
;                     if constexpr (IB) { const u32x4 w = *(const u32x4*)((const bf16_t*)Xin + ro + bj * HALF);
;                         x0 = (f32x4){bflo(w[0]), bfhi(w[0]), bflo(w[1]), bfhi(w[1])}; x1 = (f32x4){bflo(w[2]), bfhi(w[2]), bflo(w[3]), bfhi(w[3])}; }
;                     else { x0 = *(const f32x4*)((const float*)Xin + ro + bj * HALF); x1 = *(const f32x4*)((const float*)Xin + ro + bj * HALF + 4); }
;                     x0 += acc[ai][bj][m][0] * sc[bj][0]; x1 += acc[ai][bj][m][1] * sc[bj][1];
;                     if constexpr (OB) { u32x4 o; o[0] = pack2(x0[0], x0[1]); o[1] = pack2(x0[2], x0[3]); o[2] = pack2(x1[0], x1[1]); o[3] = pack2(x1[2], x1[3]);
;                         *(u32x4*)((bf16_t*)Xout + ro + bj * HALF) = o; }
;                     else { *(f32x4*)((float*)Xout + ro + bj * HALF) = x0; *(f32x4*)((float*)Xout + ro + bj * HALF + 4) = x1; } } }
	v_lshlrev_b32_e32 v88, 16, v82
	v_and_b32_e32 v89, 0xffff0000, v82
	v_lshlrev_b32_e32 v82, 16, v83
	v_and_b32_e32 v83, 0xffff0000, v83
	v_lshlrev_b32_e32 v90, 16, v84
	v_and_b32_e32 v91, 0xffff0000, v84
	v_lshlrev_b32_e32 v84, 16, v85
	v_and_b32_e32 v85, 0xffff0000, v85
	v_pk_add_f32 v[78:79], v[78:79], v[82:83]
	v_pk_add_f32 v[76:77], v[76:77], v[88:89]
	v_pk_add_f32 v[82:83], v[74:75], v[84:85]
	v_pk_add_f32 v[74:75], v[72:73], v[90:91]
	v_cvt_pk_bf16_f32 v72, v76, v77
	v_cvt_pk_bf16_f32 v73, v78, v79
	v_cvt_pk_bf16_f32 v74, v74, v75
	v_cvt_pk_bf16_f32 v75, v82, v83
	global_store_dwordx4 v[86:87], v[72:75], off
	s_waitcnt vmcnt(15)
	s_nop 1
	v_mov_b32_e32 v72, v188
	v_mov_b32_e32 v73, v189
	v_mov_b32_e32 v74, v190
	v_mov_b32_e32 v75, v191
	s_waitcnt lgkmcnt(0)
	v_lshlrev_b32_e32 v76, 16, v72
	v_and_b32_e32 v77, 0xffff0000, v72
	v_lshlrev_b32_e32 v72, 16, v73
	v_and_b32_e32 v73, 0xffff0000, v73
	v_lshlrev_b32_e32 v78, 16, v74
	v_and_b32_e32 v79, 0xffff0000, v74
	v_lshlrev_b32_e32 v74, 16, v75
	v_and_b32_e32 v75, 0xffff0000, v75
	v_pk_add_f32 v[70:71], v[70:71], v[72:73]
	v_pk_add_f32 v[68:69], v[68:69], v[76:77]
	v_pk_add_f32 v[72:73], v[66:67], v[74:75]
	v_pk_add_f32 v[66:67], v[64:65], v[78:79]
	v_cvt_pk_bf16_f32 v64, v68, v69
	v_cvt_pk_bf16_f32 v65, v70, v71
	v_cvt_pk_bf16_f32 v66, v66, v67
	v_cvt_pk_bf16_f32 v67, v72, v73
	global_store_dwordx4 v[80:81], v[64:67], off offset:256
	s_nop 1
	v_lshl_add_u64 v[64:65], v[144:145], 0, s[2:3]
	s_mov_b32 s2, 0x80000
	v_add_co_u32_e32 v70, vcc, s2, v144
	s_mov_b64 s[2:3], 0x90000
	s_nop 0
	v_addc_co_u32_e32 v71, vcc, 0, v145, vcc
	s_waitcnt vmcnt(15)
	s_nop 1
	v_mov_b32_e32 v66, v192
	v_mov_b32_e32 v67, v193
	v_mov_b32_e32 v68, v194
	v_mov_b32_e32 v69, v195
	s_waitcnt lgkmcnt(0)
	v_lshlrev_b32_e32 v72, 16, v66
	v_and_b32_e32 v73, 0xffff0000, v66
	v_lshlrev_b32_e32 v66, 16, v67
	v_and_b32_e32 v67, 0xffff0000, v67
	v_lshlrev_b32_e32 v74, 16, v68
	v_and_b32_e32 v75, 0xffff0000, v68
	v_lshlrev_b32_e32 v68, 16, v69
	v_and_b32_e32 v69, 0xffff0000, v69
	v_pk_add_f32 v[62:63], v[62:63], v[66:67]
	v_pk_add_f32 v[60:61], v[60:61], v[72:73]
	v_pk_add_f32 v[66:67], v[58:59], v[68:69]
	v_pk_add_f32 v[58:59], v[56:57], v[74:75]
	v_cvt_pk_bf16_f32 v56, v60, v61
	v_cvt_pk_bf16_f32 v57, v62, v63
	v_cvt_pk_bf16_f32 v58, v58, v59
	v_cvt_pk_bf16_f32 v59, v66, v67
	global_store_dwordx4 v[70:71], v[56:59], off
	s_waitcnt vmcnt(15)
	s_nop 1
	v_mov_b32_e32 v56, v198
	v_mov_b32_e32 v57, v199
	v_mov_b32_e32 v58, v200
	v_mov_b32_e32 v59, v201
	s_waitcnt lgkmcnt(0)
	v_lshlrev_b32_e32 v60, 16, v56
	v_and_b32_e32 v61, 0xffff0000, v56
	v_lshlrev_b32_e32 v56, 16, v57
	v_and_b32_e32 v57, 0xffff0000, v57
	v_lshlrev_b32_e32 v62, 16, v58
	v_and_b32_e32 v63, 0xffff0000, v58
	v_lshlrev_b32_e32 v58, 16, v59
	v_and_b32_e32 v59, 0xffff0000, v59
	v_pk_add_f32 v[54:55], v[54:55], v[56:57]
	v_pk_add_f32 v[52:53], v[52:53], v[60:61]
	v_pk_add_f32 v[56:57], v[50:51], v[58:59]
	v_pk_add_f32 v[50:51], v[48:49], v[62:63]
	v_cvt_pk_bf16_f32 v48, v52, v53
	v_cvt_pk_bf16_f32 v49, v54, v55
	v_cvt_pk_bf16_f32 v50, v50, v51
	v_cvt_pk_bf16_f32 v51, v56, v57
	global_store_dwordx4 v[64:65], v[48:51], off offset:256
	s_nop 1
	v_lshl_add_u64 v[48:49], v[144:145], 0, s[2:3]
	s_mov_b32 s2, 0x90000
	v_add_co_u32_e32 v54, vcc, s2, v144
	s_mov_b64 s[2:3], 0xa0000
	s_nop 0
	v_addc_co_u32_e32 v55, vcc, 0, v145, vcc
	s_waitcnt vmcnt(15)
	s_nop 1
	v_mov_b32_e32 v50, v202
	v_mov_b32_e32 v51, v203
	v_mov_b32_e32 v52, v204
	v_mov_b32_e32 v53, v205
	s_waitcnt lgkmcnt(0)
	v_lshlrev_b32_e32 v56, 16, v50
	v_and_b32_e32 v57, 0xffff0000, v50
	v_lshlrev_b32_e32 v50, 16, v51
	v_and_b32_e32 v51, 0xffff0000, v51
	v_lshlrev_b32_e32 v58, 16, v52
	v_and_b32_e32 v59, 0xffff0000, v52
	v_lshlrev_b32_e32 v52, 16, v53
	v_and_b32_e32 v53, 0xffff0000, v53
	v_pk_add_f32 v[46:47], v[46:47], v[50:51]
	v_pk_add_f32 v[44:45], v[44:45], v[56:57]
	v_pk_add_f32 v[50:51], v[42:43], v[52:53]
	v_pk_add_f32 v[42:43], v[40:41], v[58:59]
	v_cvt_pk_bf16_f32 v40, v44, v45
	v_cvt_pk_bf16_f32 v41, v46, v47
	v_cvt_pk_bf16_f32 v42, v42, v43
	v_cvt_pk_bf16_f32 v43, v50, v51
	global_store_dwordx4 v[54:55], v[40:43], off
	s_waitcnt vmcnt(15)
	s_nop 1
	v_mov_b32_e32 v40, v206
	v_mov_b32_e32 v41, v207
	v_mov_b32_e32 v42, v208
	v_mov_b32_e32 v43, v209
	s_waitcnt lgkmcnt(0)
; DI unsigned pack2(float a, float b) { f32x2 v = {a, b}; hwbf16x2 r = __builtin_convertvector(v, hwbf16x2); return __builtin_bit_cast(unsigned, r); }
; DI float bflo(unsigned w) { return __uint_as_float(w << 16); }
; DI float bfhi(unsigned w) { return __uint_as_float(w & 0xffff0000u); }
; #define PG8_WAIT_V(n) asm volatile("s_waitcnt vmcnt(" #n ")" ::: "memory")
; #define PG8_BAR __builtin_amdgcn_s_barrier()
;     DI void operator()(const f32x4 (&acc)[2][2][4][2], const Unit& u, int wr, int wc, int fr, int fq) const {
;     ...
;             for (int m = 0; m < 4; ++m) { const size_t ro = (size_t)(row0 + ai * HALF + m * 16) * D + col0;
; #pragma unroll
;                 for (int bj = 0; bj < 2; ++bj) {
;                     f32x4 x0, x1;
;                     if constexpr (IB) { const u32x4 w = *(const u32x4*)((const bf16_t*)Xin + ro + bj * HALF);
;                         x0 = (f32x4){bflo(w[0]), bfhi(w[0]), bflo(w[1]), bfhi(w[1])}; x1 = (f32x4){bflo(w[2]), bfhi(w[2]), bflo(w[3]), bfhi(w[3])}; }
;                     else { x0 = *(const f32x4*)((const float*)Xin + ro + bj * HALF); x1 = *(const f32x4*)((const float*)Xin + ro + bj * HALF + 4); }
;                     x0 += acc[ai][bj][m][0] * sc[bj][0]; x1 += acc[ai][bj][m][1] * sc[bj][1];
;                     if constexpr (OB) { u32x4 o; o[0] = pack2(x0[0], x0[1]); o[1] = pack2(x0[2], x0[3]); o[2] = pack2(x1[0], x1[1]); o[3] = pack2(x1[2], x1[3]);
;                         *(u32x4*)((bf16_t*)Xout + ro + bj * HALF) = o; }
;                     else { *(f32x4*)((float*)Xout + ro + bj * HALF) = x0; *(f32x4*)((float*)Xout + ro + bj * HALF + 4) = x1; } } }
; template <class Map, class Epi>
; DI void gemm_phase(LAS unsigned char* lds, const Map& MP, const Epi& E, const int nM, const int nN, const int K, const int lda, const int ldb) {
;     ...
;         if (!has_next) break;
;     ...
;     PG8_WAIT_V(0);
;     if (wr == 0) PG8_BAR;
;     PG8_BAR;
	v_lshlrev_b32_e32 v44, 16, v40
	v_and_b32_e32 v45, 0xffff0000, v40
	v_lshlrev_b32_e32 v40, 16, v41
	v_and_b32_e32 v41, 0xffff0000, v41
	v_lshlrev_b32_e32 v46, 16, v42
	v_and_b32_e32 v47, 0xffff0000, v42
	v_lshlrev_b32_e32 v42, 16, v43
	v_and_b32_e32 v43, 0xffff0000, v43
	v_pk_add_f32 v[38:39], v[38:39], v[40:41]
	v_pk_add_f32 v[36:37], v[36:37], v[44:45]
	v_pk_add_f32 v[40:41], v[34:35], v[42:43]
	v_pk_add_f32 v[34:35], v[32:33], v[46:47]
	v_cvt_pk_bf16_f32 v32, v36, v37
	v_cvt_pk_bf16_f32 v33, v38, v39
	v_cvt_pk_bf16_f32 v34, v34, v35
	v_cvt_pk_bf16_f32 v35, v40, v41
	global_store_dwordx4 v[48:49], v[32:35], off offset:256
	s_nop 1
	v_lshl_add_u64 v[32:33], v[144:145], 0, s[2:3]
	s_mov_b32 s2, 0xa0000
	v_add_co_u32_e32 v38, vcc, s2, v144
	s_mov_b64 s[2:3], 0xb0000
	s_nop 0
	v_addc_co_u32_e32 v39, vcc, 0, v145, vcc
	s_waitcnt vmcnt(15)
	s_nop 1
	v_mov_b32_e32 v34, v210
	v_mov_b32_e32 v35, v211
	v_mov_b32_e32 v36, v212
	v_mov_b32_e32 v37, v213
	s_waitcnt lgkmcnt(0)
	v_lshlrev_b32_e32 v40, 16, v34
	v_and_b32_e32 v41, 0xffff0000, v34
	v_lshlrev_b32_e32 v34, 16, v35
	v_and_b32_e32 v35, 0xffff0000, v35
	v_lshlrev_b32_e32 v42, 16, v36
	v_and_b32_e32 v43, 0xffff0000, v36
	v_lshlrev_b32_e32 v36, 16, v37
	v_and_b32_e32 v37, 0xffff0000, v37
	v_pk_add_f32 v[30:31], v[30:31], v[34:35]
	v_pk_add_f32 v[28:29], v[28:29], v[40:41]
	v_pk_add_f32 v[34:35], v[26:27], v[36:37]
	v_pk_add_f32 v[26:27], v[24:25], v[42:43]
	v_cvt_pk_bf16_f32 v24, v28, v29
	v_cvt_pk_bf16_f32 v25, v30, v31
	v_cvt_pk_bf16_f32 v26, v26, v27
	v_cvt_pk_bf16_f32 v27, v34, v35
	global_store_dwordx4 v[38:39], v[24:27], off
	s_waitcnt vmcnt(15)
	s_nop 1
	v_mov_b32_e32 v24, v214
	v_mov_b32_e32 v25, v215
	v_mov_b32_e32 v26, v216
	v_mov_b32_e32 v27, v217
	s_waitcnt lgkmcnt(0)
	v_lshlrev_b32_e32 v28, 16, v24
	v_and_b32_e32 v29, 0xffff0000, v24
	v_lshlrev_b32_e32 v24, 16, v25
	v_and_b32_e32 v25, 0xffff0000, v25
	v_lshlrev_b32_e32 v30, 16, v26
	v_and_b32_e32 v31, 0xffff0000, v26
	v_lshlrev_b32_e32 v26, 16, v27
	v_and_b32_e32 v27, 0xffff0000, v27
	v_pk_add_f32 v[22:23], v[22:23], v[24:25]
	v_pk_add_f32 v[20:21], v[20:21], v[28:29]
	v_pk_add_f32 v[24:25], v[18:19], v[26:27]
	v_pk_add_f32 v[18:19], v[16:17], v[30:31]
	v_cvt_pk_bf16_f32 v16, v20, v21
	v_cvt_pk_bf16_f32 v17, v22, v23
	v_cvt_pk_bf16_f32 v18, v18, v19
	v_cvt_pk_bf16_f32 v19, v24, v25
	global_store_dwordx4 v[32:33], v[16:19], off offset:256
	s_nop 1
	v_lshl_add_u64 v[16:17], v[144:145], 0, s[2:3]
	s_mov_b32 s2, 0xb0000
	v_add_co_u32_e32 v22, vcc, s2, v144
	s_mov_b32 s2, s53
	s_nop 0
	v_addc_co_u32_e32 v23, vcc, 0, v145, vcc
	s_waitcnt vmcnt(15)
	s_nop 1
	v_mov_b32_e32 v18, v248
	v_mov_b32_e32 v19, v249
	v_mov_b32_e32 v20, v250
	v_mov_b32_e32 v21, v251
	s_and_b64 vcc, exec, s[40:41]
	s_waitcnt lgkmcnt(0)
	v_lshlrev_b32_e32 v24, 16, v18
	v_and_b32_e32 v25, 0xffff0000, v18
	v_lshlrev_b32_e32 v18, 16, v19
	v_and_b32_e32 v19, 0xffff0000, v19
	v_lshlrev_b32_e32 v26, 16, v20
	v_and_b32_e32 v27, 0xffff0000, v20
	v_lshlrev_b32_e32 v20, 16, v21
	v_and_b32_e32 v21, 0xffff0000, v21
	v_pk_add_f32 v[14:15], v[14:15], v[18:19]
	v_pk_add_f32 v[12:13], v[12:13], v[24:25]
	v_pk_add_f32 v[18:19], v[10:11], v[20:21]
	v_pk_add_f32 v[10:11], v[8:9], v[26:27]
	v_cvt_pk_bf16_f32 v8, v12, v13
	v_cvt_pk_bf16_f32 v9, v14, v15
	v_cvt_pk_bf16_f32 v10, v10, v11
	v_cvt_pk_bf16_f32 v11, v18, v19
	global_store_dwordx4 v[22:23], v[8:11], off
	s_waitcnt vmcnt(15)
	s_nop 1
	v_mov_b32_e32 v8, v252
	v_mov_b32_e32 v9, v253
	v_mov_b32_e32 v10, v254
	v_mov_b32_e32 v11, v255
	s_waitcnt lgkmcnt(0)
	v_lshlrev_b32_e32 v12, 16, v8
	v_and_b32_e32 v13, 0xffff0000, v8
	v_lshlrev_b32_e32 v8, 16, v9
	v_and_b32_e32 v9, 0xffff0000, v9
	v_lshlrev_b32_e32 v14, 16, v10
	v_and_b32_e32 v15, 0xffff0000, v10
	v_lshlrev_b32_e32 v10, 16, v11
	v_and_b32_e32 v11, 0xffff0000, v11
	v_pk_add_f32 v[6:7], v[6:7], v[8:9]
	v_pk_add_f32 v[4:5], v[4:5], v[12:13]
	v_pk_add_f32 v[8:9], v[2:3], v[10:11]
	v_pk_add_f32 v[2:3], v[0:1], v[14:15]
	v_cvt_pk_bf16_f32 v0, v4, v5
	v_cvt_pk_bf16_f32 v1, v6, v7
	v_cvt_pk_bf16_f32 v2, v2, v3
	v_cvt_pk_bf16_f32 v3, v8, v9
	global_store_dwordx4 v[16:17], v[0:3], off offset:256
	s_cbranch_vccz .LBB1_2071
	s_waitcnt vmcnt(0)
	s_cmpk_gt_u32 s17, 0xff
	s_cbranch_scc1 .LBB1_2082
	s_barrier

; #define PG8_STAGE(bufoff, gbase, voff) do { _Pragma("unroll") for (int _i = 0; _i < 2; ++_i) \
;         __builtin_amdgcn_global_load_lds((const unsigned*)((const char*)(gbase) + (voff)[_i]), (LAS unsigned*)(lds + (bufoff) + ldsw + _i * 8192), 16, 0, 0); } while (0)
; #define PG8_LDA(dst, b, h) do { _Pragma("unroll") for (int m = 0; m < 4; ++m) _Pragma("unroll") for (int k = 0; k < 2; ++k) dst[m][k] = *(const LAS bf16x8*)(lds + PG8_SA(b, h) + aoff + m * 2048 + k * 1024); } while (0)
; #define PG8_LDB(dst, b, h) do { _Pragma("unroll") for (int n = 0; n < 2; ++n) _Pragma("unroll") for (int k = 0; k < 2; ++k) dst[n][k] = *(const LAS bf16x8*)(lds + PG8_SB(b, h) + boff + n * 2048 + k * 1024); } while (0)
; #define PG8_MMA(ai, bj, At, Bt) do { __builtin_amdgcn_s_setprio(1); _Pragma("unroll") for (int m = 0; m < 4; ++m) _Pragma("unroll") for (int n = 0; n < 2; ++n) _Pragma("unroll") for (int k = 0; k < 2; ++k) \
;         acc[ai][bj][m][n] = __builtin_amdgcn_mfma_f32_16x16x32_bf16(Bt[n][k], At[m][k], acc[ai][bj][m][n], 0, 0, 0); __builtin_amdgcn_s_setprio(0); } while (0)
; #define PG8_WAIT_V(n) asm volatile("s_waitcnt vmcnt(" #n ")" ::: "memory")
; #define PG8_WAIT_L(n) asm volatile("s_waitcnt lgkmcnt(" #n ")" ::: "memory")
; #define PG8_BAR __builtin_amdgcn_s_barrier()
; #define PG8_SCHED __builtin_amdgcn_sched_barrier(0)
; template <class Map, class Epi>
; DI void gemm_phase(LAS unsigned char* lds, const Map& MP, const Epi& E, const int nM, const int nN, const int K, const int lda, const int ldb) {
;     ...
;             PG8_LDB(B0, 0, 0); PG8_SCHED; PG8_LDA(At, 0, 0); PG8_STAGE(PG8_SA(1, 1), a1 + hstepA, voffA);
;             PG8_WAIT_L(8); PG8_BAR; PG8_WAIT_L(0); PG8_MMA(0, 0, At, B0); PG8_BAR; PG8_SCHED;
;             PG8_LDB(B1, 0, 1); PG8_STAGE(PG8_SB(0, 0), b2, voffB);
;             PG8_BAR; PG8_WAIT_L(0); PG8_MMA(0, 1, At, B1); PG8_BAR;
;             PG8_LDA(At, 0, 1); PG8_STAGE(PG8_SA(0, 0), a2, voffA);
;             PG8_BAR; PG8_WAIT_L(0); PG8_MMA(1, 0, At, B0); PG8_BAR; PG8_SCHED;
;             PG8_STAGE(PG8_SB(0, 1), b2 + hstepB, voffB);
;             PG8_WAIT_V(6); PG8_BAR; PG8_MMA(1, 1, At, B1); PG8_BAR;
.LBB1_2653:
	ds_read_b128 v[152:155], v149
	ds_read_b128 v[156:159], v149 offset:1024
	ds_read_b128 v[160:163], v149 offset:2048
	ds_read_b128 v[164:167], v149 offset:3072
	s_add_u32 s10, s8, 0x100
	s_addc_u32 s11, s9, 0
	s_cmpk_eq_i32 s48, 0x54
	s_cselect_b32 s15, s43, s11
	s_cselect_b32 s14, s42, s10
	s_cselect_b32 s13, s45, s39
	s_cselect_b32 s12, s44, s38
	v_lshl_add_u64 v[144:145], s[8:9], 0, v[138:139]
	s_add_i32 m0, s22, 0xc000
	ds_read_b128 v[168:171], v150
	ds_read_b128 v[172:175], v150 offset:1024
	ds_read_b128 v[176:179], v150 offset:2048
	ds_read_b128 v[180:183], v150 offset:3072
	ds_read_b128 v[184:187], v150 offset:4096
	ds_read_b128 v[188:191], v150 offset:5120
	ds_read_b128 v[192:195], v150 offset:6144
	ds_read_b128 v[196:199], v150 offset:7168
	global_load_lds_dwordx4 v[144:145], off
	v_lshl_add_u64 v[144:145], s[8:9], 0, v[136:137]
	s_add_i32 m0, s22, 0xe000
	s_nop 0
	global_load_lds_dwordx4 v[144:145], off
	s_waitcnt lgkmcnt(8)
	s_barrier
	s_setprio 1
	s_waitcnt lgkmcnt(7)
	v_mfma_f32_16x16x32_bf16 v[124:127], v[152:155], v[168:171], v[124:127]
	v_mfma_f32_16x16x32_bf16 v[120:123], v[160:163], v[168:171], v[120:123]
	s_waitcnt lgkmcnt(5)
	v_mfma_f32_16x16x32_bf16 v[108:111], v[152:155], v[176:179], v[108:111]
	v_mfma_f32_16x16x32_bf16 v[104:107], v[160:163], v[176:179], v[104:107]
	s_waitcnt lgkmcnt(3)
	v_mfma_f32_16x16x32_bf16 v[92:95], v[152:155], v[184:187], v[92:95]
	v_mfma_f32_16x16x32_bf16 v[88:91], v[160:163], v[184:187], v[88:91]
	s_waitcnt lgkmcnt(1)
	v_mfma_f32_16x16x32_bf16 v[76:79], v[152:155], v[192:195], v[76:79]
	v_mfma_f32_16x16x32_bf16 v[72:75], v[160:163], v[192:195], v[72:75]
	v_mfma_f32_16x16x32_bf16 v[124:127], v[156:159], v[172:175], v[124:127]
	v_mfma_f32_16x16x32_bf16 v[120:123], v[164:167], v[172:175], v[120:123]
	v_mfma_f32_16x16x32_bf16 v[108:111], v[156:159], v[180:183], v[108:111]
	v_mfma_f32_16x16x32_bf16 v[104:107], v[164:167], v[180:183], v[104:107]
	v_mfma_f32_16x16x32_bf16 v[92:95], v[156:159], v[188:191], v[92:95]
	v_mfma_f32_16x16x32_bf16 v[88:91], v[164:167], v[188:191], v[88:91]
	s_waitcnt lgkmcnt(0)
	v_mfma_f32_16x16x32_bf16 v[76:79], v[156:159], v[196:199], v[76:79]
	v_mfma_f32_16x16x32_bf16 v[72:75], v[164:167], v[196:199], v[72:75]
	s_setprio 0
	s_barrier
	s_add_i32 s8, s33, s20
	v_lshl_add_u64 v[144:145], s[12:13], 0, v[132:133]
	s_mov_b32 m0, s8
	ds_read_b128 v[200:203], v151
	ds_read_b128 v[204:207], v151 offset:1024
	ds_read_b128 v[208:211], v151 offset:2048
	ds_read_b128 v[212:215], v151 offset:3072
	global_load_lds_dwordx4 v[144:145], off
	v_lshl_add_u64 v[216:217], s[12:13], 0, v[128:129]
	s_add_i32 m0, s8, 0x2000
	s_nop 0
	global_load_lds_dwordx4 v[216:217], off
	s_barrier
	s_setprio 1
	s_waitcnt lgkmcnt(3)
	v_mfma_f32_16x16x32_bf16 v[116:119], v[200:203], v[168:171], v[116:119]
	s_waitcnt lgkmcnt(1)
	v_mfma_f32_16x16x32_bf16 v[112:115], v[208:211], v[168:171], v[112:115]
	v_mfma_f32_16x16x32_bf16 v[100:103], v[200:203], v[176:179], v[100:103]
	v_mfma_f32_16x16x32_bf16 v[96:99], v[208:211], v[176:179], v[96:99]
	v_mfma_f32_16x16x32_bf16 v[84:87], v[200:203], v[184:187], v[84:87]
	v_mfma_f32_16x16x32_bf16 v[80:83], v[208:211], v[184:187], v[80:83]
	v_mfma_f32_16x16x32_bf16 v[68:71], v[200:203], v[192:195], v[68:71]
	v_mfma_f32_16x16x32_bf16 v[64:67], v[208:211], v[192:195], v[64:67]
	v_mfma_f32_16x16x32_bf16 v[116:119], v[204:207], v[172:175], v[116:119]
	s_waitcnt lgkmcnt(0)
	v_mfma_f32_16x16x32_bf16 v[112:115], v[212:215], v[172:175], v[112:115]
	v_mfma_f32_16x16x32_bf16 v[100:103], v[204:207], v[180:183], v[100:103]
	v_mfma_f32_16x16x32_bf16 v[96:99], v[212:215], v[180:183], v[96:99]
	v_mfma_f32_16x16x32_bf16 v[84:87], v[204:207], v[188:191], v[84:87]
	v_mfma_f32_16x16x32_bf16 v[80:83], v[212:215], v[188:191], v[80:83]
	v_mfma_f32_16x16x32_bf16 v[68:71], v[204:207], v[196:199], v[68:71]
	v_mfma_f32_16x16x32_bf16 v[64:67], v[212:215], v[196:199], v[64:67]
	s_setprio 0
	s_mov_b32 m0, s22
	v_lshl_add_u64 v[218:219], s[14:15], 0, v[134:135]
	s_barrier
	ds_read_b128 v[168:171], v150 offset:16384
	ds_read_b128 v[172:175], v150 offset:17408
	ds_read_b128 v[176:179], v150 offset:18432
	ds_read_b128 v[180:183], v150 offset:19456
	ds_read_b128 v[184:187], v150 offset:20480
	ds_read_b128 v[188:191], v150 offset:21504
	ds_read_b128 v[192:195], v150 offset:22528
	ds_read_b128 v[196:199], v150 offset:23552
	global_load_lds_dwordx4 v[218:219], off
	v_lshl_add_u64 v[220:221], s[14:15], 0, v[130:131]
	s_mov_b32 m0, s23
	s_nop 0
	global_load_lds_dwordx4 v[220:221], off
	s_barrier
	s_setprio 1
	s_waitcnt lgkmcnt(7)
	v_mfma_f32_16x16x32_bf16 v[60:63], v[152:155], v[168:171], v[60:63]
	v_mfma_f32_16x16x32_bf16 v[56:59], v[160:163], v[168:171], v[56:59]
	s_waitcnt lgkmcnt(5)
	v_mfma_f32_16x16x32_bf16 v[44:47], v[152:155], v[176:179], v[44:47]
	v_mfma_f32_16x16x32_bf16 v[40:43], v[160:163], v[176:179], v[40:43]
	s_waitcnt lgkmcnt(3)
	v_mfma_f32_16x16x32_bf16 v[28:31], v[152:155], v[184:187], v[28:31]
	v_mfma_f32_16x16x32_bf16 v[24:27], v[160:163], v[184:187], v[24:27]
	s_waitcnt lgkmcnt(1)
	v_mfma_f32_16x16x32_bf16 v[12:15], v[152:155], v[192:195], v[12:15]
	v_mfma_f32_16x16x32_bf16 v[8:11], v[160:163], v[192:195], v[8:11]
	v_mfma_f32_16x16x32_bf16 v[60:63], v[156:159], v[172:175], v[60:63]
	v_mfma_f32_16x16x32_bf16 v[56:59], v[164:167], v[172:175], v[56:59]
	v_mfma_f32_16x16x32_bf16 v[44:47], v[156:159], v[180:183], v[44:47]
	v_mfma_f32_16x16x32_bf16 v[40:43], v[164:167], v[180:183], v[40:43]
	v_mfma_f32_16x16x32_bf16 v[28:31], v[156:159], v[188:191], v[28:31]
	v_mfma_f32_16x16x32_bf16 v[24:27], v[164:167], v[188:191], v[24:27]
	s_waitcnt lgkmcnt(0)
	v_mfma_f32_16x16x32_bf16 v[12:15], v[156:159], v[196:199], v[12:15]
	v_mfma_f32_16x16x32_bf16 v[8:11], v[164:167], v[196:199], v[8:11]
	s_setprio 0
	s_barrier
; #define PG8_STAGE(bufoff, gbase, voff) do { _Pragma("unroll") for (int _i = 0; _i < 2; ++_i) \
;         __builtin_amdgcn_global_load_lds((const unsigned*)((const char*)(gbase) + (voff)[_i]), (LAS unsigned*)(lds + (bufoff) + ldsw + _i * 8192), 16, 0, 0); } while (0)
; #define PG8_LDA(dst, b, h) do { _Pragma("unroll") for (int m = 0; m < 4; ++m) _Pragma("unroll") for (int k = 0; k < 2; ++k) dst[m][k] = *(const LAS bf16x8*)(lds + PG8_SA(b, h) + aoff + m * 2048 + k * 1024); } while (0)
; #define PG8_LDB(dst, b, h) do { _Pragma("unroll") for (int n = 0; n < 2; ++n) _Pragma("unroll") for (int k = 0; k < 2; ++k) dst[n][k] = *(const LAS bf16x8*)(lds + PG8_SB(b, h) + boff + n * 2048 + k * 1024); } while (0)
; #define PG8_MMA(ai, bj, At, Bt) do { __builtin_amdgcn_s_setprio(1); _Pragma("unroll") for (int m = 0; m < 4; ++m) _Pragma("unroll") for (int n = 0; n < 2; ++n) _Pragma("unroll") for (int k = 0; k < 2; ++k) \
;         acc[ai][bj][m][n] = __builtin_amdgcn_mfma_f32_16x16x32_bf16(Bt[n][k], At[m][k], acc[ai][bj][m][n], 0, 0, 0); __builtin_amdgcn_s_setprio(0); } while (0)
; #define PG8_WAIT_V(n) asm volatile("s_waitcnt vmcnt(" #n ")" ::: "memory")
; #define PG8_WAIT_L(n) asm volatile("s_waitcnt lgkmcnt(" #n ")" ::: "memory")
; #define PG8_BAR __builtin_amdgcn_s_barrier()
; #define PG8_SCHED __builtin_amdgcn_sched_barrier(0)
; template <class Map, class Epi>
; DI void gemm_phase(LAS unsigned char* lds, const Map& MP, const Epi& E, const int nM, const int nN, const int K, const int lda, const int ldb) {
;     ...
;             PG8_WAIT_V(6); PG8_BAR; PG8_MMA(1, 1, At, B1); PG8_BAR;
;             PG8_LDB(B0, 1, 0); PG8_SCHED; PG8_LDA(At, 1, 0); PG8_STAGE(PG8_SA(0, 1), a2 + hstepA, voffA);
;             PG8_WAIT_L(8); PG8_BAR; PG8_WAIT_L(0); PG8_MMA(0, 0, At, B0); PG8_BAR; PG8_SCHED;
;             PG8_LDB(B1, 1, 1); PG8_STAGE(PG8_SB(1, 0), b3, voffB);
;             PG8_BAR; PG8_WAIT_L(0); PG8_MMA(0, 1, At, B1); PG8_BAR;
;             PG8_LDA(At, 1, 1); PG8_STAGE(PG8_SA(1, 0), a3, voffA);
;             PG8_BAR; PG8_WAIT_L(0); PG8_MMA(1, 0, At, B0); PG8_BAR; PG8_SCHED;
	s_add_u32 s8, s12, 0x160000
	s_addc_u32 s9, s13, 0
	s_add_i32 s49, s34, s20
	v_lshl_add_u64 v[152:153], s[8:9], 0, v[132:133]
	s_mov_b32 m0, s49
	s_nop 0
	global_load_lds_dwordx4 v[152:153], off
	v_lshl_add_u64 v[152:153], s[8:9], 0, v[128:129]
	s_add_i32 m0, s49, 0x2000
	s_nop 0
	global_load_lds_dwordx4 v[152:153], off
	s_waitcnt vmcnt(6)
	s_barrier
	s_setprio 1
	v_mfma_f32_16x16x32_bf16 v[52:55], v[200:203], v[168:171], v[52:55]
	v_mfma_f32_16x16x32_bf16 v[48:51], v[208:211], v[168:171], v[48:51]
	v_mfma_f32_16x16x32_bf16 v[36:39], v[200:203], v[176:179], v[36:39]
	v_mfma_f32_16x16x32_bf16 v[32:35], v[208:211], v[176:179], v[32:35]
	v_mfma_f32_16x16x32_bf16 v[20:23], v[200:203], v[184:187], v[20:23]
	v_mfma_f32_16x16x32_bf16 v[16:19], v[208:211], v[184:187], v[16:19]
	v_mfma_f32_16x16x32_bf16 v[4:7], v[200:203], v[192:195], v[4:7]
	v_mfma_f32_16x16x32_bf16 v[0:3], v[208:211], v[192:195], v[0:3]
	v_mfma_f32_16x16x32_bf16 v[52:55], v[204:207], v[172:175], v[52:55]
	v_mfma_f32_16x16x32_bf16 v[48:51], v[212:215], v[172:175], v[48:51]
	v_mfma_f32_16x16x32_bf16 v[36:39], v[204:207], v[180:183], v[36:39]
	v_mfma_f32_16x16x32_bf16 v[32:35], v[212:215], v[180:183], v[32:35]
	v_mfma_f32_16x16x32_bf16 v[20:23], v[204:207], v[188:191], v[20:23]
	v_mfma_f32_16x16x32_bf16 v[16:19], v[212:215], v[188:191], v[16:19]
	v_mfma_f32_16x16x32_bf16 v[4:7], v[204:207], v[196:199], v[4:7]
	v_mfma_f32_16x16x32_bf16 v[0:3], v[212:215], v[196:199], v[0:3]
	s_setprio 0
	s_add_i32 s49, 0, 0x18000
	v_add_u32_e32 v164, s49, v148
	s_barrier
	ds_read_b128 v[152:155], v164
	ds_read_b128 v[156:159], v164 offset:1024
	ds_read_b128 v[160:163], v164 offset:2048
	ds_read_b128 v[164:167], v164 offset:3072
	s_add_u32 s8, s14, 0x160000
	s_addc_u32 s9, s15, 0
	s_mov_b32 m0, s24
	v_lshl_add_u64 v[200:201], s[8:9], 0, v[134:135]
	ds_read_b128 v[168:171], v150 offset:32768
	ds_read_b128 v[172:175], v150 offset:33792
	ds_read_b128 v[176:179], v150 offset:34816
	ds_read_b128 v[180:183], v150 offset:35840
	ds_read_b128 v[184:187], v150 offset:36864
	ds_read_b128 v[188:191], v150 offset:37888
	ds_read_b128 v[192:195], v150 offset:38912
	ds_read_b128 v[196:199], v150 offset:39936
	global_load_lds_dwordx4 v[200:201], off
	v_lshl_add_u64 v[200:201], s[8:9], 0, v[130:131]
	s_mov_b32 m0, s25
	s_nop 0
	global_load_lds_dwordx4 v[200:201], off
	s_waitcnt lgkmcnt(8)
	s_barrier
	s_setprio 1
	s_waitcnt lgkmcnt(7)
	v_mfma_f32_16x16x32_bf16 v[124:127], v[152:155], v[168:171], v[124:127]
	v_mfma_f32_16x16x32_bf16 v[120:123], v[160:163], v[168:171], v[120:123]
	s_waitcnt lgkmcnt(5)
	v_mfma_f32_16x16x32_bf16 v[108:111], v[152:155], v[176:179], v[108:111]
	v_mfma_f32_16x16x32_bf16 v[104:107], v[160:163], v[176:179], v[104:107]
	s_waitcnt lgkmcnt(3)
	v_mfma_f32_16x16x32_bf16 v[92:95], v[152:155], v[184:187], v[92:95]
	v_mfma_f32_16x16x32_bf16 v[88:91], v[160:163], v[184:187], v[88:91]
	s_waitcnt lgkmcnt(1)
	v_mfma_f32_16x16x32_bf16 v[76:79], v[152:155], v[192:195], v[76:79]
	v_mfma_f32_16x16x32_bf16 v[72:75], v[160:163], v[192:195], v[72:75]
	v_mfma_f32_16x16x32_bf16 v[124:127], v[156:159], v[172:175], v[124:127]
	v_mfma_f32_16x16x32_bf16 v[120:123], v[164:167], v[172:175], v[120:123]
	v_mfma_f32_16x16x32_bf16 v[108:111], v[156:159], v[180:183], v[108:111]
	v_mfma_f32_16x16x32_bf16 v[104:107], v[164:167], v[180:183], v[104:107]
	v_mfma_f32_16x16x32_bf16 v[92:95], v[156:159], v[188:191], v[92:95]
	v_mfma_f32_16x16x32_bf16 v[88:91], v[164:167], v[188:191], v[88:91]
	s_waitcnt lgkmcnt(0)
	v_mfma_f32_16x16x32_bf16 v[76:79], v[156:159], v[196:199], v[76:79]
	v_mfma_f32_16x16x32_bf16 v[72:75], v[164:167], v[196:199], v[72:75]
	s_setprio 0
	s_barrier
	s_add_i32 s14, 0, 0x1c000
	s_add_i32 s8, s49, s20
	v_add_u32_e32 v212, s14, v148
	v_lshl_add_u64 v[144:145], v[144:145], 0, s[46:47]
	s_mov_b32 m0, s8
	ds_read_b128 v[200:203], v212
	ds_read_b128 v[204:207], v212 offset:1024
	ds_read_b128 v[208:211], v212 offset:2048
	ds_read_b128 v[212:215], v212 offset:3072
	global_load_lds_dwordx4 v[144:145], off
	v_lshl_add_u64 v[144:145], v[216:217], 0, s[46:47]
	s_add_i32 m0, s8, 0x2000
	s_nop 0
	global_load_lds_dwordx4 v[144:145], off
	s_barrier
	s_setprio 1
	s_waitcnt lgkmcnt(3)
	v_mfma_f32_16x16x32_bf16 v[116:119], v[200:203], v[168:171], v[116:119]
	s_waitcnt lgkmcnt(1)
	v_mfma_f32_16x16x32_bf16 v[112:115], v[208:211], v[168:171], v[112:115]
	v_mfma_f32_16x16x32_bf16 v[100:103], v[200:203], v[176:179], v[100:103]
	v_mfma_f32_16x16x32_bf16 v[96:99], v[208:211], v[176:179], v[96:99]
	v_mfma_f32_16x16x32_bf16 v[84:87], v[200:203], v[184:187], v[84:87]
	v_mfma_f32_16x16x32_bf16 v[80:83], v[208:211], v[184:187], v[80:83]
	v_mfma_f32_16x16x32_bf16 v[68:71], v[200:203], v[192:195], v[68:71]
	v_mfma_f32_16x16x32_bf16 v[64:67], v[208:211], v[192:195], v[64:67]
	v_mfma_f32_16x16x32_bf16 v[116:119], v[204:207], v[172:175], v[116:119]
	s_waitcnt lgkmcnt(0)
	v_mfma_f32_16x16x32_bf16 v[112:115], v[212:215], v[172:175], v[112:115]
	v_mfma_f32_16x16x32_bf16 v[100:103], v[204:207], v[180:183], v[100:103]
	v_mfma_f32_16x16x32_bf16 v[96:99], v[212:215], v[180:183], v[96:99]
	v_mfma_f32_16x16x32_bf16 v[84:87], v[204:207], v[188:191], v[84:87]
	v_mfma_f32_16x16x32_bf16 v[80:83], v[212:215], v[188:191], v[80:83]
	v_mfma_f32_16x16x32_bf16 v[68:71], v[204:207], v[196:199], v[68:71]
	v_mfma_f32_16x16x32_bf16 v[64:67], v[212:215], v[196:199], v[64:67]
	s_setprio 0
	s_mov_b32 m0, s29
	v_lshl_add_u64 v[144:145], v[218:219], 0, s[46:47]
	s_barrier
; #define PG8_STAGE(bufoff, gbase, voff) do { _Pragma("unroll") for (int _i = 0; _i < 2; ++_i) \
;         __builtin_amdgcn_global_load_lds((const unsigned*)((const char*)(gbase) + (voff)[_i]), (LAS unsigned*)(lds + (bufoff) + ldsw + _i * 8192), 16, 0, 0); } while (0)
; #define PG8_MMA(ai, bj, At, Bt) do { __builtin_amdgcn_s_setprio(1); _Pragma("unroll") for (int m = 0; m < 4; ++m) _Pragma("unroll") for (int n = 0; n < 2; ++n) _Pragma("unroll") for (int k = 0; k < 2; ++k) \
;         acc[ai][bj][m][n] = __builtin_amdgcn_mfma_f32_16x16x32_bf16(Bt[n][k], At[m][k], acc[ai][bj][m][n], 0, 0, 0); __builtin_amdgcn_s_setprio(0); } while (0)
; #define PG8_WAIT_V(n) asm volatile("s_waitcnt vmcnt(" #n ")" ::: "memory")
; #define PG8_WAIT_L(n) asm volatile("s_waitcnt lgkmcnt(" #n ")" ::: "memory")
; #define PG8_BAR __builtin_amdgcn_s_barrier()
; #define PG8_SCHED __builtin_amdgcn_sched_barrier(0)
;     DI void operator()(const f32x4 (&acc)[2][2][4][2], const Unit& u, int wr, int wc, int fr, int fq) const {
;         const int row0 = u.pm * BM + wr * 64 + fr, col0 = u.pn * BM + wc * 32 + 8 * fq;
;         f32x4 sc[2][2];
; #pragma unroll
;         for (int bj = 0; bj < 2; ++bj)
; #pragma unroll
;             for (int n = 0; n < 2; ++n) sc[bj][n] = scale ? *(const f32x4*)(scale + col0 + bj * HALF + 4 * n) : (f32x4){1.f, 1.f, 1.f, 1.f};
; #pragma unroll
;         for (int ai = 0; ai < 2; ++ai)
; #pragma unroll
;             for (int m = 0; m < 4; ++m) { const size_t ro = (size_t)(row0 + ai * HALF + m * 16) * D + col0;
; #pragma unroll
;                 for (int bj = 0; bj < 2; ++bj) {
;                     f32x4 x0, x1;
;                     if constexpr (IB) { const u32x4 w = *(const u32x4*)((const bf16_t*)Xin + ro + bj * HALF);
; template <class Map, class Epi>
; DI void gemm_phase(LAS unsigned char* lds, const Map& MP, const Epi& E, const int nM, const int nN, const int K, const int lda, const int ldb) {
;     ...
;             PG8_BAR; PG8_WAIT_L(0); PG8_MMA(1, 0, At, B0); PG8_BAR; PG8_SCHED;
;             PG8_STAGE(PG8_SB(1, 1), b3 + hstepB, voffB);
;             PG8_WAIT_V(6); PG8_BAR; PG8_MMA(1, 1, At, B1); PG8_BAR;
	ds_read_b128 v[168:171], v150 offset:49152
	ds_read_b128 v[172:175], v150 offset:50176
	ds_read_b128 v[176:179], v150 offset:51200
	ds_read_b128 v[180:183], v150 offset:52224
	ds_read_b128 v[184:187], v150 offset:53248
	ds_read_b128 v[188:191], v150 offset:54272
	ds_read_b128 v[192:195], v150 offset:55296
	ds_read_b128 v[196:199], v150 offset:56320
	global_load_lds_dwordx4 v[144:145], off
	v_lshl_add_u64 v[144:145], v[220:221], 0, s[46:47]
	s_mov_b32 m0, s30
	s_nop 0
	global_load_lds_dwordx4 v[144:145], off
	s_barrier
	s_setprio 1
	s_waitcnt lgkmcnt(7)
	v_mfma_f32_16x16x32_bf16 v[60:63], v[152:155], v[168:171], v[60:63]
	v_mfma_f32_16x16x32_bf16 v[56:59], v[160:163], v[168:171], v[56:59]
	s_waitcnt lgkmcnt(5)
	v_mfma_f32_16x16x32_bf16 v[44:47], v[152:155], v[176:179], v[44:47]
	v_mfma_f32_16x16x32_bf16 v[40:43], v[160:163], v[176:179], v[40:43]
	s_waitcnt lgkmcnt(3)
	v_mfma_f32_16x16x32_bf16 v[28:31], v[152:155], v[184:187], v[28:31]
	v_mfma_f32_16x16x32_bf16 v[24:27], v[160:163], v[184:187], v[24:27]
	s_waitcnt lgkmcnt(1)
	v_mfma_f32_16x16x32_bf16 v[12:15], v[152:155], v[192:195], v[12:15]
	v_mfma_f32_16x16x32_bf16 v[8:11], v[160:163], v[192:195], v[8:11]
	v_mfma_f32_16x16x32_bf16 v[60:63], v[156:159], v[172:175], v[60:63]
	v_mfma_f32_16x16x32_bf16 v[56:59], v[164:167], v[172:175], v[56:59]
	v_mfma_f32_16x16x32_bf16 v[44:47], v[156:159], v[180:183], v[44:47]
	v_mfma_f32_16x16x32_bf16 v[40:43], v[164:167], v[180:183], v[40:43]
	v_mfma_f32_16x16x32_bf16 v[28:31], v[156:159], v[188:191], v[28:31]
	v_mfma_f32_16x16x32_bf16 v[24:27], v[164:167], v[188:191], v[24:27]
	s_waitcnt lgkmcnt(0)
	v_mfma_f32_16x16x32_bf16 v[12:15], v[156:159], v[196:199], v[12:15]
	v_mfma_f32_16x16x32_bf16 v[8:11], v[164:167], v[196:199], v[8:11]
	s_setprio 0
	s_barrier
	s_add_u32 s8, s12, 0x160080
	s_addc_u32 s9, s13, 0
	s_add_i32 s12, s14, s20
	v_lshl_add_u64 v[144:145], s[8:9], 0, v[132:133]
	s_mov_b32 m0, s12
	s_nop 0
	global_load_lds_dwordx4 v[144:145], off
	v_lshl_add_u64 v[144:145], s[8:9], 0, v[128:129]
	s_add_i32 m0, s12, 0x2000
	s_nop 0
	global_load_lds_dwordx4 v[144:145], off
	s_waitcnt vmcnt(6)
	s_barrier
	s_setprio 1
	v_mfma_f32_16x16x32_bf16 v[52:55], v[200:203], v[168:171], v[52:55]
	v_mfma_f32_16x16x32_bf16 v[48:51], v[208:211], v[168:171], v[48:51]
	v_mfma_f32_16x16x32_bf16 v[36:39], v[200:203], v[176:179], v[36:39]
	v_mfma_f32_16x16x32_bf16 v[32:35], v[208:211], v[176:179], v[32:35]
	v_mfma_f32_16x16x32_bf16 v[20:23], v[200:203], v[184:187], v[20:23]
	v_mfma_f32_16x16x32_bf16 v[16:19], v[208:211], v[184:187], v[16:19]
	v_mfma_f32_16x16x32_bf16 v[4:7], v[200:203], v[192:195], v[4:7]
	v_mfma_f32_16x16x32_bf16 v[0:3], v[208:211], v[192:195], v[0:3]
	v_mfma_f32_16x16x32_bf16 v[52:55], v[204:207], v[172:175], v[52:55]
	v_mfma_f32_16x16x32_bf16 v[48:51], v[212:215], v[172:175], v[48:51]
	v_mfma_f32_16x16x32_bf16 v[36:39], v[204:207], v[180:183], v[36:39]
	v_mfma_f32_16x16x32_bf16 v[32:35], v[212:215], v[180:183], v[32:35]
	v_mfma_f32_16x16x32_bf16 v[20:23], v[204:207], v[188:191], v[20:23]
	v_mfma_f32_16x16x32_bf16 v[16:19], v[212:215], v[188:191], v[16:19]
	v_mfma_f32_16x16x32_bf16 v[4:7], v[204:207], v[196:199], v[4:7]
	v_mfma_f32_16x16x32_bf16 v[0:3], v[212:215], v[196:199], v[0:3]
	s_setprio 0
	s_add_i32 s48, s48, 2
	s_add_u32 s38, s38, 0x100
	s_addc_u32 s39, s39, 0
	s_cmpk_gt_u32 s48, 0x55
	s_mov_b64 s[8:9], s[10:11]
	s_barrier
	s_cbranch_scc0 .LBB1_2653
	v_mov_b32_e32 v144, v147
	v_mov_b32_e32 v152, v146
	s_lshl_b32 s2, s2, 8
	s_lshl_b32 s8, s37, 8
	s_add_i32 s2, s2, s27
	s_or_b32 s8, s8, s28
	v_add_u32_e32 v152, s2, v152
	v_lshl_add_u32 v144, v144, 3, s8
	v_ashrrev_i32_e32 v153, 31, v152
	v_ashrrev_i32_e32 v145, 31, v144
	v_lshlrev_b64 v[152:153], 11, v[152:153]
	v_lshl_add_u64 v[144:145], v[152:153], 0, v[144:145]
	v_lshl_add_u64 v[156:157], v[144:145], 1, s[6:7]
	global_load_dwordx4 v[162:165], v[156:157], off
	global_load_dwordx4 v[166:169], v[156:157], off offset:256
	s_mov_b64 s[98:99], 0x10000
	v_lshl_add_u64 v[154:155], v[156:157], 0, s[98:99]
	global_load_dwordx4 v[170:173], v[154:155], off
	global_load_dwordx4 v[174:177], v[154:155], off offset:256
	s_mov_b64 s[98:99], 0x20000
	v_lshl_add_u64 v[154:155], v[156:157], 0, s[98:99]
	global_load_dwordx4 v[178:181], v[154:155], off
	global_load_dwordx4 v[182:185], v[154:155], off offset:256
	s_mov_b64 s[98:99], 0x30000
	v_lshl_add_u64 v[154:155], v[156:157], 0, s[98:99]
	global_load_dwordx4 v[186:189], v[154:155], off
	global_load_dwordx4 v[190:193], v[154:155], off offset:256
	s_mov_b64 s[98:99], 0x80000
	v_lshl_add_u64 v[154:155], v[156:157], 0, s[98:99]
	global_load_dwordx4 v[194:197], v[154:155], off
	global_load_dwordx4 v[198:201], v[154:155], off offset:256
	s_mov_b64 s[98:99], 0x90000
	v_lshl_add_u64 v[154:155], v[156:157], 0, s[98:99]
	global_load_dwordx4 v[202:205], v[154:155], off
	global_load_dwordx4 v[206:209], v[154:155], off offset:256
	s_mov_b64 s[98:99], 0xa0000
	v_lshl_add_u64 v[154:155], v[156:157], 0, s[98:99]
	global_load_dwordx4 v[210:213], v[154:155], off
	global_load_dwordx4 v[248:251], v[154:155], off offset:256
	s_mov_b64 s[98:99], 0xb0000
	v_lshl_add_u64 v[154:155], v[156:157], 0, s[98:99]
	global_load_dwordx4 v[252:255], v[154:155], off
	s_waitcnt vmcnt(14)
	s_nop 1
	v_mov_b32_e32 v152, v162
	v_mov_b32_e32 v153, v163
	v_mov_b32_e32 v154, v164
	v_mov_b32_e32 v155, v165
	s_mov_b64 s[8:9], 0x8000
	s_and_b64 vcc, exec, s[40:41]
	s_mov_b32 s37, s35
	s_mov_b32 s2, s36
	s_mov_b64 s[10:11], s[44:45]
	s_waitcnt lgkmcnt(0)
; DI unsigned pack2(float a, float b) { f32x2 v = {a, b}; hwbf16x2 r = __builtin_convertvector(v, hwbf16x2); return __builtin_bit_cast(unsigned, r); }
; DI float bflo(unsigned w) { return __uint_as_float(w << 16); }
; DI float bfhi(unsigned w) { return __uint_as_float(w & 0xffff0000u); }
;     DI void operator()(const f32x4 (&acc)[2][2][4][2], const Unit& u, int wr, int wc, int fr, int fq) const {
;     ...
;             for (int m = 0; m < 4; ++m) { const size_t ro = (size_t)(row0 + ai * HALF + m * 16) * D + col0;
; #pragma unroll
;                 for (int bj = 0; bj < 2; ++bj) {
;                     f32x4 x0, x1;
;                     if constexpr (IB) { const u32x4 w = *(const u32x4*)((const bf16_t*)Xin + ro + bj * HALF);
;                         x0 = (f32x4){bflo(w[0]), bfhi(w[0]), bflo(w[1]), bfhi(w[1])}; x1 = (f32x4){bflo(w[2]), bfhi(w[2]), bflo(w[3]), bfhi(w[3])}; }
;                     else { x0 = *(const f32x4*)((const float*)Xin + ro + bj * HALF); x1 = *(const f32x4*)((const float*)Xin + ro + bj * HALF + 4); }
;                     x0 += acc[ai][bj][m][0] * sc[bj][0]; x1 += acc[ai][bj][m][1] * sc[bj][1];
;                     if constexpr (OB) { u32x4 o; o[0] = pack2(x0[0], x0[1]); o[1] = pack2(x0[2], x0[3]); o[2] = pack2(x1[0], x1[1]); o[3] = pack2(x1[2], x1[3]);
;                         *(u32x4*)((bf16_t*)Xout + ro + bj * HALF) = o; }
;                     else { *(f32x4*)((float*)Xout + ro + bj * HALF) = x0; *(f32x4*)((float*)Xout + ro + bj * HALF + 4) = x1; } } }
	v_lshlrev_b32_e32 v158, 16, v152
	v_and_b32_e32 v159, 0xffff0000, v152
	v_lshlrev_b32_e32 v152, 16, v153
	v_and_b32_e32 v153, 0xffff0000, v153
	v_lshlrev_b32_e32 v160, 16, v154
	v_and_b32_e32 v161, 0xffff0000, v154
	v_lshlrev_b32_e32 v154, 16, v155
	v_and_b32_e32 v155, 0xffff0000, v155
	v_pk_add_f32 v[126:127], v[126:127], v[152:153]
	v_pk_add_f32 v[124:125], v[124:125], v[158:159]
	v_lshl_add_u64 v[152:153], v[144:145], 2, s[4:5]
	v_pk_add_f32 v[122:123], v[122:123], v[154:155]
	v_pk_add_f32 v[120:121], v[120:121], v[160:161]
	global_store_dwordx4 v[152:153], v[124:127], off
	global_store_dwordx4 v[152:153], v[120:123], off offset:16
	s_waitcnt vmcnt(15)
	s_nop 1
	v_mov_b32_e32 v120, v166
	v_mov_b32_e32 v121, v167
	v_mov_b32_e32 v122, v168
	v_mov_b32_e32 v123, v169
	s_waitcnt lgkmcnt(0)
	v_lshlrev_b32_e32 v124, 16, v120
	v_and_b32_e32 v125, 0xffff0000, v120
	v_lshlrev_b32_e32 v120, 16, v121
	v_and_b32_e32 v121, 0xffff0000, v121
	v_lshlrev_b32_e32 v126, 16, v122
	v_and_b32_e32 v127, 0xffff0000, v122
	v_lshlrev_b32_e32 v122, 16, v123
	v_and_b32_e32 v123, 0xffff0000, v123
	v_pk_add_f32 v[118:119], v[118:119], v[120:121]
	v_pk_add_f32 v[116:117], v[116:117], v[124:125]
	v_pk_add_f32 v[114:115], v[114:115], v[122:123]
	v_pk_add_f32 v[112:113], v[112:113], v[126:127]
	global_store_dwordx4 v[152:153], v[116:119], off offset:512
	global_store_dwordx4 v[152:153], v[112:115], off offset:528
	s_nop 0
	v_lshl_add_u64 v[116:117], v[144:145], 0, s[8:9]
	v_lshl_add_u64 v[118:119], v[116:117], 1, s[6:7]
	s_waitcnt vmcnt(16)
	s_nop 1
	v_mov_b32_e32 v112, v170
	v_mov_b32_e32 v113, v171
	v_mov_b32_e32 v114, v172
	v_mov_b32_e32 v115, v173
	s_mov_b64 s[8:9], 0x10000
	s_waitcnt lgkmcnt(0)
	v_lshlrev_b32_e32 v120, 16, v112
	v_and_b32_e32 v121, 0xffff0000, v112
	v_lshlrev_b32_e32 v112, 16, v113
	v_and_b32_e32 v113, 0xffff0000, v113
	v_lshlrev_b32_e32 v122, 16, v114
	v_and_b32_e32 v123, 0xffff0000, v114
	v_lshlrev_b32_e32 v114, 16, v115
	v_and_b32_e32 v115, 0xffff0000, v115
	v_pk_add_f32 v[110:111], v[110:111], v[112:113]
	v_pk_add_f32 v[108:109], v[108:109], v[120:121]
	v_lshl_add_u64 v[112:113], v[116:117], 2, s[4:5]
	v_pk_add_f32 v[106:107], v[106:107], v[114:115]
	v_pk_add_f32 v[104:105], v[104:105], v[122:123]
	global_store_dwordx4 v[112:113], v[108:111], off
	global_store_dwordx4 v[112:113], v[104:107], off offset:16
	s_waitcnt vmcnt(17)
	s_nop 1
	v_mov_b32_e32 v104, v174
	v_mov_b32_e32 v105, v175
	v_mov_b32_e32 v106, v176
	v_mov_b32_e32 v107, v177
	s_waitcnt lgkmcnt(0)
	v_lshlrev_b32_e32 v108, 16, v104
	v_and_b32_e32 v109, 0xffff0000, v104
	v_lshlrev_b32_e32 v104, 16, v105
	v_and_b32_e32 v105, 0xffff0000, v105
	v_lshlrev_b32_e32 v110, 16, v106
	v_and_b32_e32 v111, 0xffff0000, v106
	v_lshlrev_b32_e32 v106, 16, v107
	v_and_b32_e32 v107, 0xffff0000, v107
	v_pk_add_f32 v[102:103], v[102:103], v[104:105]
	v_pk_add_f32 v[100:101], v[100:101], v[108:109]
	v_pk_add_f32 v[98:99], v[98:99], v[106:107]
	v_pk_add_f32 v[96:97], v[96:97], v[110:111]
	global_store_dwordx4 v[112:113], v[100:103], off offset:512
	global_store_dwordx4 v[112:113], v[96:99], off offset:528
	s_nop 0
	v_lshl_add_u64 v[100:101], v[144:145], 0, s[8:9]
	v_lshl_add_u64 v[102:103], v[100:101], 1, s[6:7]
	s_waitcnt vmcnt(18)
	s_nop 1
	v_mov_b32_e32 v96, v178
	v_mov_b32_e32 v97, v179
	v_mov_b32_e32 v98, v180
	v_mov_b32_e32 v99, v181
	s_mov_b64 s[8:9], 0x18000
	s_waitcnt lgkmcnt(0)
	v_lshlrev_b32_e32 v104, 16, v96
	v_and_b32_e32 v105, 0xffff0000, v96
	v_lshlrev_b32_e32 v96, 16, v97
	v_and_b32_e32 v97, 0xffff0000, v97
	v_lshlrev_b32_e32 v106, 16, v98
	v_and_b32_e32 v107, 0xffff0000, v98
	v_lshlrev_b32_e32 v98, 16, v99
	v_and_b32_e32 v99, 0xffff0000, v99
	v_pk_add_f32 v[94:95], v[94:95], v[96:97]
	v_pk_add_f32 v[92:93], v[92:93], v[104:105]
	v_lshl_add_u64 v[96:97], v[100:101], 2, s[4:5]
	v_pk_add_f32 v[90:91], v[90:91], v[98:99]
	v_pk_add_f32 v[88:89], v[88:89], v[106:107]
	global_store_dwordx4 v[96:97], v[92:95], off
	global_store_dwordx4 v[96:97], v[88:91], off offset:16
	s_waitcnt vmcnt(19)
	s_nop 1
	v_mov_b32_e32 v88, v182
	v_mov_b32_e32 v89, v183
	v_mov_b32_e32 v90, v184
	v_mov_b32_e32 v91, v185
	s_waitcnt lgkmcnt(0)
	v_lshlrev_b32_e32 v92, 16, v88
	v_and_b32_e32 v93, 0xffff0000, v88
	v_lshlrev_b32_e32 v88, 16, v89
	v_and_b32_e32 v89, 0xffff0000, v89
	v_lshlrev_b32_e32 v94, 16, v90
	v_and_b32_e32 v95, 0xffff0000, v90
	v_lshlrev_b32_e32 v90, 16, v91
	v_and_b32_e32 v91, 0xffff0000, v91
	v_pk_add_f32 v[86:87], v[86:87], v[88:89]
	v_pk_add_f32 v[84:85], v[84:85], v[92:93]
	v_pk_add_f32 v[82:83], v[82:83], v[90:91]
	v_pk_add_f32 v[80:81], v[80:81], v[94:95]
	global_store_dwordx4 v[96:97], v[84:87], off offset:512
	global_store_dwordx4 v[96:97], v[80:83], off offset:528
	s_nop 0
	v_lshl_add_u64 v[84:85], v[144:145], 0, s[8:9]
	v_lshl_add_u64 v[86:87], v[84:85], 1, s[6:7]
	s_waitcnt vmcnt(20)
	s_nop 1
	v_mov_b32_e32 v80, v186
	v_mov_b32_e32 v81, v187
	v_mov_b32_e32 v82, v188
	v_mov_b32_e32 v83, v189
	s_mov_b64 s[8:9], 0x40000
	s_waitcnt lgkmcnt(0)
	v_lshlrev_b32_e32 v88, 16, v80
	v_and_b32_e32 v89, 0xffff0000, v80
	v_lshlrev_b32_e32 v80, 16, v81
	v_and_b32_e32 v81, 0xffff0000, v81
	v_lshlrev_b32_e32 v90, 16, v82
	v_and_b32_e32 v91, 0xffff0000, v82
	v_lshlrev_b32_e32 v82, 16, v83
	v_and_b32_e32 v83, 0xffff0000, v83
	v_pk_add_f32 v[78:79], v[78:79], v[80:81]
	v_pk_add_f32 v[76:77], v[76:77], v[88:89]
	v_lshl_add_u64 v[80:81], v[84:85], 2, s[4:5]
	v_pk_add_f32 v[74:75], v[74:75], v[82:83]
	v_pk_add_f32 v[72:73], v[72:73], v[90:91]
	global_store_dwordx4 v[80:81], v[76:79], off
	global_store_dwordx4 v[80:81], v[72:75], off offset:16
	s_waitcnt vmcnt(21)
; DI unsigned pack2(float a, float b) { f32x2 v = {a, b}; hwbf16x2 r = __builtin_convertvector(v, hwbf16x2); return __builtin_bit_cast(unsigned, r); }
; DI float bflo(unsigned w) { return __uint_as_float(w << 16); }
; DI float bfhi(unsigned w) { return __uint_as_float(w & 0xffff0000u); }
; #define PG8_WAIT_V(n) asm volatile("s_waitcnt vmcnt(" #n ")" ::: "memory")
; #define PG8_BAR __builtin_amdgcn_s_barrier()
;     DI void operator()(const f32x4 (&acc)[2][2][4][2], const Unit& u, int wr, int wc, int fr, int fq) const {
;     ...
;             for (int m = 0; m < 4; ++m) { const size_t ro = (size_t)(row0 + ai * HALF + m * 16) * D + col0;
; #pragma unroll
;                 for (int bj = 0; bj < 2; ++bj) {
;                     f32x4 x0, x1;
;                     if constexpr (IB) { const u32x4 w = *(const u32x4*)((const bf16_t*)Xin + ro + bj * HALF);
;                         x0 = (f32x4){bflo(w[0]), bfhi(w[0]), bflo(w[1]), bfhi(w[1])}; x1 = (f32x4){bflo(w[2]), bfhi(w[2]), bflo(w[3]), bfhi(w[3])}; }
;                     else { x0 = *(const f32x4*)((const float*)Xin + ro + bj * HALF); x1 = *(const f32x4*)((const float*)Xin + ro + bj * HALF + 4); }
;                     x0 += acc[ai][bj][m][0] * sc[bj][0]; x1 += acc[ai][bj][m][1] * sc[bj][1];
;                     if constexpr (OB) { u32x4 o; o[0] = pack2(x0[0], x0[1]); o[1] = pack2(x0[2], x0[3]); o[2] = pack2(x1[0], x1[1]); o[3] = pack2(x1[2], x1[3]);
;                         *(u32x4*)((bf16_t*)Xout + ro + bj * HALF) = o; }
;                     else { *(f32x4*)((float*)Xout + ro + bj * HALF) = x0; *(f32x4*)((float*)Xout + ro + bj * HALF + 4) = x1; } } }
; template <class Map, class Epi>
; DI void gemm_phase(LAS unsigned char* lds, const Map& MP, const Epi& E, const int nM, const int nN, const int K, const int lda, const int ldb) {
;     ...
;         if (!has_next) break;
;     ...
;     PG8_WAIT_V(0);
;     if (wr == 0) PG8_BAR;
;     PG8_BAR;
	s_nop 1
	v_mov_b32_e32 v72, v190
	v_mov_b32_e32 v73, v191
	v_mov_b32_e32 v74, v192
	v_mov_b32_e32 v75, v193
	s_waitcnt lgkmcnt(0)
	v_lshlrev_b32_e32 v76, 16, v72
	v_and_b32_e32 v77, 0xffff0000, v72
	v_lshlrev_b32_e32 v72, 16, v73
	v_and_b32_e32 v73, 0xffff0000, v73
	v_lshlrev_b32_e32 v78, 16, v74
	v_and_b32_e32 v79, 0xffff0000, v74
	v_lshlrev_b32_e32 v74, 16, v75
	v_and_b32_e32 v75, 0xffff0000, v75
	v_pk_add_f32 v[70:71], v[70:71], v[72:73]
	v_pk_add_f32 v[68:69], v[68:69], v[76:77]
	v_pk_add_f32 v[66:67], v[66:67], v[74:75]
	v_pk_add_f32 v[64:65], v[64:65], v[78:79]
	global_store_dwordx4 v[80:81], v[68:71], off offset:512
	global_store_dwordx4 v[80:81], v[64:67], off offset:528
	s_nop 0
	v_lshl_add_u64 v[68:69], v[144:145], 0, s[8:9]
	v_lshl_add_u64 v[70:71], v[68:69], 1, s[6:7]
	s_waitcnt vmcnt(22)
	s_nop 1
	v_mov_b32_e32 v64, v194
	v_mov_b32_e32 v65, v195
	v_mov_b32_e32 v66, v196
	v_mov_b32_e32 v67, v197
	s_mov_b64 s[8:9], 0x48000
	s_waitcnt lgkmcnt(0)
	v_lshlrev_b32_e32 v72, 16, v64
	v_and_b32_e32 v73, 0xffff0000, v64
	v_lshlrev_b32_e32 v64, 16, v65
	v_and_b32_e32 v65, 0xffff0000, v65
	v_lshlrev_b32_e32 v74, 16, v66
	v_and_b32_e32 v75, 0xffff0000, v66
	v_lshlrev_b32_e32 v66, 16, v67
	v_and_b32_e32 v67, 0xffff0000, v67
	v_pk_add_f32 v[62:63], v[62:63], v[64:65]
	v_pk_add_f32 v[60:61], v[60:61], v[72:73]
	v_lshl_add_u64 v[64:65], v[68:69], 2, s[4:5]
	v_pk_add_f32 v[58:59], v[58:59], v[66:67]
	v_pk_add_f32 v[56:57], v[56:57], v[74:75]
	global_store_dwordx4 v[64:65], v[60:63], off
	global_store_dwordx4 v[64:65], v[56:59], off offset:16
	s_waitcnt vmcnt(23)
	s_nop 1
	v_mov_b32_e32 v56, v198
	v_mov_b32_e32 v57, v199
	v_mov_b32_e32 v58, v200
	v_mov_b32_e32 v59, v201
	s_waitcnt lgkmcnt(0)
	v_lshlrev_b32_e32 v60, 16, v56
	v_and_b32_e32 v61, 0xffff0000, v56
	v_lshlrev_b32_e32 v56, 16, v57
	v_and_b32_e32 v57, 0xffff0000, v57
	v_lshlrev_b32_e32 v62, 16, v58
	v_and_b32_e32 v63, 0xffff0000, v58
	v_lshlrev_b32_e32 v58, 16, v59
	v_and_b32_e32 v59, 0xffff0000, v59
	v_pk_add_f32 v[54:55], v[54:55], v[56:57]
	v_pk_add_f32 v[52:53], v[52:53], v[60:61]
	v_pk_add_f32 v[50:51], v[50:51], v[58:59]
	v_pk_add_f32 v[48:49], v[48:49], v[62:63]
	global_store_dwordx4 v[64:65], v[52:55], off offset:512
	global_store_dwordx4 v[64:65], v[48:51], off offset:528
	s_nop 0
	v_lshl_add_u64 v[52:53], v[144:145], 0, s[8:9]
	v_lshl_add_u64 v[54:55], v[52:53], 1, s[6:7]
	s_waitcnt vmcnt(24)
	s_nop 1
	v_mov_b32_e32 v48, v202
	v_mov_b32_e32 v49, v203
	v_mov_b32_e32 v50, v204
	v_mov_b32_e32 v51, v205
	s_mov_b64 s[8:9], 0x50000
	s_waitcnt lgkmcnt(0)
	v_lshlrev_b32_e32 v56, 16, v48
	v_and_b32_e32 v57, 0xffff0000, v48
	v_lshlrev_b32_e32 v48, 16, v49
	v_and_b32_e32 v49, 0xffff0000, v49
	v_lshlrev_b32_e32 v58, 16, v50
	v_and_b32_e32 v59, 0xffff0000, v50
	v_lshlrev_b32_e32 v50, 16, v51
	v_and_b32_e32 v51, 0xffff0000, v51
	v_pk_add_f32 v[46:47], v[46:47], v[48:49]
	v_pk_add_f32 v[44:45], v[44:45], v[56:57]
	v_lshl_add_u64 v[48:49], v[52:53], 2, s[4:5]
	v_pk_add_f32 v[42:43], v[42:43], v[50:51]
	v_pk_add_f32 v[40:41], v[40:41], v[58:59]
	global_store_dwordx4 v[48:49], v[44:47], off
	global_store_dwordx4 v[48:49], v[40:43], off offset:16
	s_waitcnt vmcnt(25)
	s_nop 1
	v_mov_b32_e32 v40, v206
	v_mov_b32_e32 v41, v207
	v_mov_b32_e32 v42, v208
	v_mov_b32_e32 v43, v209
	s_waitcnt lgkmcnt(0)
	v_lshlrev_b32_e32 v44, 16, v40
	v_and_b32_e32 v45, 0xffff0000, v40
	v_lshlrev_b32_e32 v40, 16, v41
	v_and_b32_e32 v41, 0xffff0000, v41
	v_lshlrev_b32_e32 v46, 16, v42
	v_and_b32_e32 v47, 0xffff0000, v42
	v_lshlrev_b32_e32 v42, 16, v43
	v_and_b32_e32 v43, 0xffff0000, v43
	v_pk_add_f32 v[38:39], v[38:39], v[40:41]
	v_pk_add_f32 v[36:37], v[36:37], v[44:45]
	v_pk_add_f32 v[34:35], v[34:35], v[42:43]
	v_pk_add_f32 v[32:33], v[32:33], v[46:47]
	global_store_dwordx4 v[48:49], v[36:39], off offset:512
	global_store_dwordx4 v[48:49], v[32:35], off offset:528
	s_nop 0
	v_lshl_add_u64 v[36:37], v[144:145], 0, s[8:9]
	v_lshl_add_u64 v[38:39], v[36:37], 1, s[6:7]
	s_waitcnt vmcnt(26)
	s_nop 1
	v_mov_b32_e32 v32, v210
	v_mov_b32_e32 v33, v211
	v_mov_b32_e32 v34, v212
	v_mov_b32_e32 v35, v213
	s_mov_b64 s[8:9], 0x58000
	s_waitcnt lgkmcnt(0)
	v_lshlrev_b32_e32 v40, 16, v32
	v_and_b32_e32 v41, 0xffff0000, v32
	v_lshlrev_b32_e32 v32, 16, v33
	v_and_b32_e32 v33, 0xffff0000, v33
	v_lshlrev_b32_e32 v42, 16, v34
	v_and_b32_e32 v43, 0xffff0000, v34
	v_lshlrev_b32_e32 v34, 16, v35
	v_and_b32_e32 v35, 0xffff0000, v35
	v_pk_add_f32 v[30:31], v[30:31], v[32:33]
	v_pk_add_f32 v[28:29], v[28:29], v[40:41]
	v_lshl_add_u64 v[32:33], v[36:37], 2, s[4:5]
	v_pk_add_f32 v[26:27], v[26:27], v[34:35]
	v_pk_add_f32 v[24:25], v[24:25], v[42:43]
	global_store_dwordx4 v[32:33], v[28:31], off
	global_store_dwordx4 v[32:33], v[24:27], off offset:16
	s_waitcnt vmcnt(27)
	s_nop 1
	v_mov_b32_e32 v24, v248
	v_mov_b32_e32 v25, v249
	v_mov_b32_e32 v26, v250
	v_mov_b32_e32 v27, v251
	s_waitcnt lgkmcnt(0)
	v_lshlrev_b32_e32 v28, 16, v24
	v_and_b32_e32 v29, 0xffff0000, v24
	v_lshlrev_b32_e32 v24, 16, v25
	v_and_b32_e32 v25, 0xffff0000, v25
	v_lshlrev_b32_e32 v30, 16, v26
	v_and_b32_e32 v31, 0xffff0000, v26
	v_lshlrev_b32_e32 v26, 16, v27
	v_and_b32_e32 v27, 0xffff0000, v27
	v_pk_add_f32 v[22:23], v[22:23], v[24:25]
	v_pk_add_f32 v[20:21], v[20:21], v[28:29]
	v_pk_add_f32 v[18:19], v[18:19], v[26:27]
	v_pk_add_f32 v[16:17], v[16:17], v[30:31]
	global_store_dwordx4 v[32:33], v[20:23], off offset:512
	global_store_dwordx4 v[32:33], v[16:19], off offset:528
	s_nop 0
	v_lshl_add_u64 v[20:21], v[144:145], 0, s[8:9]
	v_lshl_add_u64 v[22:23], v[20:21], 1, s[6:7]
	s_waitcnt vmcnt(28)
	s_nop 1
	v_mov_b32_e32 v16, v252
	v_mov_b32_e32 v17, v253
	v_mov_b32_e32 v18, v254
	v_mov_b32_e32 v19, v255
	s_mov_b64 s[8:9], s[42:43]
	s_waitcnt lgkmcnt(0)
	v_lshlrev_b32_e32 v24, 16, v16
	v_and_b32_e32 v25, 0xffff0000, v16
	v_lshlrev_b32_e32 v16, 16, v17
	v_and_b32_e32 v17, 0xffff0000, v17
	v_lshlrev_b32_e32 v26, 16, v18
	v_and_b32_e32 v27, 0xffff0000, v18
	v_lshlrev_b32_e32 v18, 16, v19
	v_and_b32_e32 v19, 0xffff0000, v19
	v_pk_add_f32 v[14:15], v[14:15], v[16:17]
	v_pk_add_f32 v[12:13], v[12:13], v[24:25]
	v_lshl_add_u64 v[16:17], v[20:21], 2, s[4:5]
	v_pk_add_f32 v[10:11], v[10:11], v[18:19]
	v_pk_add_f32 v[8:9], v[8:9], v[26:27]
	global_store_dwordx4 v[16:17], v[12:15], off
	global_store_dwordx4 v[16:17], v[8:11], off offset:16
	global_load_dwordx4 v[8:11], v[22:23], off offset:256
	s_waitcnt vmcnt(0) lgkmcnt(0)
	v_lshlrev_b32_e32 v12, 16, v8
	v_and_b32_e32 v13, 0xffff0000, v8
	v_lshlrev_b32_e32 v8, 16, v9
	v_and_b32_e32 v9, 0xffff0000, v9
	v_lshlrev_b32_e32 v14, 16, v10
	v_and_b32_e32 v15, 0xffff0000, v10
	v_lshlrev_b32_e32 v10, 16, v11
	v_and_b32_e32 v11, 0xffff0000, v11
	v_pk_add_f32 v[6:7], v[6:7], v[8:9]
	v_pk_add_f32 v[4:5], v[4:5], v[12:13]
	v_pk_add_f32 v[2:3], v[2:3], v[10:11]
	v_pk_add_f32 v[0:1], v[0:1], v[14:15]
	global_store_dwordx4 v[16:17], v[4:7], off offset:512
	global_store_dwordx4 v[16:17], v[0:3], off offset:528
	s_cbranch_vccz .LBB1_2646
	s_waitcnt vmcnt(0)
	s_cmpk_gt_u32 s3, 0xff
	s_cbranch_scc1 .LBB1_2657
	s_barrier

; template <bool MEGA>
; __global__ void __launch_bounds__(512) fwd_kernel(Params p, int phase) {
	.amdhsa_kernel _Z10fwd_kernelILb1EEv6Paramsi
		.amdhsa_group_segment_fixed_size 0
		.amdhsa_private_segment_fixed_size 0
		.amdhsa_kernarg_size 1120
		.amdhsa_user_sgpr_count 2
		.amdhsa_user_sgpr_dispatch_ptr 0
		.amdhsa_user_sgpr_queue_ptr 0
		.amdhsa_user_sgpr_kernarg_segment_ptr 1
		.amdhsa_user_sgpr_dispatch_id 0
		.amdhsa_user_sgpr_kernarg_preload_length 0
		.amdhsa_user_sgpr_kernarg_preload_offset 0
		.amdhsa_user_sgpr_private_segment_size 0
		.amdhsa_uses_dynamic_stack 0
		.amdhsa_enable_private_segment 0
		.amdhsa_system_sgpr_workgroup_id_x 1
		.amdhsa_system_sgpr_workgroup_id_y 0
		.amdhsa_system_sgpr_workgroup_id_z 0
		.amdhsa_system_sgpr_workgroup_info 0
		.amdhsa_system_vgpr_workitem_id 2
		.amdhsa_next_free_vgpr 256
		.amdhsa_next_free_sgpr 100
		.amdhsa_accum_offset 256
		.amdhsa_reserve_vcc 1
		.amdhsa_float_round_mode_32 0
		.amdhsa_float_round_mode_16_64 0
		.amdhsa_float_denorm_mode_32 3
		.amdhsa_float_denorm_mode_16_64 3
		.amdhsa_dx10_clamp 1
		.amdhsa_ieee_mode 1
		.amdhsa_fp16_overflow 0
		.amdhsa_tg_split 0
		.amdhsa_exception_fp_ieee_invalid_op 0
		.amdhsa_exception_fp_denorm_src 0
		.amdhsa_exception_fp_ieee_div_zero 0
		.amdhsa_exception_fp_ieee_overflow 0
		.amdhsa_exception_fp_ieee_underflow 0
		.amdhsa_exception_fp_ieee_inexact 0
		.amdhsa_exception_int_div_zero 0
	.end_amdhsa_kernel

; template <bool MEGA>
; __global__ void __launch_bounds__(512) fwd_kernel(Params p, int phase) {
amdhsa.kernels:
  - .agpr_count:     0
    .args:
      - .address_space:  global
        .offset:         0
        .size:           8
        .value_kind:     global_buffer
      - .offset:         8
        .size:           4
        .value_kind:     by_value
      - .offset:         16
        .size:           4
        .value_kind:     hidden_block_count_x
      - .offset:         20
        .size:           4
        .value_kind:     hidden_block_count_y
      - .offset:         24
        .size:           4
        .value_kind:     hidden_block_count_z
      - .offset:         28
        .size:           2
        .value_kind:     hidden_group_size_x
      - .offset:         30
        .size:           2
        .value_kind:     hidden_group_size_y
      - .offset:         32
        .size:           2
        .value_kind:     hidden_group_size_z
      - .offset:         34
        .size:           2
        .value_kind:     hidden_remainder_x
      - .offset:         36
        .size:           2
        .value_kind:     hidden_remainder_y
      - .offset:         38
        .size:           2
        .value_kind:     hidden_remainder_z
      - .offset:         56
        .size:           8
        .value_kind:     hidden_global_offset_x
      - .offset:         64
        .size:           8
        .value_kind:     hidden_global_offset_y
      - .offset:         72
        .size:           8
        .value_kind:     hidden_global_offset_z
      - .offset:         80
        .size:           2
        .value_kind:     hidden_grid_dims
    .group_segment_fixed_size: 0
    .kernarg_segment_align: 8
    .kernarg_segment_size: 272
    .language:       OpenCL C
    .language_version:
      - 2
      - 0
    .max_flat_workgroup_size: 1024
    .name:           _Z8nan_fillPfi
    .private_segment_fixed_size: 0
    .sgpr_count:     15
    .sgpr_spill_count: 0
    .symbol:         _Z8nan_fillPfi.kd
    .uniform_work_group_size: 1
    .uses_dynamic_stack: false
    .vgpr_count:     6
    .vgpr_spill_count: 0
    .wavefront_size: 64
  - .agpr_count:     0
    .args:
      - .offset:         0
        .size:           856
        .value_kind:     by_value
      - .offset:         856
        .size:           4
        .value_kind:     by_value
      - .offset:         864
        .size:           4
        .value_kind:     hidden_block_count_x
      - .offset:         868
        .size:           4
        .value_kind:     hidden_block_count_y
      - .offset:         872
        .size:           4
        .value_kind:     hidden_block_count_z
      - .offset:         876
        .size:           2
        .value_kind:     hidden_group_size_x
      - .offset:         878
        .size:           2
        .value_kind:     hidden_group_size_y
      - .offset:         880
        .size:           2
        .value_kind:     hidden_group_size_z
      - .offset:         882
        .size:           2
        .value_kind:     hidden_remainder_x
      - .offset:         884
        .size:           2
        .value_kind:     hidden_remainder_y
      - .offset:         886
        .size:           2
        .value_kind:     hidden_remainder_z
      - .offset:         904
        .size:           8
        .value_kind:     hidden_global_offset_x
      - .offset:         912
        .size:           8
        .value_kind:     hidden_global_offset_y
      - .offset:         920
        .size:           8
        .value_kind:     hidden_global_offset_z
      - .offset:         928
        .size:           2
        .value_kind:     hidden_grid_dims
      - .offset:         952
        .size:           8
        .value_kind:     hidden_multigrid_sync_arg
      - .offset:         984
        .size:           4
        .value_kind:     hidden_dynamic_lds_size
    .group_segment_fixed_size: 0
    .kernarg_segment_align: 8
    .kernarg_segment_size: 1120
    .language:       OpenCL C
    .language_version:
      - 2
      - 0
    .max_flat_workgroup_size: 512
    .name:           _Z10fwd_kernelILb1EEv6Paramsi
    .private_segment_fixed_size: 0
    .sgpr_count:     106
    .sgpr_spill_count: 61
    .symbol:         _Z10fwd_kernelILb1EEv6Paramsi.kd
    .uniform_work_group_size: 1
    .uses_dynamic_stack: false
    .vgpr_count:     256
    .vgpr_spill_count: 0
    .wavefront_size: 64
